# phase 0 loops hand-written (32/64 loads in flight), phase 4 LDS fill and sample-row slab sum de-serialised
# speedup vs baseline: 1.0150x; 1.0150x over previous
; #define LAS __attribute__((address_space(3)))
; __device__ __forceinline__ void ph_mod(const float* cp, const float* cs, const float* w_ada, const float* b_ada, float* MOD, float* MISC,
;                                        const float* lq1, const float* lk1, const float* lq2, const float* lk2, LAS unsigned char* lds, int G, int tid) {
;     ...
;     LAS float* red = (LAS float*)(lds + 65536);
;     const int lane = tid & 63, wave = tid >> 6;
;     if ((int)blockIdx.x < 144) for (int i = tid; i < 16384; i += 512) { const int b = i >> 10, k = i & 1023; const float c = b < 8 ? cp[b * 1024 + k] : cs[(b - 8) * 1024 + k]; scT[k * 16 + b] = c / (1.0f + __expf(-c)); }
; __global__ void __launch_bounds__(NWAVES * 64, 2) mk_fwd(Args args) {
;     ...
;     if (IN(0)) for (int rep_ = 0; rep_ < REPS(0); ++rep_) { ph_mod(karg_in<6>(), karg_in<7>(), karg_in<8>(), karg_in<9>(), MOD, MISC, karg_in<21>(), karg_in<22>(), karg_in<23>(), karg_in<24>(), L, G, tid); flag_arrive(CNT(3), tid); }
.LBB0_10:
	s_load_dwordx4 s[0:3], s[58:59], 0x100
	s_waitcnt lgkmcnt(0)
	s_mov_b32 s6, s2
	s_mov_b64 s[4:5], s[0:1]
	s_cmp_lt_i32 s4, 1
	s_cselect_b64 s[0:1], -1, 0
	s_cmp_gt_i32 s5, 0
	s_cselect_b64 s[2:3], -1, 0
	s_and_b64 s[0:1], s[0:1], s[2:3]
	s_andn2_b64 vcc, exec, s[0:1]
	s_cbranch_vccnz .LBB0_31
	s_load_dwordx2 s[18:19], s[58:59], 48
	s_waitcnt lgkmcnt(0)
	v_readlane_b32 s0, v254, 6
	s_load_dwordx2 s[14:15], s[58:59], 56
	s_waitcnt lgkmcnt(0)
	s_cmpk_lt_i32 s0, 0x90
	s_load_dwordx2 s[0:1], s[58:59], 64
	s_waitcnt lgkmcnt(0)
	s_load_dwordx2 s[10:11], s[58:59], 0x48
	s_waitcnt lgkmcnt(0)
	s_load_dwordx2 s[8:9], s[58:59], 0xa8
	s_waitcnt lgkmcnt(0)
	s_load_dwordx2 s[6:7], s[58:59], 0xb0
	s_waitcnt lgkmcnt(0)
	s_load_dwordx2 s[4:5], s[58:59], 0xb8
	s_waitcnt lgkmcnt(0)
	s_load_dwordx2 s[2:3], s[58:59], 0xc0
	s_waitcnt lgkmcnt(0)
	v_mov_b32_e32 v2, v252
	v_and_b32_e32 v1, 63, v2
	v_lshlrev_b32_e32 v4, 2, v1
	s_cbranch_scc0 .Lp0_done
	v_lshlrev_b32_e32 v5, 2, v2
	v_lshlrev_b32_e32 v6, 6, v2
	s_mov_b64 s[20:21], s[18:19]
	global_load_dword v64, v5, s[20:21]
	s_add_u32 s20, s20, 0x800
	s_addc_u32 s21, s21, 0
	global_load_dword v65, v5, s[20:21]
	s_add_u32 s20, s20, 0x800
	s_addc_u32 s21, s21, 0
	global_load_dword v66, v5, s[20:21]
	s_add_u32 s20, s20, 0x800
	s_addc_u32 s21, s21, 0
	global_load_dword v67, v5, s[20:21]
	s_add_u32 s20, s20, 0x800
	s_addc_u32 s21, s21, 0
	global_load_dword v68, v5, s[20:21]
	s_add_u32 s20, s20, 0x800
	s_addc_u32 s21, s21, 0
	global_load_dword v69, v5, s[20:21]
	s_add_u32 s20, s20, 0x800
	s_addc_u32 s21, s21, 0
	global_load_dword v70, v5, s[20:21]
	s_add_u32 s20, s20, 0x800
	s_addc_u32 s21, s21, 0
	global_load_dword v71, v5, s[20:21]
	s_add_u32 s20, s20, 0x800
	s_addc_u32 s21, s21, 0
	global_load_dword v72, v5, s[20:21]
	s_add_u32 s20, s20, 0x800
	s_addc_u32 s21, s21, 0
	global_load_dword v73, v5, s[20:21]
	s_add_u32 s20, s20, 0x800
	s_addc_u32 s21, s21, 0
	global_load_dword v74, v5, s[20:21]
	s_add_u32 s20, s20, 0x800
	s_addc_u32 s21, s21, 0
	global_load_dword v75, v5, s[20:21]
	s_add_u32 s20, s20, 0x800
	s_addc_u32 s21, s21, 0
	global_load_dword v76, v5, s[20:21]
	s_add_u32 s20, s20, 0x800
	s_addc_u32 s21, s21, 0
	global_load_dword v77, v5, s[20:21]
	s_add_u32 s20, s20, 0x800
	s_addc_u32 s21, s21, 0
	global_load_dword v78, v5, s[20:21]
	s_add_u32 s20, s20, 0x800
	s_addc_u32 s21, s21, 0
	global_load_dword v79, v5, s[20:21]
	s_mov_b64 s[20:21], s[14:15]
	global_load_dword v80, v5, s[20:21]
	s_add_u32 s20, s20, 0x800
	s_addc_u32 s21, s21, 0
	global_load_dword v81, v5, s[20:21]
	s_add_u32 s20, s20, 0x800
	s_addc_u32 s21, s21, 0
	global_load_dword v82, v5, s[20:21]
	s_add_u32 s20, s20, 0x800
	s_addc_u32 s21, s21, 0
	global_load_dword v83, v5, s[20:21]
	s_add_u32 s20, s20, 0x800
	s_addc_u32 s21, s21, 0
	global_load_dword v84, v5, s[20:21]
	s_add_u32 s20, s20, 0x800
	s_addc_u32 s21, s21, 0
	global_load_dword v85, v5, s[20:21]
	s_add_u32 s20, s20, 0x800
	s_addc_u32 s21, s21, 0
	global_load_dword v86, v5, s[20:21]
	s_add_u32 s20, s20, 0x800
	s_addc_u32 s21, s21, 0
	global_load_dword v87, v5, s[20:21]
	s_add_u32 s20, s20, 0x800
	s_addc_u32 s21, s21, 0
	global_load_dword v88, v5, s[20:21]
	s_add_u32 s20, s20, 0x800
	s_addc_u32 s21, s21, 0
	global_load_dword v89, v5, s[20:21]
	s_add_u32 s20, s20, 0x800
	s_addc_u32 s21, s21, 0
	global_load_dword v90, v5, s[20:21]
	s_add_u32 s20, s20, 0x800
	s_addc_u32 s21, s21, 0
	global_load_dword v91, v5, s[20:21]
	s_add_u32 s20, s20, 0x800
	s_addc_u32 s21, s21, 0
	global_load_dword v92, v5, s[20:21]
	s_add_u32 s20, s20, 0x800
	s_addc_u32 s21, s21, 0
	global_load_dword v93, v5, s[20:21]
	s_add_u32 s20, s20, 0x800
	s_addc_u32 s21, s21, 0
	global_load_dword v94, v5, s[20:21]
	s_add_u32 s20, s20, 0x800
	s_addc_u32 s21, s21, 0
	global_load_dword v95, v5, s[20:21]
	s_waitcnt vmcnt(31)
	v_mul_f32_e32 v10, 0xbfb8aa3b, v64
	v_exp_f32_e32 v10, v10
	s_nop 0
	v_add_f32_e32 v3, 1.0, v10
	v_div_scale_f32 v8, s[22:23], v3, v3, v64
	v_rcp_f32_e32 v10, v8
	v_div_scale_f32 v11, vcc, v64, v3, v64
	v_fma_f32 v12, -v8, v10, 1.0
	v_fmac_f32_e32 v10, v12, v10
	v_mul_f32_e32 v12, v11, v10
	v_fma_f32 v13, -v8, v12, v11
	v_fmac_f32_e32 v12, v13, v10
	v_fma_f32 v8, -v8, v12, v11
	v_div_fmas_f32 v8, v8, v10, v12
	v_div_fixup_f32 v3, v8, v3, v64
	ds_write_b32 v6, v3 offset:0
	s_waitcnt vmcnt(30)
	v_mul_f32_e32 v10, 0xbfb8aa3b, v65
	v_exp_f32_e32 v10, v10
	s_nop 0
	v_add_f32_e32 v3, 1.0, v10
	v_div_scale_f32 v8, s[22:23], v3, v3, v65
	v_rcp_f32_e32 v10, v8
	v_div_scale_f32 v11, vcc, v65, v3, v65
	v_fma_f32 v12, -v8, v10, 1.0
	v_fmac_f32_e32 v10, v12, v10
	v_mul_f32_e32 v12, v11, v10
	v_fma_f32 v13, -v8, v12, v11
	v_fmac_f32_e32 v12, v13, v10
	v_fma_f32 v8, -v8, v12, v11
	v_div_fmas_f32 v8, v8, v10, v12
	v_div_fixup_f32 v3, v8, v3, v65
	ds_write_b32 v6, v3 offset:32768
	s_waitcnt vmcnt(29)
	v_mul_f32_e32 v10, 0xbfb8aa3b, v66
	v_exp_f32_e32 v10, v10
	s_nop 0
	v_add_f32_e32 v3, 1.0, v10
	v_div_scale_f32 v8, s[22:23], v3, v3, v66
	v_rcp_f32_e32 v10, v8
	v_div_scale_f32 v11, vcc, v66, v3, v66
	v_fma_f32 v12, -v8, v10, 1.0
	v_fmac_f32_e32 v10, v12, v10
	v_mul_f32_e32 v12, v11, v10
	v_fma_f32 v13, -v8, v12, v11
	v_fmac_f32_e32 v12, v13, v10
	v_fma_f32 v8, -v8, v12, v11
	v_div_fmas_f32 v8, v8, v10, v12
	v_div_fixup_f32 v3, v8, v3, v66
	ds_write_b32 v6, v3 offset:4
	s_waitcnt vmcnt(28)
	v_mul_f32_e32 v10, 0xbfb8aa3b, v67
	v_exp_f32_e32 v10, v10
	s_nop 0
	v_add_f32_e32 v3, 1.0, v10
	v_div_scale_f32 v8, s[22:23], v3, v3, v67
	v_rcp_f32_e32 v10, v8
	v_div_scale_f32 v11, vcc, v67, v3, v67
	v_fma_f32 v12, -v8, v10, 1.0
	v_fmac_f32_e32 v10, v12, v10
	v_mul_f32_e32 v12, v11, v10
	v_fma_f32 v13, -v8, v12, v11
	v_fmac_f32_e32 v12, v13, v10
	v_fma_f32 v8, -v8, v12, v11
	v_div_fmas_f32 v8, v8, v10, v12
	v_div_fixup_f32 v3, v8, v3, v67
	ds_write_b32 v6, v3 offset:32772
	s_waitcnt vmcnt(27)
; __device__ __forceinline__ void ph_mod(const float* cp, const float* cs, const float* w_ada, const float* b_ada, float* MOD, float* MISC,
;                                        const float* lq1, const float* lk1, const float* lq2, const float* lk2, LAS unsigned char* lds, int G, int tid) {
;     ...
;     if ((int)blockIdx.x < 144) for (int i = tid; i < 16384; i += 512) { const int b = i >> 10, k = i & 1023; const float c = b < 8 ? cp[b * 1024 + k] : cs[(b - 8) * 1024 + k]; scT[k * 16 + b] = c / (1.0f + __expf(-c)); }
	v_mul_f32_e32 v10, 0xbfb8aa3b, v68
	v_exp_f32_e32 v10, v10
	s_nop 0
	v_add_f32_e32 v3, 1.0, v10
	v_div_scale_f32 v8, s[22:23], v3, v3, v68
	v_rcp_f32_e32 v10, v8
	v_div_scale_f32 v11, vcc, v68, v3, v68
	v_fma_f32 v12, -v8, v10, 1.0
	v_fmac_f32_e32 v10, v12, v10
	v_mul_f32_e32 v12, v11, v10
	v_fma_f32 v13, -v8, v12, v11
	v_fmac_f32_e32 v12, v13, v10
	v_fma_f32 v8, -v8, v12, v11
	v_div_fmas_f32 v8, v8, v10, v12
	v_div_fixup_f32 v3, v8, v3, v68
	ds_write_b32 v6, v3 offset:8
	s_waitcnt vmcnt(26)
	v_mul_f32_e32 v10, 0xbfb8aa3b, v69
	v_exp_f32_e32 v10, v10
	s_nop 0
	v_add_f32_e32 v3, 1.0, v10
	v_div_scale_f32 v8, s[22:23], v3, v3, v69
	v_rcp_f32_e32 v10, v8
	v_div_scale_f32 v11, vcc, v69, v3, v69
	v_fma_f32 v12, -v8, v10, 1.0
	v_fmac_f32_e32 v10, v12, v10
	v_mul_f32_e32 v12, v11, v10
	v_fma_f32 v13, -v8, v12, v11
	v_fmac_f32_e32 v12, v13, v10
	v_fma_f32 v8, -v8, v12, v11
	v_div_fmas_f32 v8, v8, v10, v12
	v_div_fixup_f32 v3, v8, v3, v69
	ds_write_b32 v6, v3 offset:32776
	s_waitcnt vmcnt(25)
	v_mul_f32_e32 v10, 0xbfb8aa3b, v70
	v_exp_f32_e32 v10, v10
	s_nop 0
	v_add_f32_e32 v3, 1.0, v10
	v_div_scale_f32 v8, s[22:23], v3, v3, v70
	v_rcp_f32_e32 v10, v8
	v_div_scale_f32 v11, vcc, v70, v3, v70
	v_fma_f32 v12, -v8, v10, 1.0
	v_fmac_f32_e32 v10, v12, v10
	v_mul_f32_e32 v12, v11, v10
	v_fma_f32 v13, -v8, v12, v11
	v_fmac_f32_e32 v12, v13, v10
	v_fma_f32 v8, -v8, v12, v11
	v_div_fmas_f32 v8, v8, v10, v12
	v_div_fixup_f32 v3, v8, v3, v70
	ds_write_b32 v6, v3 offset:12
	s_waitcnt vmcnt(24)
	v_mul_f32_e32 v10, 0xbfb8aa3b, v71
	v_exp_f32_e32 v10, v10
	s_nop 0
	v_add_f32_e32 v3, 1.0, v10
	v_div_scale_f32 v8, s[22:23], v3, v3, v71
	v_rcp_f32_e32 v10, v8
	v_div_scale_f32 v11, vcc, v71, v3, v71
	v_fma_f32 v12, -v8, v10, 1.0
	v_fmac_f32_e32 v10, v12, v10
	v_mul_f32_e32 v12, v11, v10
	v_fma_f32 v13, -v8, v12, v11
	v_fmac_f32_e32 v12, v13, v10
	v_fma_f32 v8, -v8, v12, v11
	v_div_fmas_f32 v8, v8, v10, v12
	v_div_fixup_f32 v3, v8, v3, v71
	ds_write_b32 v6, v3 offset:32780
	s_waitcnt vmcnt(23)
	v_mul_f32_e32 v10, 0xbfb8aa3b, v72
	v_exp_f32_e32 v10, v10
	s_nop 0
	v_add_f32_e32 v3, 1.0, v10
	v_div_scale_f32 v8, s[22:23], v3, v3, v72
	v_rcp_f32_e32 v10, v8
	v_div_scale_f32 v11, vcc, v72, v3, v72
	v_fma_f32 v12, -v8, v10, 1.0
	v_fmac_f32_e32 v10, v12, v10
	v_mul_f32_e32 v12, v11, v10
	v_fma_f32 v13, -v8, v12, v11
	v_fmac_f32_e32 v12, v13, v10
	v_fma_f32 v8, -v8, v12, v11
	v_div_fmas_f32 v8, v8, v10, v12
	v_div_fixup_f32 v3, v8, v3, v72
	ds_write_b32 v6, v3 offset:16
	s_waitcnt vmcnt(22)
	v_mul_f32_e32 v10, 0xbfb8aa3b, v73
	v_exp_f32_e32 v10, v10
	s_nop 0
	v_add_f32_e32 v3, 1.0, v10
	v_div_scale_f32 v8, s[22:23], v3, v3, v73
	v_rcp_f32_e32 v10, v8
	v_div_scale_f32 v11, vcc, v73, v3, v73
	v_fma_f32 v12, -v8, v10, 1.0
	v_fmac_f32_e32 v10, v12, v10
	v_mul_f32_e32 v12, v11, v10
	v_fma_f32 v13, -v8, v12, v11
	v_fmac_f32_e32 v12, v13, v10
	v_fma_f32 v8, -v8, v12, v11
	v_div_fmas_f32 v8, v8, v10, v12
	v_div_fixup_f32 v3, v8, v3, v73
	ds_write_b32 v6, v3 offset:32784
	s_waitcnt vmcnt(21)
	v_mul_f32_e32 v10, 0xbfb8aa3b, v74
	v_exp_f32_e32 v10, v10
	s_nop 0
	v_add_f32_e32 v3, 1.0, v10
	v_div_scale_f32 v8, s[22:23], v3, v3, v74
	v_rcp_f32_e32 v10, v8
	v_div_scale_f32 v11, vcc, v74, v3, v74
	v_fma_f32 v12, -v8, v10, 1.0
	v_fmac_f32_e32 v10, v12, v10
	v_mul_f32_e32 v12, v11, v10
	v_fma_f32 v13, -v8, v12, v11
	v_fmac_f32_e32 v12, v13, v10
	v_fma_f32 v8, -v8, v12, v11
	v_div_fmas_f32 v8, v8, v10, v12
	v_div_fixup_f32 v3, v8, v3, v74
	ds_write_b32 v6, v3 offset:20
	s_waitcnt vmcnt(20)
	v_mul_f32_e32 v10, 0xbfb8aa3b, v75
	v_exp_f32_e32 v10, v10
	s_nop 0
	v_add_f32_e32 v3, 1.0, v10
	v_div_scale_f32 v8, s[22:23], v3, v3, v75
	v_rcp_f32_e32 v10, v8
	v_div_scale_f32 v11, vcc, v75, v3, v75
	v_fma_f32 v12, -v8, v10, 1.0
	v_fmac_f32_e32 v10, v12, v10
	v_mul_f32_e32 v12, v11, v10
	v_fma_f32 v13, -v8, v12, v11
	v_fmac_f32_e32 v12, v13, v10
	v_fma_f32 v8, -v8, v12, v11
	v_div_fmas_f32 v8, v8, v10, v12
	v_div_fixup_f32 v3, v8, v3, v75
	ds_write_b32 v6, v3 offset:32788
	s_waitcnt vmcnt(19)
	v_mul_f32_e32 v10, 0xbfb8aa3b, v76
	v_exp_f32_e32 v10, v10
	s_nop 0
	v_add_f32_e32 v3, 1.0, v10
	v_div_scale_f32 v8, s[22:23], v3, v3, v76
	v_rcp_f32_e32 v10, v8
	v_div_scale_f32 v11, vcc, v76, v3, v76
	v_fma_f32 v12, -v8, v10, 1.0
	v_fmac_f32_e32 v10, v12, v10
	v_mul_f32_e32 v12, v11, v10
	v_fma_f32 v13, -v8, v12, v11
	v_fmac_f32_e32 v12, v13, v10
	v_fma_f32 v8, -v8, v12, v11
	v_div_fmas_f32 v8, v8, v10, v12
	v_div_fixup_f32 v3, v8, v3, v76
	ds_write_b32 v6, v3 offset:24
	s_waitcnt vmcnt(18)
	v_mul_f32_e32 v10, 0xbfb8aa3b, v77
	v_exp_f32_e32 v10, v10
	s_nop 0
	v_add_f32_e32 v3, 1.0, v10
	v_div_scale_f32 v8, s[22:23], v3, v3, v77
	v_rcp_f32_e32 v10, v8
	v_div_scale_f32 v11, vcc, v77, v3, v77
	v_fma_f32 v12, -v8, v10, 1.0
	v_fmac_f32_e32 v10, v12, v10
	v_mul_f32_e32 v12, v11, v10
	v_fma_f32 v13, -v8, v12, v11
	v_fmac_f32_e32 v12, v13, v10
	v_fma_f32 v8, -v8, v12, v11
	v_div_fmas_f32 v8, v8, v10, v12
	v_div_fixup_f32 v3, v8, v3, v77
	ds_write_b32 v6, v3 offset:32792
	s_waitcnt vmcnt(17)
	v_mul_f32_e32 v10, 0xbfb8aa3b, v78
	v_exp_f32_e32 v10, v10
	s_nop 0
	v_add_f32_e32 v3, 1.0, v10
	v_div_scale_f32 v8, s[22:23], v3, v3, v78
	v_rcp_f32_e32 v10, v8
	v_div_scale_f32 v11, vcc, v78, v3, v78
	v_fma_f32 v12, -v8, v10, 1.0
	v_fmac_f32_e32 v10, v12, v10
	v_mul_f32_e32 v12, v11, v10
	v_fma_f32 v13, -v8, v12, v11
	v_fmac_f32_e32 v12, v13, v10
	v_fma_f32 v8, -v8, v12, v11
	v_div_fmas_f32 v8, v8, v10, v12
	v_div_fixup_f32 v3, v8, v3, v78
	ds_write_b32 v6, v3 offset:28
	s_waitcnt vmcnt(16)
; __device__ __forceinline__ void ph_mod(const float* cp, const float* cs, const float* w_ada, const float* b_ada, float* MOD, float* MISC,
;                                        const float* lq1, const float* lk1, const float* lq2, const float* lk2, LAS unsigned char* lds, int G, int tid) {
;     ...
;     if ((int)blockIdx.x < 144) for (int i = tid; i < 16384; i += 512) { const int b = i >> 10, k = i & 1023; const float c = b < 8 ? cp[b * 1024 + k] : cs[(b - 8) * 1024 + k]; scT[k * 16 + b] = c / (1.0f + __expf(-c)); }
	v_mul_f32_e32 v10, 0xbfb8aa3b, v79
	v_exp_f32_e32 v10, v10
	s_nop 0
	v_add_f32_e32 v3, 1.0, v10
	v_div_scale_f32 v8, s[22:23], v3, v3, v79
	v_rcp_f32_e32 v10, v8
	v_div_scale_f32 v11, vcc, v79, v3, v79
	v_fma_f32 v12, -v8, v10, 1.0
	v_fmac_f32_e32 v10, v12, v10
	v_mul_f32_e32 v12, v11, v10
	v_fma_f32 v13, -v8, v12, v11
	v_fmac_f32_e32 v12, v13, v10
	v_fma_f32 v8, -v8, v12, v11
	v_div_fmas_f32 v8, v8, v10, v12
	v_div_fixup_f32 v3, v8, v3, v79
	ds_write_b32 v6, v3 offset:32796
	s_waitcnt vmcnt(15)
	v_mul_f32_e32 v10, 0xbfb8aa3b, v80
	v_exp_f32_e32 v10, v10
	s_nop 0
	v_add_f32_e32 v3, 1.0, v10
	v_div_scale_f32 v8, s[22:23], v3, v3, v80
	v_rcp_f32_e32 v10, v8
	v_div_scale_f32 v11, vcc, v80, v3, v80
	v_fma_f32 v12, -v8, v10, 1.0
	v_fmac_f32_e32 v10, v12, v10
	v_mul_f32_e32 v12, v11, v10
	v_fma_f32 v13, -v8, v12, v11
	v_fmac_f32_e32 v12, v13, v10
	v_fma_f32 v8, -v8, v12, v11
	v_div_fmas_f32 v8, v8, v10, v12
	v_div_fixup_f32 v3, v8, v3, v80
	ds_write_b32 v6, v3 offset:32
	s_waitcnt vmcnt(14)
	v_mul_f32_e32 v10, 0xbfb8aa3b, v81
	v_exp_f32_e32 v10, v10
	s_nop 0
	v_add_f32_e32 v3, 1.0, v10
	v_div_scale_f32 v8, s[22:23], v3, v3, v81
	v_rcp_f32_e32 v10, v8
	v_div_scale_f32 v11, vcc, v81, v3, v81
	v_fma_f32 v12, -v8, v10, 1.0
	v_fmac_f32_e32 v10, v12, v10
	v_mul_f32_e32 v12, v11, v10
	v_fma_f32 v13, -v8, v12, v11
	v_fmac_f32_e32 v12, v13, v10
	v_fma_f32 v8, -v8, v12, v11
	v_div_fmas_f32 v8, v8, v10, v12
	v_div_fixup_f32 v3, v8, v3, v81
	ds_write_b32 v6, v3 offset:32800
	s_waitcnt vmcnt(13)
	v_mul_f32_e32 v10, 0xbfb8aa3b, v82
	v_exp_f32_e32 v10, v10
	s_nop 0
	v_add_f32_e32 v3, 1.0, v10
	v_div_scale_f32 v8, s[22:23], v3, v3, v82
	v_rcp_f32_e32 v10, v8
	v_div_scale_f32 v11, vcc, v82, v3, v82
	v_fma_f32 v12, -v8, v10, 1.0
	v_fmac_f32_e32 v10, v12, v10
	v_mul_f32_e32 v12, v11, v10
	v_fma_f32 v13, -v8, v12, v11
	v_fmac_f32_e32 v12, v13, v10
	v_fma_f32 v8, -v8, v12, v11
	v_div_fmas_f32 v8, v8, v10, v12
	v_div_fixup_f32 v3, v8, v3, v82
	ds_write_b32 v6, v3 offset:36
	s_waitcnt vmcnt(12)
	v_mul_f32_e32 v10, 0xbfb8aa3b, v83
	v_exp_f32_e32 v10, v10
	s_nop 0
	v_add_f32_e32 v3, 1.0, v10
	v_div_scale_f32 v8, s[22:23], v3, v3, v83
	v_rcp_f32_e32 v10, v8
	v_div_scale_f32 v11, vcc, v83, v3, v83
	v_fma_f32 v12, -v8, v10, 1.0
	v_fmac_f32_e32 v10, v12, v10
	v_mul_f32_e32 v12, v11, v10
	v_fma_f32 v13, -v8, v12, v11
	v_fmac_f32_e32 v12, v13, v10
	v_fma_f32 v8, -v8, v12, v11
	v_div_fmas_f32 v8, v8, v10, v12
	v_div_fixup_f32 v3, v8, v3, v83
	ds_write_b32 v6, v3 offset:32804
	s_waitcnt vmcnt(11)
	v_mul_f32_e32 v10, 0xbfb8aa3b, v84
	v_exp_f32_e32 v10, v10
	s_nop 0
	v_add_f32_e32 v3, 1.0, v10
	v_div_scale_f32 v8, s[22:23], v3, v3, v84
	v_rcp_f32_e32 v10, v8
	v_div_scale_f32 v11, vcc, v84, v3, v84
	v_fma_f32 v12, -v8, v10, 1.0
	v_fmac_f32_e32 v10, v12, v10
	v_mul_f32_e32 v12, v11, v10
	v_fma_f32 v13, -v8, v12, v11
	v_fmac_f32_e32 v12, v13, v10
	v_fma_f32 v8, -v8, v12, v11
	v_div_fmas_f32 v8, v8, v10, v12
	v_div_fixup_f32 v3, v8, v3, v84
	ds_write_b32 v6, v3 offset:40
	s_waitcnt vmcnt(10)
	v_mul_f32_e32 v10, 0xbfb8aa3b, v85
	v_exp_f32_e32 v10, v10
	s_nop 0
	v_add_f32_e32 v3, 1.0, v10
	v_div_scale_f32 v8, s[22:23], v3, v3, v85
	v_rcp_f32_e32 v10, v8
	v_div_scale_f32 v11, vcc, v85, v3, v85
	v_fma_f32 v12, -v8, v10, 1.0
	v_fmac_f32_e32 v10, v12, v10
	v_mul_f32_e32 v12, v11, v10
	v_fma_f32 v13, -v8, v12, v11
	v_fmac_f32_e32 v12, v13, v10
	v_fma_f32 v8, -v8, v12, v11
	v_div_fmas_f32 v8, v8, v10, v12
	v_div_fixup_f32 v3, v8, v3, v85
	ds_write_b32 v6, v3 offset:32808
	s_waitcnt vmcnt(9)
	v_mul_f32_e32 v10, 0xbfb8aa3b, v86
	v_exp_f32_e32 v10, v10
	s_nop 0
	v_add_f32_e32 v3, 1.0, v10
	v_div_scale_f32 v8, s[22:23], v3, v3, v86
	v_rcp_f32_e32 v10, v8
	v_div_scale_f32 v11, vcc, v86, v3, v86
	v_fma_f32 v12, -v8, v10, 1.0
	v_fmac_f32_e32 v10, v12, v10
	v_mul_f32_e32 v12, v11, v10
	v_fma_f32 v13, -v8, v12, v11
	v_fmac_f32_e32 v12, v13, v10
	v_fma_f32 v8, -v8, v12, v11
	v_div_fmas_f32 v8, v8, v10, v12
	v_div_fixup_f32 v3, v8, v3, v86
	ds_write_b32 v6, v3 offset:44
	s_waitcnt vmcnt(8)
	v_mul_f32_e32 v10, 0xbfb8aa3b, v87
	v_exp_f32_e32 v10, v10
	s_nop 0
	v_add_f32_e32 v3, 1.0, v10
	v_div_scale_f32 v8, s[22:23], v3, v3, v87
	v_rcp_f32_e32 v10, v8
	v_div_scale_f32 v11, vcc, v87, v3, v87
	v_fma_f32 v12, -v8, v10, 1.0
	v_fmac_f32_e32 v10, v12, v10
	v_mul_f32_e32 v12, v11, v10
	v_fma_f32 v13, -v8, v12, v11
	v_fmac_f32_e32 v12, v13, v10
	v_fma_f32 v8, -v8, v12, v11
	v_div_fmas_f32 v8, v8, v10, v12
	v_div_fixup_f32 v3, v8, v3, v87
	ds_write_b32 v6, v3 offset:32812
	s_waitcnt vmcnt(7)
	v_mul_f32_e32 v10, 0xbfb8aa3b, v88
	v_exp_f32_e32 v10, v10
	s_nop 0
	v_add_f32_e32 v3, 1.0, v10
	v_div_scale_f32 v8, s[22:23], v3, v3, v88
	v_rcp_f32_e32 v10, v8
	v_div_scale_f32 v11, vcc, v88, v3, v88
	v_fma_f32 v12, -v8, v10, 1.0
	v_fmac_f32_e32 v10, v12, v10
	v_mul_f32_e32 v12, v11, v10
	v_fma_f32 v13, -v8, v12, v11
	v_fmac_f32_e32 v12, v13, v10
	v_fma_f32 v8, -v8, v12, v11
	v_div_fmas_f32 v8, v8, v10, v12
	v_div_fixup_f32 v3, v8, v3, v88
	ds_write_b32 v6, v3 offset:48
	s_waitcnt vmcnt(6)
	v_mul_f32_e32 v10, 0xbfb8aa3b, v89
	v_exp_f32_e32 v10, v10
	s_nop 0
	v_add_f32_e32 v3, 1.0, v10
	v_div_scale_f32 v8, s[22:23], v3, v3, v89
	v_rcp_f32_e32 v10, v8
	v_div_scale_f32 v11, vcc, v89, v3, v89
	v_fma_f32 v12, -v8, v10, 1.0
	v_fmac_f32_e32 v10, v12, v10
	v_mul_f32_e32 v12, v11, v10
	v_fma_f32 v13, -v8, v12, v11
	v_fmac_f32_e32 v12, v13, v10
	v_fma_f32 v8, -v8, v12, v11
	v_div_fmas_f32 v8, v8, v10, v12
	v_div_fixup_f32 v3, v8, v3, v89
	ds_write_b32 v6, v3 offset:32816
	s_waitcnt vmcnt(5)
; #define LAS __attribute__((address_space(3)))
; __device__ __forceinline__ void ph_mod(const float* cp, const float* cs, const float* w_ada, const float* b_ada, float* MOD, float* MISC,
;                                        const float* lq1, const float* lk1, const float* lq2, const float* lk2, LAS unsigned char* lds, int G, int tid) {
;     ...
;     if ((int)blockIdx.x < 144) for (int i = tid; i < 16384; i += 512) { const int b = i >> 10, k = i & 1023; const float c = b < 8 ? cp[b * 1024 + k] : cs[(b - 8) * 1024 + k]; scT[k * 16 + b] = c / (1.0f + __expf(-c)); }
;     __syncthreads();
;     for (int unit = blockIdx.x; unit < 144; unit += G) {
;         const int col = unit * 64 + lane;
;         float acc[16];
; #pragma unroll
;         for (int b = 0; b < 16; ++b) acc[b] = 0.f;
;         const int k0 = wave * 128;
; #pragma unroll 16
;         for (int kk = 0; kk < 128; ++kk) { const int k = k0 + kk; const float wv = w_ada[(size_t)k * 9216 + col];
;             const f32x4 s0 = *(const LAS f32x4*)(scT + k * 16), s1 = *(const LAS f32x4*)(scT + k * 16 + 4), s2 = *(const LAS f32x4*)(scT + k * 16 + 8), s3 = *(const LAS f32x4*)(scT + k * 16 + 12);
	v_mul_f32_e32 v10, 0xbfb8aa3b, v90
	v_exp_f32_e32 v10, v10
	s_nop 0
	v_add_f32_e32 v3, 1.0, v10
	v_div_scale_f32 v8, s[22:23], v3, v3, v90
	v_rcp_f32_e32 v10, v8
	v_div_scale_f32 v11, vcc, v90, v3, v90
	v_fma_f32 v12, -v8, v10, 1.0
	v_fmac_f32_e32 v10, v12, v10
	v_mul_f32_e32 v12, v11, v10
	v_fma_f32 v13, -v8, v12, v11
	v_fmac_f32_e32 v12, v13, v10
	v_fma_f32 v8, -v8, v12, v11
	v_div_fmas_f32 v8, v8, v10, v12
	v_div_fixup_f32 v3, v8, v3, v90
	ds_write_b32 v6, v3 offset:52
	s_waitcnt vmcnt(4)
	v_mul_f32_e32 v10, 0xbfb8aa3b, v91
	v_exp_f32_e32 v10, v10
	s_nop 0
	v_add_f32_e32 v3, 1.0, v10
	v_div_scale_f32 v8, s[22:23], v3, v3, v91
	v_rcp_f32_e32 v10, v8
	v_div_scale_f32 v11, vcc, v91, v3, v91
	v_fma_f32 v12, -v8, v10, 1.0
	v_fmac_f32_e32 v10, v12, v10
	v_mul_f32_e32 v12, v11, v10
	v_fma_f32 v13, -v8, v12, v11
	v_fmac_f32_e32 v12, v13, v10
	v_fma_f32 v8, -v8, v12, v11
	v_div_fmas_f32 v8, v8, v10, v12
	v_div_fixup_f32 v3, v8, v3, v91
	ds_write_b32 v6, v3 offset:32820
	s_waitcnt vmcnt(3)
	v_mul_f32_e32 v10, 0xbfb8aa3b, v92
	v_exp_f32_e32 v10, v10
	s_nop 0
	v_add_f32_e32 v3, 1.0, v10
	v_div_scale_f32 v8, s[22:23], v3, v3, v92
	v_rcp_f32_e32 v10, v8
	v_div_scale_f32 v11, vcc, v92, v3, v92
	v_fma_f32 v12, -v8, v10, 1.0
	v_fmac_f32_e32 v10, v12, v10
	v_mul_f32_e32 v12, v11, v10
	v_fma_f32 v13, -v8, v12, v11
	v_fmac_f32_e32 v12, v13, v10
	v_fma_f32 v8, -v8, v12, v11
	v_div_fmas_f32 v8, v8, v10, v12
	v_div_fixup_f32 v3, v8, v3, v92
	ds_write_b32 v6, v3 offset:56
	s_waitcnt vmcnt(2)
	v_mul_f32_e32 v10, 0xbfb8aa3b, v93
	v_exp_f32_e32 v10, v10
	s_nop 0
	v_add_f32_e32 v3, 1.0, v10
	v_div_scale_f32 v8, s[22:23], v3, v3, v93
	v_rcp_f32_e32 v10, v8
	v_div_scale_f32 v11, vcc, v93, v3, v93
	v_fma_f32 v12, -v8, v10, 1.0
	v_fmac_f32_e32 v10, v12, v10
	v_mul_f32_e32 v12, v11, v10
	v_fma_f32 v13, -v8, v12, v11
	v_fmac_f32_e32 v12, v13, v10
	v_fma_f32 v8, -v8, v12, v11
	v_div_fmas_f32 v8, v8, v10, v12
	v_div_fixup_f32 v3, v8, v3, v93
	ds_write_b32 v6, v3 offset:32824
	s_waitcnt vmcnt(1)
	v_mul_f32_e32 v10, 0xbfb8aa3b, v94
	v_exp_f32_e32 v10, v10
	s_nop 0
	v_add_f32_e32 v3, 1.0, v10
	v_div_scale_f32 v8, s[22:23], v3, v3, v94
	v_rcp_f32_e32 v10, v8
	v_div_scale_f32 v11, vcc, v94, v3, v94
	v_fma_f32 v12, -v8, v10, 1.0
	v_fmac_f32_e32 v10, v12, v10
	v_mul_f32_e32 v12, v11, v10
	v_fma_f32 v13, -v8, v12, v11
	v_fmac_f32_e32 v12, v13, v10
	v_fma_f32 v8, -v8, v12, v11
	v_div_fmas_f32 v8, v8, v10, v12
	v_div_fixup_f32 v3, v8, v3, v94
	ds_write_b32 v6, v3 offset:60
	s_waitcnt vmcnt(0)
	v_mul_f32_e32 v10, 0xbfb8aa3b, v95
	v_exp_f32_e32 v10, v10
	s_nop 0
	v_add_f32_e32 v3, 1.0, v10
	v_div_scale_f32 v8, s[22:23], v3, v3, v95
	v_rcp_f32_e32 v10, v8
	v_div_scale_f32 v11, vcc, v95, v3, v95
	v_fma_f32 v12, -v8, v10, 1.0
	v_fmac_f32_e32 v10, v12, v10
	v_mul_f32_e32 v12, v11, v10
	v_fma_f32 v13, -v8, v12, v11
	v_fmac_f32_e32 v12, v13, v10
	v_fma_f32 v8, -v8, v12, v11
	v_div_fmas_f32 v8, v8, v10, v12
	v_div_fixup_f32 v3, v8, v3, v95
	ds_write_b32 v6, v3 offset:32828
	s_waitcnt lgkmcnt(0)
	s_barrier
	v_readlane_b32 s34, v254, 6
	v_readfirstlane_b32 s24, v2
	s_lshr_b32 s24, s24, 6
	s_lshl_b32 s25, s24, 13
	v_mov_b32_e32 v7, s25
	s_lshl_b32 s26, s24, 12
	s_add_i32 s26, s26, 0x10000
	v_add_u32_e32 v9, s26, v4
	v_lshlrev_b32_e32 v14, 2, v2
	v_add_u32_e32 v14, 0x10000, v14
.Lp0_unit:
	s_mul_i32 s27, s24, 0x480000
	s_lshl_b32 s28, s34, 8
	s_add_u32 s20, s0, s27
	s_addc_u32 s21, s1, 0
	s_add_u32 s20, s20, s28
	s_addc_u32 s21, s21, 0
	v_mov_b32_e32 v16, 0
	v_mov_b32_e32 v17, 0
	v_mov_b32_e32 v18, 0
	v_mov_b32_e32 v19, 0
	v_mov_b32_e32 v20, 0
	v_mov_b32_e32 v21, 0
	v_mov_b32_e32 v22, 0
	v_mov_b32_e32 v23, 0
	v_mov_b32_e32 v24, 0
	v_mov_b32_e32 v25, 0
	v_mov_b32_e32 v26, 0
	v_mov_b32_e32 v27, 0
	v_mov_b32_e32 v28, 0
	v_mov_b32_e32 v29, 0
	v_mov_b32_e32 v30, 0
	v_mov_b32_e32 v31, 0
	global_load_dword v64, v4, s[20:21]
	s_add_u32 s20, s20, 0x9000
	s_addc_u32 s21, s21, 0
	global_load_dword v65, v4, s[20:21]
	s_add_u32 s20, s20, 0x9000
	s_addc_u32 s21, s21, 0
	global_load_dword v66, v4, s[20:21]
	s_add_u32 s20, s20, 0x9000
	s_addc_u32 s21, s21, 0
	global_load_dword v67, v4, s[20:21]
	s_add_u32 s20, s20, 0x9000
	s_addc_u32 s21, s21, 0
	global_load_dword v68, v4, s[20:21]
	s_add_u32 s20, s20, 0x9000
	s_addc_u32 s21, s21, 0
	global_load_dword v69, v4, s[20:21]
	s_add_u32 s20, s20, 0x9000
	s_addc_u32 s21, s21, 0
	global_load_dword v70, v4, s[20:21]
	s_add_u32 s20, s20, 0x9000
	s_addc_u32 s21, s21, 0
	global_load_dword v71, v4, s[20:21]
	s_add_u32 s20, s20, 0x9000
	s_addc_u32 s21, s21, 0
	global_load_dword v72, v4, s[20:21]
	s_add_u32 s20, s20, 0x9000
	s_addc_u32 s21, s21, 0
	global_load_dword v73, v4, s[20:21]
	s_add_u32 s20, s20, 0x9000
	s_addc_u32 s21, s21, 0
	global_load_dword v74, v4, s[20:21]
	s_add_u32 s20, s20, 0x9000
	s_addc_u32 s21, s21, 0
	global_load_dword v75, v4, s[20:21]
	s_add_u32 s20, s20, 0x9000
	s_addc_u32 s21, s21, 0
	global_load_dword v76, v4, s[20:21]
	s_add_u32 s20, s20, 0x9000
	s_addc_u32 s21, s21, 0
	global_load_dword v77, v4, s[20:21]
	s_add_u32 s20, s20, 0x9000
	s_addc_u32 s21, s21, 0
	global_load_dword v78, v4, s[20:21]
	s_add_u32 s20, s20, 0x9000
	s_addc_u32 s21, s21, 0
	global_load_dword v79, v4, s[20:21]
	s_add_u32 s20, s20, 0x9000
	s_addc_u32 s21, s21, 0
	global_load_dword v80, v4, s[20:21]
	s_add_u32 s20, s20, 0x9000
	s_addc_u32 s21, s21, 0
	global_load_dword v81, v4, s[20:21]
	s_add_u32 s20, s20, 0x9000
	s_addc_u32 s21, s21, 0
	global_load_dword v82, v4, s[20:21]
	s_add_u32 s20, s20, 0x9000
	s_addc_u32 s21, s21, 0
	global_load_dword v83, v4, s[20:21]
	s_add_u32 s20, s20, 0x9000
	s_addc_u32 s21, s21, 0
	global_load_dword v84, v4, s[20:21]
	s_add_u32 s20, s20, 0x9000
; #define LAS __attribute__((address_space(3)))
; __device__ __forceinline__ void ph_mod(const float* cp, const float* cs, const float* w_ada, const float* b_ada, float* MOD, float* MISC,
;                                        const float* lq1, const float* lk1, const float* lq2, const float* lk2, LAS unsigned char* lds, int G, int tid) {
;     ...
; #pragma unroll 16
;         for (int kk = 0; kk < 128; ++kk) { const int k = k0 + kk; const float wv = w_ada[(size_t)k * 9216 + col];
;             const f32x4 s0 = *(const LAS f32x4*)(scT + k * 16), s1 = *(const LAS f32x4*)(scT + k * 16 + 4), s2 = *(const LAS f32x4*)(scT + k * 16 + 8), s3 = *(const LAS f32x4*)(scT + k * 16 + 12);
;             acc[0] += s0[0] * wv; acc[1] += s0[1] * wv; acc[2] += s0[2] * wv; acc[3] += s0[3] * wv; acc[4] += s1[0] * wv; acc[5] += s1[1] * wv; acc[6] += s1[2] * wv; acc[7] += s1[3] * wv;
;             acc[8] += s2[0] * wv; acc[9] += s2[1] * wv; acc[10] += s2[2] * wv; acc[11] += s2[3] * wv; acc[12] += s3[0] * wv; acc[13] += s3[1] * wv; acc[14] += s3[2] * wv; acc[15] += s3[3] * wv; }
	s_addc_u32 s21, s21, 0
	global_load_dword v85, v4, s[20:21]
	s_add_u32 s20, s20, 0x9000
	s_addc_u32 s21, s21, 0
	global_load_dword v86, v4, s[20:21]
	s_add_u32 s20, s20, 0x9000
	s_addc_u32 s21, s21, 0
	global_load_dword v87, v4, s[20:21]
	s_add_u32 s20, s20, 0x9000
	s_addc_u32 s21, s21, 0
	global_load_dword v88, v4, s[20:21]
	s_add_u32 s20, s20, 0x9000
	s_addc_u32 s21, s21, 0
	global_load_dword v89, v4, s[20:21]
	s_add_u32 s20, s20, 0x9000
	s_addc_u32 s21, s21, 0
	global_load_dword v90, v4, s[20:21]
	s_add_u32 s20, s20, 0x9000
	s_addc_u32 s21, s21, 0
	global_load_dword v91, v4, s[20:21]
	s_add_u32 s20, s20, 0x9000
	s_addc_u32 s21, s21, 0
	global_load_dword v92, v4, s[20:21]
	s_add_u32 s20, s20, 0x9000
	s_addc_u32 s21, s21, 0
	global_load_dword v93, v4, s[20:21]
	s_add_u32 s20, s20, 0x9000
	s_addc_u32 s21, s21, 0
	global_load_dword v94, v4, s[20:21]
	s_add_u32 s20, s20, 0x9000
	s_addc_u32 s21, s21, 0
	global_load_dword v95, v4, s[20:21]
	s_add_u32 s20, s20, 0x9000
	s_addc_u32 s21, s21, 0
	global_load_dword v96, v4, s[20:21]
	s_add_u32 s20, s20, 0x9000
	s_addc_u32 s21, s21, 0
	global_load_dword v97, v4, s[20:21]
	s_add_u32 s20, s20, 0x9000
	s_addc_u32 s21, s21, 0
	global_load_dword v98, v4, s[20:21]
	s_add_u32 s20, s20, 0x9000
	s_addc_u32 s21, s21, 0
	global_load_dword v99, v4, s[20:21]
	s_add_u32 s20, s20, 0x9000
	s_addc_u32 s21, s21, 0
	global_load_dword v100, v4, s[20:21]
	s_add_u32 s20, s20, 0x9000
	s_addc_u32 s21, s21, 0
	global_load_dword v101, v4, s[20:21]
	s_add_u32 s20, s20, 0x9000
	s_addc_u32 s21, s21, 0
	global_load_dword v102, v4, s[20:21]
	s_add_u32 s20, s20, 0x9000
	s_addc_u32 s21, s21, 0
	global_load_dword v103, v4, s[20:21]
	s_add_u32 s20, s20, 0x9000
	s_addc_u32 s21, s21, 0
	global_load_dword v104, v4, s[20:21]
	s_add_u32 s20, s20, 0x9000
	s_addc_u32 s21, s21, 0
	global_load_dword v105, v4, s[20:21]
	s_add_u32 s20, s20, 0x9000
	s_addc_u32 s21, s21, 0
	global_load_dword v106, v4, s[20:21]
	s_add_u32 s20, s20, 0x9000
	s_addc_u32 s21, s21, 0
	global_load_dword v107, v4, s[20:21]
	s_add_u32 s20, s20, 0x9000
	s_addc_u32 s21, s21, 0
	global_load_dword v108, v4, s[20:21]
	s_add_u32 s20, s20, 0x9000
	s_addc_u32 s21, s21, 0
	global_load_dword v109, v4, s[20:21]
	s_add_u32 s20, s20, 0x9000
	s_addc_u32 s21, s21, 0
	global_load_dword v110, v4, s[20:21]
	s_add_u32 s20, s20, 0x9000
	s_addc_u32 s21, s21, 0
	global_load_dword v111, v4, s[20:21]
	s_add_u32 s20, s20, 0x9000
	s_addc_u32 s21, s21, 0
	global_load_dword v112, v4, s[20:21]
	s_add_u32 s20, s20, 0x9000
	s_addc_u32 s21, s21, 0
	global_load_dword v113, v4, s[20:21]
	s_add_u32 s20, s20, 0x9000
	s_addc_u32 s21, s21, 0
	global_load_dword v114, v4, s[20:21]
	s_add_u32 s20, s20, 0x9000
	s_addc_u32 s21, s21, 0
	global_load_dword v115, v4, s[20:21]
	s_add_u32 s20, s20, 0x9000
	s_addc_u32 s21, s21, 0
	global_load_dword v116, v4, s[20:21]
	s_add_u32 s20, s20, 0x9000
	s_addc_u32 s21, s21, 0
	global_load_dword v117, v4, s[20:21]
	s_add_u32 s20, s20, 0x9000
	s_addc_u32 s21, s21, 0
	global_load_dword v118, v4, s[20:21]
	s_add_u32 s20, s20, 0x9000
	s_addc_u32 s21, s21, 0
	global_load_dword v119, v4, s[20:21]
	s_add_u32 s20, s20, 0x9000
	s_addc_u32 s21, s21, 0
	global_load_dword v120, v4, s[20:21]
	s_add_u32 s20, s20, 0x9000
	s_addc_u32 s21, s21, 0
	global_load_dword v121, v4, s[20:21]
	s_add_u32 s20, s20, 0x9000
	s_addc_u32 s21, s21, 0
	global_load_dword v122, v4, s[20:21]
	s_add_u32 s20, s20, 0x9000
	s_addc_u32 s21, s21, 0
	global_load_dword v123, v4, s[20:21]
	s_add_u32 s20, s20, 0x9000
	s_addc_u32 s21, s21, 0
	global_load_dword v124, v4, s[20:21]
	s_add_u32 s20, s20, 0x9000
	s_addc_u32 s21, s21, 0
	global_load_dword v125, v4, s[20:21]
	s_add_u32 s20, s20, 0x9000
	s_addc_u32 s21, s21, 0
	global_load_dword v126, v4, s[20:21]
	s_add_u32 s20, s20, 0x9000
	s_addc_u32 s21, s21, 0
	global_load_dword v127, v4, s[20:21]
	s_add_u32 s20, s20, 0x9000
	s_addc_u32 s21, s21, 0
	ds_read_b128 v[32:35], v7 offset:0
	ds_read_b128 v[36:39], v7 offset:16
	ds_read_b128 v[40:43], v7 offset:32
	ds_read_b128 v[44:47], v7 offset:48
	ds_read_b128 v[48:51], v7 offset:64
	ds_read_b128 v[52:55], v7 offset:80
	ds_read_b128 v[56:59], v7 offset:96
	ds_read_b128 v[60:63], v7 offset:112
	s_waitcnt vmcnt(63) lgkmcnt(4)
	v_pk_fma_f32 v[16:17], v[32:33], v[64:65], v[16:17] op_sel_hi:[1,0,1]
	v_pk_fma_f32 v[18:19], v[34:35], v[64:65], v[18:19] op_sel_hi:[1,0,1]
	v_pk_fma_f32 v[20:21], v[36:37], v[64:65], v[20:21] op_sel_hi:[1,0,1]
	v_pk_fma_f32 v[22:23], v[38:39], v[64:65], v[22:23] op_sel_hi:[1,0,1]
	v_pk_fma_f32 v[24:25], v[40:41], v[64:65], v[24:25] op_sel_hi:[1,0,1]
	v_pk_fma_f32 v[26:27], v[42:43], v[64:65], v[26:27] op_sel_hi:[1,0,1]
	v_pk_fma_f32 v[28:29], v[44:45], v[64:65], v[28:29] op_sel_hi:[1,0,1]
	v_pk_fma_f32 v[30:31], v[46:47], v[64:65], v[30:31] op_sel_hi:[1,0,1]
	ds_read_b128 v[32:35], v7 offset:128
	ds_read_b128 v[36:39], v7 offset:144
	ds_read_b128 v[40:43], v7 offset:160
	ds_read_b128 v[44:47], v7 offset:176
	s_waitcnt vmcnt(62) lgkmcnt(4)
	v_pk_fma_f32 v[16:17], v[48:49], v[64:65], v[16:17] op_sel:[0,1,0] op_sel_hi:[1,1,1]
	v_pk_fma_f32 v[18:19], v[50:51], v[64:65], v[18:19] op_sel:[0,1,0] op_sel_hi:[1,1,1]
	v_pk_fma_f32 v[20:21], v[52:53], v[64:65], v[20:21] op_sel:[0,1,0] op_sel_hi:[1,1,1]
	v_pk_fma_f32 v[22:23], v[54:55], v[64:65], v[22:23] op_sel:[0,1,0] op_sel_hi:[1,1,1]
	v_pk_fma_f32 v[24:25], v[56:57], v[64:65], v[24:25] op_sel:[0,1,0] op_sel_hi:[1,1,1]
	v_pk_fma_f32 v[26:27], v[58:59], v[64:65], v[26:27] op_sel:[0,1,0] op_sel_hi:[1,1,1]
	v_pk_fma_f32 v[28:29], v[60:61], v[64:65], v[28:29] op_sel:[0,1,0] op_sel_hi:[1,1,1]
	v_pk_fma_f32 v[30:31], v[62:63], v[64:65], v[30:31] op_sel:[0,1,0] op_sel_hi:[1,1,1]
	ds_read_b128 v[48:51], v7 offset:192
	ds_read_b128 v[52:55], v7 offset:208
	ds_read_b128 v[56:59], v7 offset:224
	ds_read_b128 v[60:63], v7 offset:240
	s_waitcnt vmcnt(61) lgkmcnt(4)
; #define LAS __attribute__((address_space(3)))
; __device__ __forceinline__ void ph_mod(const float* cp, const float* cs, const float* w_ada, const float* b_ada, float* MOD, float* MISC,
;                                        const float* lq1, const float* lk1, const float* lq2, const float* lk2, LAS unsigned char* lds, int G, int tid) {
;     ...
; #pragma unroll 16
;         for (int kk = 0; kk < 128; ++kk) { const int k = k0 + kk; const float wv = w_ada[(size_t)k * 9216 + col];
;             const f32x4 s0 = *(const LAS f32x4*)(scT + k * 16), s1 = *(const LAS f32x4*)(scT + k * 16 + 4), s2 = *(const LAS f32x4*)(scT + k * 16 + 8), s3 = *(const LAS f32x4*)(scT + k * 16 + 12);
;             acc[0] += s0[0] * wv; acc[1] += s0[1] * wv; acc[2] += s0[2] * wv; acc[3] += s0[3] * wv; acc[4] += s1[0] * wv; acc[5] += s1[1] * wv; acc[6] += s1[2] * wv; acc[7] += s1[3] * wv;
;             acc[8] += s2[0] * wv; acc[9] += s2[1] * wv; acc[10] += s2[2] * wv; acc[11] += s2[3] * wv; acc[12] += s3[0] * wv; acc[13] += s3[1] * wv; acc[14] += s3[2] * wv; acc[15] += s3[3] * wv; }
	v_pk_fma_f32 v[16:17], v[32:33], v[66:67], v[16:17] op_sel_hi:[1,0,1]
	v_pk_fma_f32 v[18:19], v[34:35], v[66:67], v[18:19] op_sel_hi:[1,0,1]
	v_pk_fma_f32 v[20:21], v[36:37], v[66:67], v[20:21] op_sel_hi:[1,0,1]
	v_pk_fma_f32 v[22:23], v[38:39], v[66:67], v[22:23] op_sel_hi:[1,0,1]
	v_pk_fma_f32 v[24:25], v[40:41], v[66:67], v[24:25] op_sel_hi:[1,0,1]
	v_pk_fma_f32 v[26:27], v[42:43], v[66:67], v[26:27] op_sel_hi:[1,0,1]
	v_pk_fma_f32 v[28:29], v[44:45], v[66:67], v[28:29] op_sel_hi:[1,0,1]
	v_pk_fma_f32 v[30:31], v[46:47], v[66:67], v[30:31] op_sel_hi:[1,0,1]
	ds_read_b128 v[32:35], v7 offset:256
	ds_read_b128 v[36:39], v7 offset:272
	ds_read_b128 v[40:43], v7 offset:288
	ds_read_b128 v[44:47], v7 offset:304
	s_waitcnt vmcnt(60) lgkmcnt(4)
	v_pk_fma_f32 v[16:17], v[48:49], v[66:67], v[16:17] op_sel:[0,1,0] op_sel_hi:[1,1,1]
	v_pk_fma_f32 v[18:19], v[50:51], v[66:67], v[18:19] op_sel:[0,1,0] op_sel_hi:[1,1,1]
	v_pk_fma_f32 v[20:21], v[52:53], v[66:67], v[20:21] op_sel:[0,1,0] op_sel_hi:[1,1,1]
	v_pk_fma_f32 v[22:23], v[54:55], v[66:67], v[22:23] op_sel:[0,1,0] op_sel_hi:[1,1,1]
	v_pk_fma_f32 v[24:25], v[56:57], v[66:67], v[24:25] op_sel:[0,1,0] op_sel_hi:[1,1,1]
	v_pk_fma_f32 v[26:27], v[58:59], v[66:67], v[26:27] op_sel:[0,1,0] op_sel_hi:[1,1,1]
	v_pk_fma_f32 v[28:29], v[60:61], v[66:67], v[28:29] op_sel:[0,1,0] op_sel_hi:[1,1,1]
	v_pk_fma_f32 v[30:31], v[62:63], v[66:67], v[30:31] op_sel:[0,1,0] op_sel_hi:[1,1,1]
	ds_read_b128 v[48:51], v7 offset:320
	ds_read_b128 v[52:55], v7 offset:336
	ds_read_b128 v[56:59], v7 offset:352
	ds_read_b128 v[60:63], v7 offset:368
	s_waitcnt vmcnt(59) lgkmcnt(4)
	v_pk_fma_f32 v[16:17], v[32:33], v[68:69], v[16:17] op_sel_hi:[1,0,1]
	v_pk_fma_f32 v[18:19], v[34:35], v[68:69], v[18:19] op_sel_hi:[1,0,1]
	v_pk_fma_f32 v[20:21], v[36:37], v[68:69], v[20:21] op_sel_hi:[1,0,1]
	v_pk_fma_f32 v[22:23], v[38:39], v[68:69], v[22:23] op_sel_hi:[1,0,1]
	v_pk_fma_f32 v[24:25], v[40:41], v[68:69], v[24:25] op_sel_hi:[1,0,1]
	v_pk_fma_f32 v[26:27], v[42:43], v[68:69], v[26:27] op_sel_hi:[1,0,1]
	v_pk_fma_f32 v[28:29], v[44:45], v[68:69], v[28:29] op_sel_hi:[1,0,1]
	v_pk_fma_f32 v[30:31], v[46:47], v[68:69], v[30:31] op_sel_hi:[1,0,1]
	ds_read_b128 v[32:35], v7 offset:384
	ds_read_b128 v[36:39], v7 offset:400
	ds_read_b128 v[40:43], v7 offset:416
	ds_read_b128 v[44:47], v7 offset:432
	s_waitcnt vmcnt(58) lgkmcnt(4)
	v_pk_fma_f32 v[16:17], v[48:49], v[68:69], v[16:17] op_sel:[0,1,0] op_sel_hi:[1,1,1]
	v_pk_fma_f32 v[18:19], v[50:51], v[68:69], v[18:19] op_sel:[0,1,0] op_sel_hi:[1,1,1]
	v_pk_fma_f32 v[20:21], v[52:53], v[68:69], v[20:21] op_sel:[0,1,0] op_sel_hi:[1,1,1]
	v_pk_fma_f32 v[22:23], v[54:55], v[68:69], v[22:23] op_sel:[0,1,0] op_sel_hi:[1,1,1]
	v_pk_fma_f32 v[24:25], v[56:57], v[68:69], v[24:25] op_sel:[0,1,0] op_sel_hi:[1,1,1]
	v_pk_fma_f32 v[26:27], v[58:59], v[68:69], v[26:27] op_sel:[0,1,0] op_sel_hi:[1,1,1]
	v_pk_fma_f32 v[28:29], v[60:61], v[68:69], v[28:29] op_sel:[0,1,0] op_sel_hi:[1,1,1]
	v_pk_fma_f32 v[30:31], v[62:63], v[68:69], v[30:31] op_sel:[0,1,0] op_sel_hi:[1,1,1]
	ds_read_b128 v[48:51], v7 offset:448
	ds_read_b128 v[52:55], v7 offset:464
	ds_read_b128 v[56:59], v7 offset:480
	ds_read_b128 v[60:63], v7 offset:496
	s_waitcnt vmcnt(57) lgkmcnt(4)
	v_pk_fma_f32 v[16:17], v[32:33], v[70:71], v[16:17] op_sel_hi:[1,0,1]
	v_pk_fma_f32 v[18:19], v[34:35], v[70:71], v[18:19] op_sel_hi:[1,0,1]
	v_pk_fma_f32 v[20:21], v[36:37], v[70:71], v[20:21] op_sel_hi:[1,0,1]
	v_pk_fma_f32 v[22:23], v[38:39], v[70:71], v[22:23] op_sel_hi:[1,0,1]
	v_pk_fma_f32 v[24:25], v[40:41], v[70:71], v[24:25] op_sel_hi:[1,0,1]
	v_pk_fma_f32 v[26:27], v[42:43], v[70:71], v[26:27] op_sel_hi:[1,0,1]
	v_pk_fma_f32 v[28:29], v[44:45], v[70:71], v[28:29] op_sel_hi:[1,0,1]
	v_pk_fma_f32 v[30:31], v[46:47], v[70:71], v[30:31] op_sel_hi:[1,0,1]
	ds_read_b128 v[32:35], v7 offset:512
	ds_read_b128 v[36:39], v7 offset:528
	ds_read_b128 v[40:43], v7 offset:544
	ds_read_b128 v[44:47], v7 offset:560
	s_waitcnt vmcnt(56) lgkmcnt(4)
	v_pk_fma_f32 v[16:17], v[48:49], v[70:71], v[16:17] op_sel:[0,1,0] op_sel_hi:[1,1,1]
	v_pk_fma_f32 v[18:19], v[50:51], v[70:71], v[18:19] op_sel:[0,1,0] op_sel_hi:[1,1,1]
	v_pk_fma_f32 v[20:21], v[52:53], v[70:71], v[20:21] op_sel:[0,1,0] op_sel_hi:[1,1,1]
	v_pk_fma_f32 v[22:23], v[54:55], v[70:71], v[22:23] op_sel:[0,1,0] op_sel_hi:[1,1,1]
	v_pk_fma_f32 v[24:25], v[56:57], v[70:71], v[24:25] op_sel:[0,1,0] op_sel_hi:[1,1,1]
	v_pk_fma_f32 v[26:27], v[58:59], v[70:71], v[26:27] op_sel:[0,1,0] op_sel_hi:[1,1,1]
	v_pk_fma_f32 v[28:29], v[60:61], v[70:71], v[28:29] op_sel:[0,1,0] op_sel_hi:[1,1,1]
	v_pk_fma_f32 v[30:31], v[62:63], v[70:71], v[30:31] op_sel:[0,1,0] op_sel_hi:[1,1,1]
	ds_read_b128 v[48:51], v7 offset:576
	ds_read_b128 v[52:55], v7 offset:592
	ds_read_b128 v[56:59], v7 offset:608
	ds_read_b128 v[60:63], v7 offset:624
	s_waitcnt vmcnt(55) lgkmcnt(4)
	v_pk_fma_f32 v[16:17], v[32:33], v[72:73], v[16:17] op_sel_hi:[1,0,1]
	v_pk_fma_f32 v[18:19], v[34:35], v[72:73], v[18:19] op_sel_hi:[1,0,1]
	v_pk_fma_f32 v[20:21], v[36:37], v[72:73], v[20:21] op_sel_hi:[1,0,1]
	v_pk_fma_f32 v[22:23], v[38:39], v[72:73], v[22:23] op_sel_hi:[1,0,1]
	v_pk_fma_f32 v[24:25], v[40:41], v[72:73], v[24:25] op_sel_hi:[1,0,1]
	v_pk_fma_f32 v[26:27], v[42:43], v[72:73], v[26:27] op_sel_hi:[1,0,1]
	v_pk_fma_f32 v[28:29], v[44:45], v[72:73], v[28:29] op_sel_hi:[1,0,1]
	v_pk_fma_f32 v[30:31], v[46:47], v[72:73], v[30:31] op_sel_hi:[1,0,1]
	ds_read_b128 v[32:35], v7 offset:640
	ds_read_b128 v[36:39], v7 offset:656
	ds_read_b128 v[40:43], v7 offset:672
	ds_read_b128 v[44:47], v7 offset:688
	s_waitcnt vmcnt(54) lgkmcnt(4)
; #define LAS __attribute__((address_space(3)))
; __device__ __forceinline__ void ph_mod(const float* cp, const float* cs, const float* w_ada, const float* b_ada, float* MOD, float* MISC,
;                                        const float* lq1, const float* lk1, const float* lq2, const float* lk2, LAS unsigned char* lds, int G, int tid) {
;     ...
; #pragma unroll 16
;         for (int kk = 0; kk < 128; ++kk) { const int k = k0 + kk; const float wv = w_ada[(size_t)k * 9216 + col];
;             const f32x4 s0 = *(const LAS f32x4*)(scT + k * 16), s1 = *(const LAS f32x4*)(scT + k * 16 + 4), s2 = *(const LAS f32x4*)(scT + k * 16 + 8), s3 = *(const LAS f32x4*)(scT + k * 16 + 12);
;             acc[0] += s0[0] * wv; acc[1] += s0[1] * wv; acc[2] += s0[2] * wv; acc[3] += s0[3] * wv; acc[4] += s1[0] * wv; acc[5] += s1[1] * wv; acc[6] += s1[2] * wv; acc[7] += s1[3] * wv;
;             acc[8] += s2[0] * wv; acc[9] += s2[1] * wv; acc[10] += s2[2] * wv; acc[11] += s2[3] * wv; acc[12] += s3[0] * wv; acc[13] += s3[1] * wv; acc[14] += s3[2] * wv; acc[15] += s3[3] * wv; }
	v_pk_fma_f32 v[16:17], v[48:49], v[72:73], v[16:17] op_sel:[0,1,0] op_sel_hi:[1,1,1]
	v_pk_fma_f32 v[18:19], v[50:51], v[72:73], v[18:19] op_sel:[0,1,0] op_sel_hi:[1,1,1]
	v_pk_fma_f32 v[20:21], v[52:53], v[72:73], v[20:21] op_sel:[0,1,0] op_sel_hi:[1,1,1]
	v_pk_fma_f32 v[22:23], v[54:55], v[72:73], v[22:23] op_sel:[0,1,0] op_sel_hi:[1,1,1]
	v_pk_fma_f32 v[24:25], v[56:57], v[72:73], v[24:25] op_sel:[0,1,0] op_sel_hi:[1,1,1]
	v_pk_fma_f32 v[26:27], v[58:59], v[72:73], v[26:27] op_sel:[0,1,0] op_sel_hi:[1,1,1]
	v_pk_fma_f32 v[28:29], v[60:61], v[72:73], v[28:29] op_sel:[0,1,0] op_sel_hi:[1,1,1]
	v_pk_fma_f32 v[30:31], v[62:63], v[72:73], v[30:31] op_sel:[0,1,0] op_sel_hi:[1,1,1]
	ds_read_b128 v[48:51], v7 offset:704
	ds_read_b128 v[52:55], v7 offset:720
	ds_read_b128 v[56:59], v7 offset:736
	ds_read_b128 v[60:63], v7 offset:752
	s_waitcnt vmcnt(53) lgkmcnt(4)
	v_pk_fma_f32 v[16:17], v[32:33], v[74:75], v[16:17] op_sel_hi:[1,0,1]
	v_pk_fma_f32 v[18:19], v[34:35], v[74:75], v[18:19] op_sel_hi:[1,0,1]
	v_pk_fma_f32 v[20:21], v[36:37], v[74:75], v[20:21] op_sel_hi:[1,0,1]
	v_pk_fma_f32 v[22:23], v[38:39], v[74:75], v[22:23] op_sel_hi:[1,0,1]
	v_pk_fma_f32 v[24:25], v[40:41], v[74:75], v[24:25] op_sel_hi:[1,0,1]
	v_pk_fma_f32 v[26:27], v[42:43], v[74:75], v[26:27] op_sel_hi:[1,0,1]
	v_pk_fma_f32 v[28:29], v[44:45], v[74:75], v[28:29] op_sel_hi:[1,0,1]
	v_pk_fma_f32 v[30:31], v[46:47], v[74:75], v[30:31] op_sel_hi:[1,0,1]
	ds_read_b128 v[32:35], v7 offset:768
	ds_read_b128 v[36:39], v7 offset:784
	ds_read_b128 v[40:43], v7 offset:800
	ds_read_b128 v[44:47], v7 offset:816
	s_waitcnt vmcnt(52) lgkmcnt(4)
	v_pk_fma_f32 v[16:17], v[48:49], v[74:75], v[16:17] op_sel:[0,1,0] op_sel_hi:[1,1,1]
	v_pk_fma_f32 v[18:19], v[50:51], v[74:75], v[18:19] op_sel:[0,1,0] op_sel_hi:[1,1,1]
	v_pk_fma_f32 v[20:21], v[52:53], v[74:75], v[20:21] op_sel:[0,1,0] op_sel_hi:[1,1,1]
	v_pk_fma_f32 v[22:23], v[54:55], v[74:75], v[22:23] op_sel:[0,1,0] op_sel_hi:[1,1,1]
	v_pk_fma_f32 v[24:25], v[56:57], v[74:75], v[24:25] op_sel:[0,1,0] op_sel_hi:[1,1,1]
	v_pk_fma_f32 v[26:27], v[58:59], v[74:75], v[26:27] op_sel:[0,1,0] op_sel_hi:[1,1,1]
	v_pk_fma_f32 v[28:29], v[60:61], v[74:75], v[28:29] op_sel:[0,1,0] op_sel_hi:[1,1,1]
	v_pk_fma_f32 v[30:31], v[62:63], v[74:75], v[30:31] op_sel:[0,1,0] op_sel_hi:[1,1,1]
	ds_read_b128 v[48:51], v7 offset:832
	ds_read_b128 v[52:55], v7 offset:848
	ds_read_b128 v[56:59], v7 offset:864
	ds_read_b128 v[60:63], v7 offset:880
	s_waitcnt vmcnt(51) lgkmcnt(4)
	v_pk_fma_f32 v[16:17], v[32:33], v[76:77], v[16:17] op_sel_hi:[1,0,1]
	v_pk_fma_f32 v[18:19], v[34:35], v[76:77], v[18:19] op_sel_hi:[1,0,1]
	v_pk_fma_f32 v[20:21], v[36:37], v[76:77], v[20:21] op_sel_hi:[1,0,1]
	v_pk_fma_f32 v[22:23], v[38:39], v[76:77], v[22:23] op_sel_hi:[1,0,1]
	v_pk_fma_f32 v[24:25], v[40:41], v[76:77], v[24:25] op_sel_hi:[1,0,1]
	v_pk_fma_f32 v[26:27], v[42:43], v[76:77], v[26:27] op_sel_hi:[1,0,1]
	v_pk_fma_f32 v[28:29], v[44:45], v[76:77], v[28:29] op_sel_hi:[1,0,1]
	v_pk_fma_f32 v[30:31], v[46:47], v[76:77], v[30:31] op_sel_hi:[1,0,1]
	ds_read_b128 v[32:35], v7 offset:896
	ds_read_b128 v[36:39], v7 offset:912
	ds_read_b128 v[40:43], v7 offset:928
	ds_read_b128 v[44:47], v7 offset:944
	s_waitcnt vmcnt(50) lgkmcnt(4)
	v_pk_fma_f32 v[16:17], v[48:49], v[76:77], v[16:17] op_sel:[0,1,0] op_sel_hi:[1,1,1]
	v_pk_fma_f32 v[18:19], v[50:51], v[76:77], v[18:19] op_sel:[0,1,0] op_sel_hi:[1,1,1]
	v_pk_fma_f32 v[20:21], v[52:53], v[76:77], v[20:21] op_sel:[0,1,0] op_sel_hi:[1,1,1]
	v_pk_fma_f32 v[22:23], v[54:55], v[76:77], v[22:23] op_sel:[0,1,0] op_sel_hi:[1,1,1]
	v_pk_fma_f32 v[24:25], v[56:57], v[76:77], v[24:25] op_sel:[0,1,0] op_sel_hi:[1,1,1]
	v_pk_fma_f32 v[26:27], v[58:59], v[76:77], v[26:27] op_sel:[0,1,0] op_sel_hi:[1,1,1]
	v_pk_fma_f32 v[28:29], v[60:61], v[76:77], v[28:29] op_sel:[0,1,0] op_sel_hi:[1,1,1]
	v_pk_fma_f32 v[30:31], v[62:63], v[76:77], v[30:31] op_sel:[0,1,0] op_sel_hi:[1,1,1]
	ds_read_b128 v[48:51], v7 offset:960
	ds_read_b128 v[52:55], v7 offset:976
	ds_read_b128 v[56:59], v7 offset:992
	ds_read_b128 v[60:63], v7 offset:1008
	s_waitcnt vmcnt(49) lgkmcnt(4)
	v_pk_fma_f32 v[16:17], v[32:33], v[78:79], v[16:17] op_sel_hi:[1,0,1]
	v_pk_fma_f32 v[18:19], v[34:35], v[78:79], v[18:19] op_sel_hi:[1,0,1]
	v_pk_fma_f32 v[20:21], v[36:37], v[78:79], v[20:21] op_sel_hi:[1,0,1]
	v_pk_fma_f32 v[22:23], v[38:39], v[78:79], v[22:23] op_sel_hi:[1,0,1]
	v_pk_fma_f32 v[24:25], v[40:41], v[78:79], v[24:25] op_sel_hi:[1,0,1]
	v_pk_fma_f32 v[26:27], v[42:43], v[78:79], v[26:27] op_sel_hi:[1,0,1]
	v_pk_fma_f32 v[28:29], v[44:45], v[78:79], v[28:29] op_sel_hi:[1,0,1]
	v_pk_fma_f32 v[30:31], v[46:47], v[78:79], v[30:31] op_sel_hi:[1,0,1]
	ds_read_b128 v[32:35], v7 offset:1024
	ds_read_b128 v[36:39], v7 offset:1040
	ds_read_b128 v[40:43], v7 offset:1056
	ds_read_b128 v[44:47], v7 offset:1072
	s_waitcnt vmcnt(48) lgkmcnt(4)
	v_pk_fma_f32 v[16:17], v[48:49], v[78:79], v[16:17] op_sel:[0,1,0] op_sel_hi:[1,1,1]
	v_pk_fma_f32 v[18:19], v[50:51], v[78:79], v[18:19] op_sel:[0,1,0] op_sel_hi:[1,1,1]
	v_pk_fma_f32 v[20:21], v[52:53], v[78:79], v[20:21] op_sel:[0,1,0] op_sel_hi:[1,1,1]
	v_pk_fma_f32 v[22:23], v[54:55], v[78:79], v[22:23] op_sel:[0,1,0] op_sel_hi:[1,1,1]
	v_pk_fma_f32 v[24:25], v[56:57], v[78:79], v[24:25] op_sel:[0,1,0] op_sel_hi:[1,1,1]
	v_pk_fma_f32 v[26:27], v[58:59], v[78:79], v[26:27] op_sel:[0,1,0] op_sel_hi:[1,1,1]
	v_pk_fma_f32 v[28:29], v[60:61], v[78:79], v[28:29] op_sel:[0,1,0] op_sel_hi:[1,1,1]
	v_pk_fma_f32 v[30:31], v[62:63], v[78:79], v[30:31] op_sel:[0,1,0] op_sel_hi:[1,1,1]
	ds_read_b128 v[48:51], v7 offset:1088
	ds_read_b128 v[52:55], v7 offset:1104
	ds_read_b128 v[56:59], v7 offset:1120
	ds_read_b128 v[60:63], v7 offset:1136
	s_waitcnt vmcnt(47) lgkmcnt(4)
; #define LAS __attribute__((address_space(3)))
; __device__ __forceinline__ void ph_mod(const float* cp, const float* cs, const float* w_ada, const float* b_ada, float* MOD, float* MISC,
;                                        const float* lq1, const float* lk1, const float* lq2, const float* lk2, LAS unsigned char* lds, int G, int tid) {
;     ...
; #pragma unroll 16
;         for (int kk = 0; kk < 128; ++kk) { const int k = k0 + kk; const float wv = w_ada[(size_t)k * 9216 + col];
;             const f32x4 s0 = *(const LAS f32x4*)(scT + k * 16), s1 = *(const LAS f32x4*)(scT + k * 16 + 4), s2 = *(const LAS f32x4*)(scT + k * 16 + 8), s3 = *(const LAS f32x4*)(scT + k * 16 + 12);
;             acc[0] += s0[0] * wv; acc[1] += s0[1] * wv; acc[2] += s0[2] * wv; acc[3] += s0[3] * wv; acc[4] += s1[0] * wv; acc[5] += s1[1] * wv; acc[6] += s1[2] * wv; acc[7] += s1[3] * wv;
;             acc[8] += s2[0] * wv; acc[9] += s2[1] * wv; acc[10] += s2[2] * wv; acc[11] += s2[3] * wv; acc[12] += s3[0] * wv; acc[13] += s3[1] * wv; acc[14] += s3[2] * wv; acc[15] += s3[3] * wv; }
	v_pk_fma_f32 v[16:17], v[32:33], v[80:81], v[16:17] op_sel_hi:[1,0,1]
	v_pk_fma_f32 v[18:19], v[34:35], v[80:81], v[18:19] op_sel_hi:[1,0,1]
	v_pk_fma_f32 v[20:21], v[36:37], v[80:81], v[20:21] op_sel_hi:[1,0,1]
	v_pk_fma_f32 v[22:23], v[38:39], v[80:81], v[22:23] op_sel_hi:[1,0,1]
	v_pk_fma_f32 v[24:25], v[40:41], v[80:81], v[24:25] op_sel_hi:[1,0,1]
	v_pk_fma_f32 v[26:27], v[42:43], v[80:81], v[26:27] op_sel_hi:[1,0,1]
	v_pk_fma_f32 v[28:29], v[44:45], v[80:81], v[28:29] op_sel_hi:[1,0,1]
	v_pk_fma_f32 v[30:31], v[46:47], v[80:81], v[30:31] op_sel_hi:[1,0,1]
	ds_read_b128 v[32:35], v7 offset:1152
	ds_read_b128 v[36:39], v7 offset:1168
	ds_read_b128 v[40:43], v7 offset:1184
	ds_read_b128 v[44:47], v7 offset:1200
	s_waitcnt vmcnt(46) lgkmcnt(4)
	v_pk_fma_f32 v[16:17], v[48:49], v[80:81], v[16:17] op_sel:[0,1,0] op_sel_hi:[1,1,1]
	v_pk_fma_f32 v[18:19], v[50:51], v[80:81], v[18:19] op_sel:[0,1,0] op_sel_hi:[1,1,1]
	v_pk_fma_f32 v[20:21], v[52:53], v[80:81], v[20:21] op_sel:[0,1,0] op_sel_hi:[1,1,1]
	v_pk_fma_f32 v[22:23], v[54:55], v[80:81], v[22:23] op_sel:[0,1,0] op_sel_hi:[1,1,1]
	v_pk_fma_f32 v[24:25], v[56:57], v[80:81], v[24:25] op_sel:[0,1,0] op_sel_hi:[1,1,1]
	v_pk_fma_f32 v[26:27], v[58:59], v[80:81], v[26:27] op_sel:[0,1,0] op_sel_hi:[1,1,1]
	v_pk_fma_f32 v[28:29], v[60:61], v[80:81], v[28:29] op_sel:[0,1,0] op_sel_hi:[1,1,1]
	v_pk_fma_f32 v[30:31], v[62:63], v[80:81], v[30:31] op_sel:[0,1,0] op_sel_hi:[1,1,1]
	ds_read_b128 v[48:51], v7 offset:1216
	ds_read_b128 v[52:55], v7 offset:1232
	ds_read_b128 v[56:59], v7 offset:1248
	ds_read_b128 v[60:63], v7 offset:1264
	s_waitcnt vmcnt(45) lgkmcnt(4)
	v_pk_fma_f32 v[16:17], v[32:33], v[82:83], v[16:17] op_sel_hi:[1,0,1]
	v_pk_fma_f32 v[18:19], v[34:35], v[82:83], v[18:19] op_sel_hi:[1,0,1]
	v_pk_fma_f32 v[20:21], v[36:37], v[82:83], v[20:21] op_sel_hi:[1,0,1]
	v_pk_fma_f32 v[22:23], v[38:39], v[82:83], v[22:23] op_sel_hi:[1,0,1]
	v_pk_fma_f32 v[24:25], v[40:41], v[82:83], v[24:25] op_sel_hi:[1,0,1]
	v_pk_fma_f32 v[26:27], v[42:43], v[82:83], v[26:27] op_sel_hi:[1,0,1]
	v_pk_fma_f32 v[28:29], v[44:45], v[82:83], v[28:29] op_sel_hi:[1,0,1]
	v_pk_fma_f32 v[30:31], v[46:47], v[82:83], v[30:31] op_sel_hi:[1,0,1]
	ds_read_b128 v[32:35], v7 offset:1280
	ds_read_b128 v[36:39], v7 offset:1296
	ds_read_b128 v[40:43], v7 offset:1312
	ds_read_b128 v[44:47], v7 offset:1328
	s_waitcnt vmcnt(44) lgkmcnt(4)
	v_pk_fma_f32 v[16:17], v[48:49], v[82:83], v[16:17] op_sel:[0,1,0] op_sel_hi:[1,1,1]
	v_pk_fma_f32 v[18:19], v[50:51], v[82:83], v[18:19] op_sel:[0,1,0] op_sel_hi:[1,1,1]
	v_pk_fma_f32 v[20:21], v[52:53], v[82:83], v[20:21] op_sel:[0,1,0] op_sel_hi:[1,1,1]
	v_pk_fma_f32 v[22:23], v[54:55], v[82:83], v[22:23] op_sel:[0,1,0] op_sel_hi:[1,1,1]
	v_pk_fma_f32 v[24:25], v[56:57], v[82:83], v[24:25] op_sel:[0,1,0] op_sel_hi:[1,1,1]
	v_pk_fma_f32 v[26:27], v[58:59], v[82:83], v[26:27] op_sel:[0,1,0] op_sel_hi:[1,1,1]
	v_pk_fma_f32 v[28:29], v[60:61], v[82:83], v[28:29] op_sel:[0,1,0] op_sel_hi:[1,1,1]
	v_pk_fma_f32 v[30:31], v[62:63], v[82:83], v[30:31] op_sel:[0,1,0] op_sel_hi:[1,1,1]
	ds_read_b128 v[48:51], v7 offset:1344
	ds_read_b128 v[52:55], v7 offset:1360
	ds_read_b128 v[56:59], v7 offset:1376
	ds_read_b128 v[60:63], v7 offset:1392
	s_waitcnt vmcnt(43) lgkmcnt(4)
	v_pk_fma_f32 v[16:17], v[32:33], v[84:85], v[16:17] op_sel_hi:[1,0,1]
	v_pk_fma_f32 v[18:19], v[34:35], v[84:85], v[18:19] op_sel_hi:[1,0,1]
	v_pk_fma_f32 v[20:21], v[36:37], v[84:85], v[20:21] op_sel_hi:[1,0,1]
	v_pk_fma_f32 v[22:23], v[38:39], v[84:85], v[22:23] op_sel_hi:[1,0,1]
	v_pk_fma_f32 v[24:25], v[40:41], v[84:85], v[24:25] op_sel_hi:[1,0,1]
	v_pk_fma_f32 v[26:27], v[42:43], v[84:85], v[26:27] op_sel_hi:[1,0,1]
	v_pk_fma_f32 v[28:29], v[44:45], v[84:85], v[28:29] op_sel_hi:[1,0,1]
	v_pk_fma_f32 v[30:31], v[46:47], v[84:85], v[30:31] op_sel_hi:[1,0,1]
	ds_read_b128 v[32:35], v7 offset:1408
	ds_read_b128 v[36:39], v7 offset:1424
	ds_read_b128 v[40:43], v7 offset:1440
	ds_read_b128 v[44:47], v7 offset:1456
	s_waitcnt vmcnt(42) lgkmcnt(4)
	v_pk_fma_f32 v[16:17], v[48:49], v[84:85], v[16:17] op_sel:[0,1,0] op_sel_hi:[1,1,1]
	v_pk_fma_f32 v[18:19], v[50:51], v[84:85], v[18:19] op_sel:[0,1,0] op_sel_hi:[1,1,1]
	v_pk_fma_f32 v[20:21], v[52:53], v[84:85], v[20:21] op_sel:[0,1,0] op_sel_hi:[1,1,1]
	v_pk_fma_f32 v[22:23], v[54:55], v[84:85], v[22:23] op_sel:[0,1,0] op_sel_hi:[1,1,1]
	v_pk_fma_f32 v[24:25], v[56:57], v[84:85], v[24:25] op_sel:[0,1,0] op_sel_hi:[1,1,1]
	v_pk_fma_f32 v[26:27], v[58:59], v[84:85], v[26:27] op_sel:[0,1,0] op_sel_hi:[1,1,1]
	v_pk_fma_f32 v[28:29], v[60:61], v[84:85], v[28:29] op_sel:[0,1,0] op_sel_hi:[1,1,1]
	v_pk_fma_f32 v[30:31], v[62:63], v[84:85], v[30:31] op_sel:[0,1,0] op_sel_hi:[1,1,1]
	ds_read_b128 v[48:51], v7 offset:1472
	ds_read_b128 v[52:55], v7 offset:1488
	ds_read_b128 v[56:59], v7 offset:1504
	ds_read_b128 v[60:63], v7 offset:1520
	s_waitcnt vmcnt(41) lgkmcnt(4)
	v_pk_fma_f32 v[16:17], v[32:33], v[86:87], v[16:17] op_sel_hi:[1,0,1]
	v_pk_fma_f32 v[18:19], v[34:35], v[86:87], v[18:19] op_sel_hi:[1,0,1]
	v_pk_fma_f32 v[20:21], v[36:37], v[86:87], v[20:21] op_sel_hi:[1,0,1]
	v_pk_fma_f32 v[22:23], v[38:39], v[86:87], v[22:23] op_sel_hi:[1,0,1]
	v_pk_fma_f32 v[24:25], v[40:41], v[86:87], v[24:25] op_sel_hi:[1,0,1]
	v_pk_fma_f32 v[26:27], v[42:43], v[86:87], v[26:27] op_sel_hi:[1,0,1]
	v_pk_fma_f32 v[28:29], v[44:45], v[86:87], v[28:29] op_sel_hi:[1,0,1]
	v_pk_fma_f32 v[30:31], v[46:47], v[86:87], v[30:31] op_sel_hi:[1,0,1]
	ds_read_b128 v[32:35], v7 offset:1536
	ds_read_b128 v[36:39], v7 offset:1552
	ds_read_b128 v[40:43], v7 offset:1568
	ds_read_b128 v[44:47], v7 offset:1584
	s_waitcnt vmcnt(40) lgkmcnt(4)
; #define LAS __attribute__((address_space(3)))
; __device__ __forceinline__ void ph_mod(const float* cp, const float* cs, const float* w_ada, const float* b_ada, float* MOD, float* MISC,
;                                        const float* lq1, const float* lk1, const float* lq2, const float* lk2, LAS unsigned char* lds, int G, int tid) {
;     ...
; #pragma unroll 16
;         for (int kk = 0; kk < 128; ++kk) { const int k = k0 + kk; const float wv = w_ada[(size_t)k * 9216 + col];
;             const f32x4 s0 = *(const LAS f32x4*)(scT + k * 16), s1 = *(const LAS f32x4*)(scT + k * 16 + 4), s2 = *(const LAS f32x4*)(scT + k * 16 + 8), s3 = *(const LAS f32x4*)(scT + k * 16 + 12);
;             acc[0] += s0[0] * wv; acc[1] += s0[1] * wv; acc[2] += s0[2] * wv; acc[3] += s0[3] * wv; acc[4] += s1[0] * wv; acc[5] += s1[1] * wv; acc[6] += s1[2] * wv; acc[7] += s1[3] * wv;
;             acc[8] += s2[0] * wv; acc[9] += s2[1] * wv; acc[10] += s2[2] * wv; acc[11] += s2[3] * wv; acc[12] += s3[0] * wv; acc[13] += s3[1] * wv; acc[14] += s3[2] * wv; acc[15] += s3[3] * wv; }
	v_pk_fma_f32 v[16:17], v[48:49], v[86:87], v[16:17] op_sel:[0,1,0] op_sel_hi:[1,1,1]
	v_pk_fma_f32 v[18:19], v[50:51], v[86:87], v[18:19] op_sel:[0,1,0] op_sel_hi:[1,1,1]
	v_pk_fma_f32 v[20:21], v[52:53], v[86:87], v[20:21] op_sel:[0,1,0] op_sel_hi:[1,1,1]
	v_pk_fma_f32 v[22:23], v[54:55], v[86:87], v[22:23] op_sel:[0,1,0] op_sel_hi:[1,1,1]
	v_pk_fma_f32 v[24:25], v[56:57], v[86:87], v[24:25] op_sel:[0,1,0] op_sel_hi:[1,1,1]
	v_pk_fma_f32 v[26:27], v[58:59], v[86:87], v[26:27] op_sel:[0,1,0] op_sel_hi:[1,1,1]
	v_pk_fma_f32 v[28:29], v[60:61], v[86:87], v[28:29] op_sel:[0,1,0] op_sel_hi:[1,1,1]
	v_pk_fma_f32 v[30:31], v[62:63], v[86:87], v[30:31] op_sel:[0,1,0] op_sel_hi:[1,1,1]
	ds_read_b128 v[48:51], v7 offset:1600
	ds_read_b128 v[52:55], v7 offset:1616
	ds_read_b128 v[56:59], v7 offset:1632
	ds_read_b128 v[60:63], v7 offset:1648
	s_waitcnt vmcnt(39) lgkmcnt(4)
	v_pk_fma_f32 v[16:17], v[32:33], v[88:89], v[16:17] op_sel_hi:[1,0,1]
	v_pk_fma_f32 v[18:19], v[34:35], v[88:89], v[18:19] op_sel_hi:[1,0,1]
	v_pk_fma_f32 v[20:21], v[36:37], v[88:89], v[20:21] op_sel_hi:[1,0,1]
	v_pk_fma_f32 v[22:23], v[38:39], v[88:89], v[22:23] op_sel_hi:[1,0,1]
	v_pk_fma_f32 v[24:25], v[40:41], v[88:89], v[24:25] op_sel_hi:[1,0,1]
	v_pk_fma_f32 v[26:27], v[42:43], v[88:89], v[26:27] op_sel_hi:[1,0,1]
	v_pk_fma_f32 v[28:29], v[44:45], v[88:89], v[28:29] op_sel_hi:[1,0,1]
	v_pk_fma_f32 v[30:31], v[46:47], v[88:89], v[30:31] op_sel_hi:[1,0,1]
	ds_read_b128 v[32:35], v7 offset:1664
	ds_read_b128 v[36:39], v7 offset:1680
	ds_read_b128 v[40:43], v7 offset:1696
	ds_read_b128 v[44:47], v7 offset:1712
	s_waitcnt vmcnt(38) lgkmcnt(4)
	v_pk_fma_f32 v[16:17], v[48:49], v[88:89], v[16:17] op_sel:[0,1,0] op_sel_hi:[1,1,1]
	v_pk_fma_f32 v[18:19], v[50:51], v[88:89], v[18:19] op_sel:[0,1,0] op_sel_hi:[1,1,1]
	v_pk_fma_f32 v[20:21], v[52:53], v[88:89], v[20:21] op_sel:[0,1,0] op_sel_hi:[1,1,1]
	v_pk_fma_f32 v[22:23], v[54:55], v[88:89], v[22:23] op_sel:[0,1,0] op_sel_hi:[1,1,1]
	v_pk_fma_f32 v[24:25], v[56:57], v[88:89], v[24:25] op_sel:[0,1,0] op_sel_hi:[1,1,1]
	v_pk_fma_f32 v[26:27], v[58:59], v[88:89], v[26:27] op_sel:[0,1,0] op_sel_hi:[1,1,1]
	v_pk_fma_f32 v[28:29], v[60:61], v[88:89], v[28:29] op_sel:[0,1,0] op_sel_hi:[1,1,1]
	v_pk_fma_f32 v[30:31], v[62:63], v[88:89], v[30:31] op_sel:[0,1,0] op_sel_hi:[1,1,1]
	ds_read_b128 v[48:51], v7 offset:1728
	ds_read_b128 v[52:55], v7 offset:1744
	ds_read_b128 v[56:59], v7 offset:1760
	ds_read_b128 v[60:63], v7 offset:1776
	s_waitcnt vmcnt(37) lgkmcnt(4)
	v_pk_fma_f32 v[16:17], v[32:33], v[90:91], v[16:17] op_sel_hi:[1,0,1]
	v_pk_fma_f32 v[18:19], v[34:35], v[90:91], v[18:19] op_sel_hi:[1,0,1]
	v_pk_fma_f32 v[20:21], v[36:37], v[90:91], v[20:21] op_sel_hi:[1,0,1]
	v_pk_fma_f32 v[22:23], v[38:39], v[90:91], v[22:23] op_sel_hi:[1,0,1]
	v_pk_fma_f32 v[24:25], v[40:41], v[90:91], v[24:25] op_sel_hi:[1,0,1]
	v_pk_fma_f32 v[26:27], v[42:43], v[90:91], v[26:27] op_sel_hi:[1,0,1]
	v_pk_fma_f32 v[28:29], v[44:45], v[90:91], v[28:29] op_sel_hi:[1,0,1]
	v_pk_fma_f32 v[30:31], v[46:47], v[90:91], v[30:31] op_sel_hi:[1,0,1]
	ds_read_b128 v[32:35], v7 offset:1792
	ds_read_b128 v[36:39], v7 offset:1808
	ds_read_b128 v[40:43], v7 offset:1824
	ds_read_b128 v[44:47], v7 offset:1840
	s_waitcnt vmcnt(36) lgkmcnt(4)
	v_pk_fma_f32 v[16:17], v[48:49], v[90:91], v[16:17] op_sel:[0,1,0] op_sel_hi:[1,1,1]
	v_pk_fma_f32 v[18:19], v[50:51], v[90:91], v[18:19] op_sel:[0,1,0] op_sel_hi:[1,1,1]
	v_pk_fma_f32 v[20:21], v[52:53], v[90:91], v[20:21] op_sel:[0,1,0] op_sel_hi:[1,1,1]
	v_pk_fma_f32 v[22:23], v[54:55], v[90:91], v[22:23] op_sel:[0,1,0] op_sel_hi:[1,1,1]
	v_pk_fma_f32 v[24:25], v[56:57], v[90:91], v[24:25] op_sel:[0,1,0] op_sel_hi:[1,1,1]
	v_pk_fma_f32 v[26:27], v[58:59], v[90:91], v[26:27] op_sel:[0,1,0] op_sel_hi:[1,1,1]
	v_pk_fma_f32 v[28:29], v[60:61], v[90:91], v[28:29] op_sel:[0,1,0] op_sel_hi:[1,1,1]
	v_pk_fma_f32 v[30:31], v[62:63], v[90:91], v[30:31] op_sel:[0,1,0] op_sel_hi:[1,1,1]
	ds_read_b128 v[48:51], v7 offset:1856
	ds_read_b128 v[52:55], v7 offset:1872
	ds_read_b128 v[56:59], v7 offset:1888
	ds_read_b128 v[60:63], v7 offset:1904
	s_waitcnt vmcnt(35) lgkmcnt(4)
	v_pk_fma_f32 v[16:17], v[32:33], v[92:93], v[16:17] op_sel_hi:[1,0,1]
	v_pk_fma_f32 v[18:19], v[34:35], v[92:93], v[18:19] op_sel_hi:[1,0,1]
	v_pk_fma_f32 v[20:21], v[36:37], v[92:93], v[20:21] op_sel_hi:[1,0,1]
	v_pk_fma_f32 v[22:23], v[38:39], v[92:93], v[22:23] op_sel_hi:[1,0,1]
	v_pk_fma_f32 v[24:25], v[40:41], v[92:93], v[24:25] op_sel_hi:[1,0,1]
	v_pk_fma_f32 v[26:27], v[42:43], v[92:93], v[26:27] op_sel_hi:[1,0,1]
	v_pk_fma_f32 v[28:29], v[44:45], v[92:93], v[28:29] op_sel_hi:[1,0,1]
	v_pk_fma_f32 v[30:31], v[46:47], v[92:93], v[30:31] op_sel_hi:[1,0,1]
	ds_read_b128 v[32:35], v7 offset:1920
	ds_read_b128 v[36:39], v7 offset:1936
	ds_read_b128 v[40:43], v7 offset:1952
	ds_read_b128 v[44:47], v7 offset:1968
	s_waitcnt vmcnt(34) lgkmcnt(4)
	v_pk_fma_f32 v[16:17], v[48:49], v[92:93], v[16:17] op_sel:[0,1,0] op_sel_hi:[1,1,1]
	v_pk_fma_f32 v[18:19], v[50:51], v[92:93], v[18:19] op_sel:[0,1,0] op_sel_hi:[1,1,1]
	v_pk_fma_f32 v[20:21], v[52:53], v[92:93], v[20:21] op_sel:[0,1,0] op_sel_hi:[1,1,1]
	v_pk_fma_f32 v[22:23], v[54:55], v[92:93], v[22:23] op_sel:[0,1,0] op_sel_hi:[1,1,1]
	v_pk_fma_f32 v[24:25], v[56:57], v[92:93], v[24:25] op_sel:[0,1,0] op_sel_hi:[1,1,1]
	v_pk_fma_f32 v[26:27], v[58:59], v[92:93], v[26:27] op_sel:[0,1,0] op_sel_hi:[1,1,1]
	v_pk_fma_f32 v[28:29], v[60:61], v[92:93], v[28:29] op_sel:[0,1,0] op_sel_hi:[1,1,1]
	v_pk_fma_f32 v[30:31], v[62:63], v[92:93], v[30:31] op_sel:[0,1,0] op_sel_hi:[1,1,1]
	ds_read_b128 v[48:51], v7 offset:1984
	ds_read_b128 v[52:55], v7 offset:2000
	ds_read_b128 v[56:59], v7 offset:2016
	ds_read_b128 v[60:63], v7 offset:2032
	s_waitcnt vmcnt(33) lgkmcnt(4)
; #define LAS __attribute__((address_space(3)))
; __device__ __forceinline__ void ph_mod(const float* cp, const float* cs, const float* w_ada, const float* b_ada, float* MOD, float* MISC,
;                                        const float* lq1, const float* lk1, const float* lq2, const float* lk2, LAS unsigned char* lds, int G, int tid) {
;     ...
; #pragma unroll 16
;         for (int kk = 0; kk < 128; ++kk) { const int k = k0 + kk; const float wv = w_ada[(size_t)k * 9216 + col];
;             const f32x4 s0 = *(const LAS f32x4*)(scT + k * 16), s1 = *(const LAS f32x4*)(scT + k * 16 + 4), s2 = *(const LAS f32x4*)(scT + k * 16 + 8), s3 = *(const LAS f32x4*)(scT + k * 16 + 12);
;             acc[0] += s0[0] * wv; acc[1] += s0[1] * wv; acc[2] += s0[2] * wv; acc[3] += s0[3] * wv; acc[4] += s1[0] * wv; acc[5] += s1[1] * wv; acc[6] += s1[2] * wv; acc[7] += s1[3] * wv;
;             acc[8] += s2[0] * wv; acc[9] += s2[1] * wv; acc[10] += s2[2] * wv; acc[11] += s2[3] * wv; acc[12] += s3[0] * wv; acc[13] += s3[1] * wv; acc[14] += s3[2] * wv; acc[15] += s3[3] * wv; }
	v_pk_fma_f32 v[16:17], v[32:33], v[94:95], v[16:17] op_sel_hi:[1,0,1]
	v_pk_fma_f32 v[18:19], v[34:35], v[94:95], v[18:19] op_sel_hi:[1,0,1]
	v_pk_fma_f32 v[20:21], v[36:37], v[94:95], v[20:21] op_sel_hi:[1,0,1]
	v_pk_fma_f32 v[22:23], v[38:39], v[94:95], v[22:23] op_sel_hi:[1,0,1]
	v_pk_fma_f32 v[24:25], v[40:41], v[94:95], v[24:25] op_sel_hi:[1,0,1]
	v_pk_fma_f32 v[26:27], v[42:43], v[94:95], v[26:27] op_sel_hi:[1,0,1]
	v_pk_fma_f32 v[28:29], v[44:45], v[94:95], v[28:29] op_sel_hi:[1,0,1]
	v_pk_fma_f32 v[30:31], v[46:47], v[94:95], v[30:31] op_sel_hi:[1,0,1]
	ds_read_b128 v[32:35], v7 offset:2048
	ds_read_b128 v[36:39], v7 offset:2064
	ds_read_b128 v[40:43], v7 offset:2080
	ds_read_b128 v[44:47], v7 offset:2096
	s_waitcnt vmcnt(32) lgkmcnt(4)
	v_pk_fma_f32 v[16:17], v[48:49], v[94:95], v[16:17] op_sel:[0,1,0] op_sel_hi:[1,1,1]
	v_pk_fma_f32 v[18:19], v[50:51], v[94:95], v[18:19] op_sel:[0,1,0] op_sel_hi:[1,1,1]
	v_pk_fma_f32 v[20:21], v[52:53], v[94:95], v[20:21] op_sel:[0,1,0] op_sel_hi:[1,1,1]
	v_pk_fma_f32 v[22:23], v[54:55], v[94:95], v[22:23] op_sel:[0,1,0] op_sel_hi:[1,1,1]
	v_pk_fma_f32 v[24:25], v[56:57], v[94:95], v[24:25] op_sel:[0,1,0] op_sel_hi:[1,1,1]
	v_pk_fma_f32 v[26:27], v[58:59], v[94:95], v[26:27] op_sel:[0,1,0] op_sel_hi:[1,1,1]
	v_pk_fma_f32 v[28:29], v[60:61], v[94:95], v[28:29] op_sel:[0,1,0] op_sel_hi:[1,1,1]
	v_pk_fma_f32 v[30:31], v[62:63], v[94:95], v[30:31] op_sel:[0,1,0] op_sel_hi:[1,1,1]
	ds_read_b128 v[48:51], v7 offset:2112
	ds_read_b128 v[52:55], v7 offset:2128
	ds_read_b128 v[56:59], v7 offset:2144
	ds_read_b128 v[60:63], v7 offset:2160
	s_waitcnt vmcnt(31) lgkmcnt(4)
	v_pk_fma_f32 v[16:17], v[32:33], v[96:97], v[16:17] op_sel_hi:[1,0,1]
	v_pk_fma_f32 v[18:19], v[34:35], v[96:97], v[18:19] op_sel_hi:[1,0,1]
	v_pk_fma_f32 v[20:21], v[36:37], v[96:97], v[20:21] op_sel_hi:[1,0,1]
	v_pk_fma_f32 v[22:23], v[38:39], v[96:97], v[22:23] op_sel_hi:[1,0,1]
	v_pk_fma_f32 v[24:25], v[40:41], v[96:97], v[24:25] op_sel_hi:[1,0,1]
	v_pk_fma_f32 v[26:27], v[42:43], v[96:97], v[26:27] op_sel_hi:[1,0,1]
	v_pk_fma_f32 v[28:29], v[44:45], v[96:97], v[28:29] op_sel_hi:[1,0,1]
	v_pk_fma_f32 v[30:31], v[46:47], v[96:97], v[30:31] op_sel_hi:[1,0,1]
	ds_read_b128 v[32:35], v7 offset:2176
	ds_read_b128 v[36:39], v7 offset:2192
	ds_read_b128 v[40:43], v7 offset:2208
	ds_read_b128 v[44:47], v7 offset:2224
	s_waitcnt vmcnt(30) lgkmcnt(4)
	v_pk_fma_f32 v[16:17], v[48:49], v[96:97], v[16:17] op_sel:[0,1,0] op_sel_hi:[1,1,1]
	v_pk_fma_f32 v[18:19], v[50:51], v[96:97], v[18:19] op_sel:[0,1,0] op_sel_hi:[1,1,1]
	v_pk_fma_f32 v[20:21], v[52:53], v[96:97], v[20:21] op_sel:[0,1,0] op_sel_hi:[1,1,1]
	v_pk_fma_f32 v[22:23], v[54:55], v[96:97], v[22:23] op_sel:[0,1,0] op_sel_hi:[1,1,1]
	v_pk_fma_f32 v[24:25], v[56:57], v[96:97], v[24:25] op_sel:[0,1,0] op_sel_hi:[1,1,1]
	v_pk_fma_f32 v[26:27], v[58:59], v[96:97], v[26:27] op_sel:[0,1,0] op_sel_hi:[1,1,1]
	v_pk_fma_f32 v[28:29], v[60:61], v[96:97], v[28:29] op_sel:[0,1,0] op_sel_hi:[1,1,1]
	v_pk_fma_f32 v[30:31], v[62:63], v[96:97], v[30:31] op_sel:[0,1,0] op_sel_hi:[1,1,1]
	ds_read_b128 v[48:51], v7 offset:2240
	ds_read_b128 v[52:55], v7 offset:2256
	ds_read_b128 v[56:59], v7 offset:2272
	ds_read_b128 v[60:63], v7 offset:2288
	s_waitcnt vmcnt(29) lgkmcnt(4)
	v_pk_fma_f32 v[16:17], v[32:33], v[98:99], v[16:17] op_sel_hi:[1,0,1]
	v_pk_fma_f32 v[18:19], v[34:35], v[98:99], v[18:19] op_sel_hi:[1,0,1]
	v_pk_fma_f32 v[20:21], v[36:37], v[98:99], v[20:21] op_sel_hi:[1,0,1]
	v_pk_fma_f32 v[22:23], v[38:39], v[98:99], v[22:23] op_sel_hi:[1,0,1]
	v_pk_fma_f32 v[24:25], v[40:41], v[98:99], v[24:25] op_sel_hi:[1,0,1]
	v_pk_fma_f32 v[26:27], v[42:43], v[98:99], v[26:27] op_sel_hi:[1,0,1]
	v_pk_fma_f32 v[28:29], v[44:45], v[98:99], v[28:29] op_sel_hi:[1,0,1]
	v_pk_fma_f32 v[30:31], v[46:47], v[98:99], v[30:31] op_sel_hi:[1,0,1]
	ds_read_b128 v[32:35], v7 offset:2304
	ds_read_b128 v[36:39], v7 offset:2320
	ds_read_b128 v[40:43], v7 offset:2336
	ds_read_b128 v[44:47], v7 offset:2352
	s_waitcnt vmcnt(28) lgkmcnt(4)
	v_pk_fma_f32 v[16:17], v[48:49], v[98:99], v[16:17] op_sel:[0,1,0] op_sel_hi:[1,1,1]
	v_pk_fma_f32 v[18:19], v[50:51], v[98:99], v[18:19] op_sel:[0,1,0] op_sel_hi:[1,1,1]
	v_pk_fma_f32 v[20:21], v[52:53], v[98:99], v[20:21] op_sel:[0,1,0] op_sel_hi:[1,1,1]
	v_pk_fma_f32 v[22:23], v[54:55], v[98:99], v[22:23] op_sel:[0,1,0] op_sel_hi:[1,1,1]
	v_pk_fma_f32 v[24:25], v[56:57], v[98:99], v[24:25] op_sel:[0,1,0] op_sel_hi:[1,1,1]
	v_pk_fma_f32 v[26:27], v[58:59], v[98:99], v[26:27] op_sel:[0,1,0] op_sel_hi:[1,1,1]
	v_pk_fma_f32 v[28:29], v[60:61], v[98:99], v[28:29] op_sel:[0,1,0] op_sel_hi:[1,1,1]
	v_pk_fma_f32 v[30:31], v[62:63], v[98:99], v[30:31] op_sel:[0,1,0] op_sel_hi:[1,1,1]
	ds_read_b128 v[48:51], v7 offset:2368
	ds_read_b128 v[52:55], v7 offset:2384
	ds_read_b128 v[56:59], v7 offset:2400
	ds_read_b128 v[60:63], v7 offset:2416
	s_waitcnt vmcnt(27) lgkmcnt(4)
	v_pk_fma_f32 v[16:17], v[32:33], v[100:101], v[16:17] op_sel_hi:[1,0,1]
	v_pk_fma_f32 v[18:19], v[34:35], v[100:101], v[18:19] op_sel_hi:[1,0,1]
	v_pk_fma_f32 v[20:21], v[36:37], v[100:101], v[20:21] op_sel_hi:[1,0,1]
	v_pk_fma_f32 v[22:23], v[38:39], v[100:101], v[22:23] op_sel_hi:[1,0,1]
	v_pk_fma_f32 v[24:25], v[40:41], v[100:101], v[24:25] op_sel_hi:[1,0,1]
	v_pk_fma_f32 v[26:27], v[42:43], v[100:101], v[26:27] op_sel_hi:[1,0,1]
	v_pk_fma_f32 v[28:29], v[44:45], v[100:101], v[28:29] op_sel_hi:[1,0,1]
	v_pk_fma_f32 v[30:31], v[46:47], v[100:101], v[30:31] op_sel_hi:[1,0,1]
	ds_read_b128 v[32:35], v7 offset:2432
	ds_read_b128 v[36:39], v7 offset:2448
	ds_read_b128 v[40:43], v7 offset:2464
	ds_read_b128 v[44:47], v7 offset:2480
	s_waitcnt vmcnt(26) lgkmcnt(4)
; #define LAS __attribute__((address_space(3)))
; __device__ __forceinline__ void ph_mod(const float* cp, const float* cs, const float* w_ada, const float* b_ada, float* MOD, float* MISC,
;                                        const float* lq1, const float* lk1, const float* lq2, const float* lk2, LAS unsigned char* lds, int G, int tid) {
;     ...
; #pragma unroll 16
;         for (int kk = 0; kk < 128; ++kk) { const int k = k0 + kk; const float wv = w_ada[(size_t)k * 9216 + col];
;             const f32x4 s0 = *(const LAS f32x4*)(scT + k * 16), s1 = *(const LAS f32x4*)(scT + k * 16 + 4), s2 = *(const LAS f32x4*)(scT + k * 16 + 8), s3 = *(const LAS f32x4*)(scT + k * 16 + 12);
;             acc[0] += s0[0] * wv; acc[1] += s0[1] * wv; acc[2] += s0[2] * wv; acc[3] += s0[3] * wv; acc[4] += s1[0] * wv; acc[5] += s1[1] * wv; acc[6] += s1[2] * wv; acc[7] += s1[3] * wv;
;             acc[8] += s2[0] * wv; acc[9] += s2[1] * wv; acc[10] += s2[2] * wv; acc[11] += s2[3] * wv; acc[12] += s3[0] * wv; acc[13] += s3[1] * wv; acc[14] += s3[2] * wv; acc[15] += s3[3] * wv; }
	v_pk_fma_f32 v[16:17], v[48:49], v[100:101], v[16:17] op_sel:[0,1,0] op_sel_hi:[1,1,1]
	v_pk_fma_f32 v[18:19], v[50:51], v[100:101], v[18:19] op_sel:[0,1,0] op_sel_hi:[1,1,1]
	v_pk_fma_f32 v[20:21], v[52:53], v[100:101], v[20:21] op_sel:[0,1,0] op_sel_hi:[1,1,1]
	v_pk_fma_f32 v[22:23], v[54:55], v[100:101], v[22:23] op_sel:[0,1,0] op_sel_hi:[1,1,1]
	v_pk_fma_f32 v[24:25], v[56:57], v[100:101], v[24:25] op_sel:[0,1,0] op_sel_hi:[1,1,1]
	v_pk_fma_f32 v[26:27], v[58:59], v[100:101], v[26:27] op_sel:[0,1,0] op_sel_hi:[1,1,1]
	v_pk_fma_f32 v[28:29], v[60:61], v[100:101], v[28:29] op_sel:[0,1,0] op_sel_hi:[1,1,1]
	v_pk_fma_f32 v[30:31], v[62:63], v[100:101], v[30:31] op_sel:[0,1,0] op_sel_hi:[1,1,1]
	ds_read_b128 v[48:51], v7 offset:2496
	ds_read_b128 v[52:55], v7 offset:2512
	ds_read_b128 v[56:59], v7 offset:2528
	ds_read_b128 v[60:63], v7 offset:2544
	s_waitcnt vmcnt(25) lgkmcnt(4)
	v_pk_fma_f32 v[16:17], v[32:33], v[102:103], v[16:17] op_sel_hi:[1,0,1]
	v_pk_fma_f32 v[18:19], v[34:35], v[102:103], v[18:19] op_sel_hi:[1,0,1]
	v_pk_fma_f32 v[20:21], v[36:37], v[102:103], v[20:21] op_sel_hi:[1,0,1]
	v_pk_fma_f32 v[22:23], v[38:39], v[102:103], v[22:23] op_sel_hi:[1,0,1]
	v_pk_fma_f32 v[24:25], v[40:41], v[102:103], v[24:25] op_sel_hi:[1,0,1]
	v_pk_fma_f32 v[26:27], v[42:43], v[102:103], v[26:27] op_sel_hi:[1,0,1]
	v_pk_fma_f32 v[28:29], v[44:45], v[102:103], v[28:29] op_sel_hi:[1,0,1]
	v_pk_fma_f32 v[30:31], v[46:47], v[102:103], v[30:31] op_sel_hi:[1,0,1]
	ds_read_b128 v[32:35], v7 offset:2560
	ds_read_b128 v[36:39], v7 offset:2576
	ds_read_b128 v[40:43], v7 offset:2592
	ds_read_b128 v[44:47], v7 offset:2608
	s_waitcnt vmcnt(24) lgkmcnt(4)
	v_pk_fma_f32 v[16:17], v[48:49], v[102:103], v[16:17] op_sel:[0,1,0] op_sel_hi:[1,1,1]
	v_pk_fma_f32 v[18:19], v[50:51], v[102:103], v[18:19] op_sel:[0,1,0] op_sel_hi:[1,1,1]
	v_pk_fma_f32 v[20:21], v[52:53], v[102:103], v[20:21] op_sel:[0,1,0] op_sel_hi:[1,1,1]
	v_pk_fma_f32 v[22:23], v[54:55], v[102:103], v[22:23] op_sel:[0,1,0] op_sel_hi:[1,1,1]
	v_pk_fma_f32 v[24:25], v[56:57], v[102:103], v[24:25] op_sel:[0,1,0] op_sel_hi:[1,1,1]
	v_pk_fma_f32 v[26:27], v[58:59], v[102:103], v[26:27] op_sel:[0,1,0] op_sel_hi:[1,1,1]
	v_pk_fma_f32 v[28:29], v[60:61], v[102:103], v[28:29] op_sel:[0,1,0] op_sel_hi:[1,1,1]
	v_pk_fma_f32 v[30:31], v[62:63], v[102:103], v[30:31] op_sel:[0,1,0] op_sel_hi:[1,1,1]
	ds_read_b128 v[48:51], v7 offset:2624
	ds_read_b128 v[52:55], v7 offset:2640
	ds_read_b128 v[56:59], v7 offset:2656
	ds_read_b128 v[60:63], v7 offset:2672
	s_waitcnt vmcnt(23) lgkmcnt(4)
	v_pk_fma_f32 v[16:17], v[32:33], v[104:105], v[16:17] op_sel_hi:[1,0,1]
	v_pk_fma_f32 v[18:19], v[34:35], v[104:105], v[18:19] op_sel_hi:[1,0,1]
	v_pk_fma_f32 v[20:21], v[36:37], v[104:105], v[20:21] op_sel_hi:[1,0,1]
	v_pk_fma_f32 v[22:23], v[38:39], v[104:105], v[22:23] op_sel_hi:[1,0,1]
	v_pk_fma_f32 v[24:25], v[40:41], v[104:105], v[24:25] op_sel_hi:[1,0,1]
	v_pk_fma_f32 v[26:27], v[42:43], v[104:105], v[26:27] op_sel_hi:[1,0,1]
	v_pk_fma_f32 v[28:29], v[44:45], v[104:105], v[28:29] op_sel_hi:[1,0,1]
	v_pk_fma_f32 v[30:31], v[46:47], v[104:105], v[30:31] op_sel_hi:[1,0,1]
	ds_read_b128 v[32:35], v7 offset:2688
	ds_read_b128 v[36:39], v7 offset:2704
	ds_read_b128 v[40:43], v7 offset:2720
	ds_read_b128 v[44:47], v7 offset:2736
	s_waitcnt vmcnt(22) lgkmcnt(4)
	v_pk_fma_f32 v[16:17], v[48:49], v[104:105], v[16:17] op_sel:[0,1,0] op_sel_hi:[1,1,1]
	v_pk_fma_f32 v[18:19], v[50:51], v[104:105], v[18:19] op_sel:[0,1,0] op_sel_hi:[1,1,1]
	v_pk_fma_f32 v[20:21], v[52:53], v[104:105], v[20:21] op_sel:[0,1,0] op_sel_hi:[1,1,1]
	v_pk_fma_f32 v[22:23], v[54:55], v[104:105], v[22:23] op_sel:[0,1,0] op_sel_hi:[1,1,1]
	v_pk_fma_f32 v[24:25], v[56:57], v[104:105], v[24:25] op_sel:[0,1,0] op_sel_hi:[1,1,1]
	v_pk_fma_f32 v[26:27], v[58:59], v[104:105], v[26:27] op_sel:[0,1,0] op_sel_hi:[1,1,1]
	v_pk_fma_f32 v[28:29], v[60:61], v[104:105], v[28:29] op_sel:[0,1,0] op_sel_hi:[1,1,1]
	v_pk_fma_f32 v[30:31], v[62:63], v[104:105], v[30:31] op_sel:[0,1,0] op_sel_hi:[1,1,1]
	ds_read_b128 v[48:51], v7 offset:2752
	ds_read_b128 v[52:55], v7 offset:2768
	ds_read_b128 v[56:59], v7 offset:2784
	ds_read_b128 v[60:63], v7 offset:2800
	s_waitcnt vmcnt(21) lgkmcnt(4)
	v_pk_fma_f32 v[16:17], v[32:33], v[106:107], v[16:17] op_sel_hi:[1,0,1]
	v_pk_fma_f32 v[18:19], v[34:35], v[106:107], v[18:19] op_sel_hi:[1,0,1]
	v_pk_fma_f32 v[20:21], v[36:37], v[106:107], v[20:21] op_sel_hi:[1,0,1]
	v_pk_fma_f32 v[22:23], v[38:39], v[106:107], v[22:23] op_sel_hi:[1,0,1]
	v_pk_fma_f32 v[24:25], v[40:41], v[106:107], v[24:25] op_sel_hi:[1,0,1]
	v_pk_fma_f32 v[26:27], v[42:43], v[106:107], v[26:27] op_sel_hi:[1,0,1]
	v_pk_fma_f32 v[28:29], v[44:45], v[106:107], v[28:29] op_sel_hi:[1,0,1]
	v_pk_fma_f32 v[30:31], v[46:47], v[106:107], v[30:31] op_sel_hi:[1,0,1]
	ds_read_b128 v[32:35], v7 offset:2816
	ds_read_b128 v[36:39], v7 offset:2832
	ds_read_b128 v[40:43], v7 offset:2848
	ds_read_b128 v[44:47], v7 offset:2864
	s_waitcnt vmcnt(20) lgkmcnt(4)
	v_pk_fma_f32 v[16:17], v[48:49], v[106:107], v[16:17] op_sel:[0,1,0] op_sel_hi:[1,1,1]
	v_pk_fma_f32 v[18:19], v[50:51], v[106:107], v[18:19] op_sel:[0,1,0] op_sel_hi:[1,1,1]
	v_pk_fma_f32 v[20:21], v[52:53], v[106:107], v[20:21] op_sel:[0,1,0] op_sel_hi:[1,1,1]
	v_pk_fma_f32 v[22:23], v[54:55], v[106:107], v[22:23] op_sel:[0,1,0] op_sel_hi:[1,1,1]
	v_pk_fma_f32 v[24:25], v[56:57], v[106:107], v[24:25] op_sel:[0,1,0] op_sel_hi:[1,1,1]
	v_pk_fma_f32 v[26:27], v[58:59], v[106:107], v[26:27] op_sel:[0,1,0] op_sel_hi:[1,1,1]
	v_pk_fma_f32 v[28:29], v[60:61], v[106:107], v[28:29] op_sel:[0,1,0] op_sel_hi:[1,1,1]
	v_pk_fma_f32 v[30:31], v[62:63], v[106:107], v[30:31] op_sel:[0,1,0] op_sel_hi:[1,1,1]
	ds_read_b128 v[48:51], v7 offset:2880
	ds_read_b128 v[52:55], v7 offset:2896
	ds_read_b128 v[56:59], v7 offset:2912
	ds_read_b128 v[60:63], v7 offset:2928
	s_waitcnt vmcnt(19) lgkmcnt(4)
; #define LAS __attribute__((address_space(3)))
; __device__ __forceinline__ void ph_mod(const float* cp, const float* cs, const float* w_ada, const float* b_ada, float* MOD, float* MISC,
;                                        const float* lq1, const float* lk1, const float* lq2, const float* lk2, LAS unsigned char* lds, int G, int tid) {
;     ...
; #pragma unroll 16
;         for (int kk = 0; kk < 128; ++kk) { const int k = k0 + kk; const float wv = w_ada[(size_t)k * 9216 + col];
;             const f32x4 s0 = *(const LAS f32x4*)(scT + k * 16), s1 = *(const LAS f32x4*)(scT + k * 16 + 4), s2 = *(const LAS f32x4*)(scT + k * 16 + 8), s3 = *(const LAS f32x4*)(scT + k * 16 + 12);
;             acc[0] += s0[0] * wv; acc[1] += s0[1] * wv; acc[2] += s0[2] * wv; acc[3] += s0[3] * wv; acc[4] += s1[0] * wv; acc[5] += s1[1] * wv; acc[6] += s1[2] * wv; acc[7] += s1[3] * wv;
;             acc[8] += s2[0] * wv; acc[9] += s2[1] * wv; acc[10] += s2[2] * wv; acc[11] += s2[3] * wv; acc[12] += s3[0] * wv; acc[13] += s3[1] * wv; acc[14] += s3[2] * wv; acc[15] += s3[3] * wv; }
	v_pk_fma_f32 v[16:17], v[32:33], v[108:109], v[16:17] op_sel_hi:[1,0,1]
	v_pk_fma_f32 v[18:19], v[34:35], v[108:109], v[18:19] op_sel_hi:[1,0,1]
	v_pk_fma_f32 v[20:21], v[36:37], v[108:109], v[20:21] op_sel_hi:[1,0,1]
	v_pk_fma_f32 v[22:23], v[38:39], v[108:109], v[22:23] op_sel_hi:[1,0,1]
	v_pk_fma_f32 v[24:25], v[40:41], v[108:109], v[24:25] op_sel_hi:[1,0,1]
	v_pk_fma_f32 v[26:27], v[42:43], v[108:109], v[26:27] op_sel_hi:[1,0,1]
	v_pk_fma_f32 v[28:29], v[44:45], v[108:109], v[28:29] op_sel_hi:[1,0,1]
	v_pk_fma_f32 v[30:31], v[46:47], v[108:109], v[30:31] op_sel_hi:[1,0,1]
	ds_read_b128 v[32:35], v7 offset:2944
	ds_read_b128 v[36:39], v7 offset:2960
	ds_read_b128 v[40:43], v7 offset:2976
	ds_read_b128 v[44:47], v7 offset:2992
	s_waitcnt vmcnt(18) lgkmcnt(4)
	v_pk_fma_f32 v[16:17], v[48:49], v[108:109], v[16:17] op_sel:[0,1,0] op_sel_hi:[1,1,1]
	v_pk_fma_f32 v[18:19], v[50:51], v[108:109], v[18:19] op_sel:[0,1,0] op_sel_hi:[1,1,1]
	v_pk_fma_f32 v[20:21], v[52:53], v[108:109], v[20:21] op_sel:[0,1,0] op_sel_hi:[1,1,1]
	v_pk_fma_f32 v[22:23], v[54:55], v[108:109], v[22:23] op_sel:[0,1,0] op_sel_hi:[1,1,1]
	v_pk_fma_f32 v[24:25], v[56:57], v[108:109], v[24:25] op_sel:[0,1,0] op_sel_hi:[1,1,1]
	v_pk_fma_f32 v[26:27], v[58:59], v[108:109], v[26:27] op_sel:[0,1,0] op_sel_hi:[1,1,1]
	v_pk_fma_f32 v[28:29], v[60:61], v[108:109], v[28:29] op_sel:[0,1,0] op_sel_hi:[1,1,1]
	v_pk_fma_f32 v[30:31], v[62:63], v[108:109], v[30:31] op_sel:[0,1,0] op_sel_hi:[1,1,1]
	ds_read_b128 v[48:51], v7 offset:3008
	ds_read_b128 v[52:55], v7 offset:3024
	ds_read_b128 v[56:59], v7 offset:3040
	ds_read_b128 v[60:63], v7 offset:3056
	s_waitcnt vmcnt(17) lgkmcnt(4)
	v_pk_fma_f32 v[16:17], v[32:33], v[110:111], v[16:17] op_sel_hi:[1,0,1]
	v_pk_fma_f32 v[18:19], v[34:35], v[110:111], v[18:19] op_sel_hi:[1,0,1]
	v_pk_fma_f32 v[20:21], v[36:37], v[110:111], v[20:21] op_sel_hi:[1,0,1]
	v_pk_fma_f32 v[22:23], v[38:39], v[110:111], v[22:23] op_sel_hi:[1,0,1]
	v_pk_fma_f32 v[24:25], v[40:41], v[110:111], v[24:25] op_sel_hi:[1,0,1]
	v_pk_fma_f32 v[26:27], v[42:43], v[110:111], v[26:27] op_sel_hi:[1,0,1]
	v_pk_fma_f32 v[28:29], v[44:45], v[110:111], v[28:29] op_sel_hi:[1,0,1]
	v_pk_fma_f32 v[30:31], v[46:47], v[110:111], v[30:31] op_sel_hi:[1,0,1]
	ds_read_b128 v[32:35], v7 offset:3072
	ds_read_b128 v[36:39], v7 offset:3088
	ds_read_b128 v[40:43], v7 offset:3104
	ds_read_b128 v[44:47], v7 offset:3120
	s_waitcnt vmcnt(16) lgkmcnt(4)
	v_pk_fma_f32 v[16:17], v[48:49], v[110:111], v[16:17] op_sel:[0,1,0] op_sel_hi:[1,1,1]
	v_pk_fma_f32 v[18:19], v[50:51], v[110:111], v[18:19] op_sel:[0,1,0] op_sel_hi:[1,1,1]
	v_pk_fma_f32 v[20:21], v[52:53], v[110:111], v[20:21] op_sel:[0,1,0] op_sel_hi:[1,1,1]
	v_pk_fma_f32 v[22:23], v[54:55], v[110:111], v[22:23] op_sel:[0,1,0] op_sel_hi:[1,1,1]
	v_pk_fma_f32 v[24:25], v[56:57], v[110:111], v[24:25] op_sel:[0,1,0] op_sel_hi:[1,1,1]
	v_pk_fma_f32 v[26:27], v[58:59], v[110:111], v[26:27] op_sel:[0,1,0] op_sel_hi:[1,1,1]
	v_pk_fma_f32 v[28:29], v[60:61], v[110:111], v[28:29] op_sel:[0,1,0] op_sel_hi:[1,1,1]
	v_pk_fma_f32 v[30:31], v[62:63], v[110:111], v[30:31] op_sel:[0,1,0] op_sel_hi:[1,1,1]
	ds_read_b128 v[48:51], v7 offset:3136
	ds_read_b128 v[52:55], v7 offset:3152
	ds_read_b128 v[56:59], v7 offset:3168
	ds_read_b128 v[60:63], v7 offset:3184
	s_waitcnt vmcnt(15) lgkmcnt(4)
	v_pk_fma_f32 v[16:17], v[32:33], v[112:113], v[16:17] op_sel_hi:[1,0,1]
	v_pk_fma_f32 v[18:19], v[34:35], v[112:113], v[18:19] op_sel_hi:[1,0,1]
	v_pk_fma_f32 v[20:21], v[36:37], v[112:113], v[20:21] op_sel_hi:[1,0,1]
	v_pk_fma_f32 v[22:23], v[38:39], v[112:113], v[22:23] op_sel_hi:[1,0,1]
	v_pk_fma_f32 v[24:25], v[40:41], v[112:113], v[24:25] op_sel_hi:[1,0,1]
	v_pk_fma_f32 v[26:27], v[42:43], v[112:113], v[26:27] op_sel_hi:[1,0,1]
	v_pk_fma_f32 v[28:29], v[44:45], v[112:113], v[28:29] op_sel_hi:[1,0,1]
	v_pk_fma_f32 v[30:31], v[46:47], v[112:113], v[30:31] op_sel_hi:[1,0,1]
	ds_read_b128 v[32:35], v7 offset:3200
	ds_read_b128 v[36:39], v7 offset:3216
	ds_read_b128 v[40:43], v7 offset:3232
	ds_read_b128 v[44:47], v7 offset:3248
	s_waitcnt vmcnt(14) lgkmcnt(4)
	v_pk_fma_f32 v[16:17], v[48:49], v[112:113], v[16:17] op_sel:[0,1,0] op_sel_hi:[1,1,1]
	v_pk_fma_f32 v[18:19], v[50:51], v[112:113], v[18:19] op_sel:[0,1,0] op_sel_hi:[1,1,1]
	v_pk_fma_f32 v[20:21], v[52:53], v[112:113], v[20:21] op_sel:[0,1,0] op_sel_hi:[1,1,1]
	v_pk_fma_f32 v[22:23], v[54:55], v[112:113], v[22:23] op_sel:[0,1,0] op_sel_hi:[1,1,1]
	v_pk_fma_f32 v[24:25], v[56:57], v[112:113], v[24:25] op_sel:[0,1,0] op_sel_hi:[1,1,1]
	v_pk_fma_f32 v[26:27], v[58:59], v[112:113], v[26:27] op_sel:[0,1,0] op_sel_hi:[1,1,1]
	v_pk_fma_f32 v[28:29], v[60:61], v[112:113], v[28:29] op_sel:[0,1,0] op_sel_hi:[1,1,1]
	v_pk_fma_f32 v[30:31], v[62:63], v[112:113], v[30:31] op_sel:[0,1,0] op_sel_hi:[1,1,1]
	ds_read_b128 v[48:51], v7 offset:3264
	ds_read_b128 v[52:55], v7 offset:3280
	ds_read_b128 v[56:59], v7 offset:3296
	ds_read_b128 v[60:63], v7 offset:3312
	s_waitcnt vmcnt(13) lgkmcnt(4)
	v_pk_fma_f32 v[16:17], v[32:33], v[114:115], v[16:17] op_sel_hi:[1,0,1]
	v_pk_fma_f32 v[18:19], v[34:35], v[114:115], v[18:19] op_sel_hi:[1,0,1]
	v_pk_fma_f32 v[20:21], v[36:37], v[114:115], v[20:21] op_sel_hi:[1,0,1]
	v_pk_fma_f32 v[22:23], v[38:39], v[114:115], v[22:23] op_sel_hi:[1,0,1]
	v_pk_fma_f32 v[24:25], v[40:41], v[114:115], v[24:25] op_sel_hi:[1,0,1]
	v_pk_fma_f32 v[26:27], v[42:43], v[114:115], v[26:27] op_sel_hi:[1,0,1]
	v_pk_fma_f32 v[28:29], v[44:45], v[114:115], v[28:29] op_sel_hi:[1,0,1]
	v_pk_fma_f32 v[30:31], v[46:47], v[114:115], v[30:31] op_sel_hi:[1,0,1]
	ds_read_b128 v[32:35], v7 offset:3328
	ds_read_b128 v[36:39], v7 offset:3344
	ds_read_b128 v[40:43], v7 offset:3360
	ds_read_b128 v[44:47], v7 offset:3376
	s_waitcnt vmcnt(12) lgkmcnt(4)
; #define LAS __attribute__((address_space(3)))
; __device__ __forceinline__ void ph_mod(const float* cp, const float* cs, const float* w_ada, const float* b_ada, float* MOD, float* MISC,
;                                        const float* lq1, const float* lk1, const float* lq2, const float* lk2, LAS unsigned char* lds, int G, int tid) {
;     ...
; #pragma unroll 16
;         for (int kk = 0; kk < 128; ++kk) { const int k = k0 + kk; const float wv = w_ada[(size_t)k * 9216 + col];
;             const f32x4 s0 = *(const LAS f32x4*)(scT + k * 16), s1 = *(const LAS f32x4*)(scT + k * 16 + 4), s2 = *(const LAS f32x4*)(scT + k * 16 + 8), s3 = *(const LAS f32x4*)(scT + k * 16 + 12);
;             acc[0] += s0[0] * wv; acc[1] += s0[1] * wv; acc[2] += s0[2] * wv; acc[3] += s0[3] * wv; acc[4] += s1[0] * wv; acc[5] += s1[1] * wv; acc[6] += s1[2] * wv; acc[7] += s1[3] * wv;
;             acc[8] += s2[0] * wv; acc[9] += s2[1] * wv; acc[10] += s2[2] * wv; acc[11] += s2[3] * wv; acc[12] += s3[0] * wv; acc[13] += s3[1] * wv; acc[14] += s3[2] * wv; acc[15] += s3[3] * wv; }
	v_pk_fma_f32 v[16:17], v[48:49], v[114:115], v[16:17] op_sel:[0,1,0] op_sel_hi:[1,1,1]
	v_pk_fma_f32 v[18:19], v[50:51], v[114:115], v[18:19] op_sel:[0,1,0] op_sel_hi:[1,1,1]
	v_pk_fma_f32 v[20:21], v[52:53], v[114:115], v[20:21] op_sel:[0,1,0] op_sel_hi:[1,1,1]
	v_pk_fma_f32 v[22:23], v[54:55], v[114:115], v[22:23] op_sel:[0,1,0] op_sel_hi:[1,1,1]
	v_pk_fma_f32 v[24:25], v[56:57], v[114:115], v[24:25] op_sel:[0,1,0] op_sel_hi:[1,1,1]
	v_pk_fma_f32 v[26:27], v[58:59], v[114:115], v[26:27] op_sel:[0,1,0] op_sel_hi:[1,1,1]
	v_pk_fma_f32 v[28:29], v[60:61], v[114:115], v[28:29] op_sel:[0,1,0] op_sel_hi:[1,1,1]
	v_pk_fma_f32 v[30:31], v[62:63], v[114:115], v[30:31] op_sel:[0,1,0] op_sel_hi:[1,1,1]
	ds_read_b128 v[48:51], v7 offset:3392
	ds_read_b128 v[52:55], v7 offset:3408
	ds_read_b128 v[56:59], v7 offset:3424
	ds_read_b128 v[60:63], v7 offset:3440
	s_waitcnt vmcnt(11) lgkmcnt(4)
	v_pk_fma_f32 v[16:17], v[32:33], v[116:117], v[16:17] op_sel_hi:[1,0,1]
	v_pk_fma_f32 v[18:19], v[34:35], v[116:117], v[18:19] op_sel_hi:[1,0,1]
	v_pk_fma_f32 v[20:21], v[36:37], v[116:117], v[20:21] op_sel_hi:[1,0,1]
	v_pk_fma_f32 v[22:23], v[38:39], v[116:117], v[22:23] op_sel_hi:[1,0,1]
	v_pk_fma_f32 v[24:25], v[40:41], v[116:117], v[24:25] op_sel_hi:[1,0,1]
	v_pk_fma_f32 v[26:27], v[42:43], v[116:117], v[26:27] op_sel_hi:[1,0,1]
	v_pk_fma_f32 v[28:29], v[44:45], v[116:117], v[28:29] op_sel_hi:[1,0,1]
	v_pk_fma_f32 v[30:31], v[46:47], v[116:117], v[30:31] op_sel_hi:[1,0,1]
	ds_read_b128 v[32:35], v7 offset:3456
	ds_read_b128 v[36:39], v7 offset:3472
	ds_read_b128 v[40:43], v7 offset:3488
	ds_read_b128 v[44:47], v7 offset:3504
	s_waitcnt vmcnt(10) lgkmcnt(4)
	v_pk_fma_f32 v[16:17], v[48:49], v[116:117], v[16:17] op_sel:[0,1,0] op_sel_hi:[1,1,1]
	v_pk_fma_f32 v[18:19], v[50:51], v[116:117], v[18:19] op_sel:[0,1,0] op_sel_hi:[1,1,1]
	v_pk_fma_f32 v[20:21], v[52:53], v[116:117], v[20:21] op_sel:[0,1,0] op_sel_hi:[1,1,1]
	v_pk_fma_f32 v[22:23], v[54:55], v[116:117], v[22:23] op_sel:[0,1,0] op_sel_hi:[1,1,1]
	v_pk_fma_f32 v[24:25], v[56:57], v[116:117], v[24:25] op_sel:[0,1,0] op_sel_hi:[1,1,1]
	v_pk_fma_f32 v[26:27], v[58:59], v[116:117], v[26:27] op_sel:[0,1,0] op_sel_hi:[1,1,1]
	v_pk_fma_f32 v[28:29], v[60:61], v[116:117], v[28:29] op_sel:[0,1,0] op_sel_hi:[1,1,1]
	v_pk_fma_f32 v[30:31], v[62:63], v[116:117], v[30:31] op_sel:[0,1,0] op_sel_hi:[1,1,1]
	ds_read_b128 v[48:51], v7 offset:3520
	ds_read_b128 v[52:55], v7 offset:3536
	ds_read_b128 v[56:59], v7 offset:3552
	ds_read_b128 v[60:63], v7 offset:3568
	s_waitcnt vmcnt(9) lgkmcnt(4)
	v_pk_fma_f32 v[16:17], v[32:33], v[118:119], v[16:17] op_sel_hi:[1,0,1]
	v_pk_fma_f32 v[18:19], v[34:35], v[118:119], v[18:19] op_sel_hi:[1,0,1]
	v_pk_fma_f32 v[20:21], v[36:37], v[118:119], v[20:21] op_sel_hi:[1,0,1]
	v_pk_fma_f32 v[22:23], v[38:39], v[118:119], v[22:23] op_sel_hi:[1,0,1]
	v_pk_fma_f32 v[24:25], v[40:41], v[118:119], v[24:25] op_sel_hi:[1,0,1]
	v_pk_fma_f32 v[26:27], v[42:43], v[118:119], v[26:27] op_sel_hi:[1,0,1]
	v_pk_fma_f32 v[28:29], v[44:45], v[118:119], v[28:29] op_sel_hi:[1,0,1]
	v_pk_fma_f32 v[30:31], v[46:47], v[118:119], v[30:31] op_sel_hi:[1,0,1]
	ds_read_b128 v[32:35], v7 offset:3584
	ds_read_b128 v[36:39], v7 offset:3600
	ds_read_b128 v[40:43], v7 offset:3616
	ds_read_b128 v[44:47], v7 offset:3632
	s_waitcnt vmcnt(8) lgkmcnt(4)
	v_pk_fma_f32 v[16:17], v[48:49], v[118:119], v[16:17] op_sel:[0,1,0] op_sel_hi:[1,1,1]
	v_pk_fma_f32 v[18:19], v[50:51], v[118:119], v[18:19] op_sel:[0,1,0] op_sel_hi:[1,1,1]
	v_pk_fma_f32 v[20:21], v[52:53], v[118:119], v[20:21] op_sel:[0,1,0] op_sel_hi:[1,1,1]
	v_pk_fma_f32 v[22:23], v[54:55], v[118:119], v[22:23] op_sel:[0,1,0] op_sel_hi:[1,1,1]
	v_pk_fma_f32 v[24:25], v[56:57], v[118:119], v[24:25] op_sel:[0,1,0] op_sel_hi:[1,1,1]
	v_pk_fma_f32 v[26:27], v[58:59], v[118:119], v[26:27] op_sel:[0,1,0] op_sel_hi:[1,1,1]
	v_pk_fma_f32 v[28:29], v[60:61], v[118:119], v[28:29] op_sel:[0,1,0] op_sel_hi:[1,1,1]
	v_pk_fma_f32 v[30:31], v[62:63], v[118:119], v[30:31] op_sel:[0,1,0] op_sel_hi:[1,1,1]
	ds_read_b128 v[48:51], v7 offset:3648
	ds_read_b128 v[52:55], v7 offset:3664
	ds_read_b128 v[56:59], v7 offset:3680
	ds_read_b128 v[60:63], v7 offset:3696
	s_waitcnt vmcnt(7) lgkmcnt(4)
	v_pk_fma_f32 v[16:17], v[32:33], v[120:121], v[16:17] op_sel_hi:[1,0,1]
	v_pk_fma_f32 v[18:19], v[34:35], v[120:121], v[18:19] op_sel_hi:[1,0,1]
	v_pk_fma_f32 v[20:21], v[36:37], v[120:121], v[20:21] op_sel_hi:[1,0,1]
	v_pk_fma_f32 v[22:23], v[38:39], v[120:121], v[22:23] op_sel_hi:[1,0,1]
	v_pk_fma_f32 v[24:25], v[40:41], v[120:121], v[24:25] op_sel_hi:[1,0,1]
	v_pk_fma_f32 v[26:27], v[42:43], v[120:121], v[26:27] op_sel_hi:[1,0,1]
	v_pk_fma_f32 v[28:29], v[44:45], v[120:121], v[28:29] op_sel_hi:[1,0,1]
	v_pk_fma_f32 v[30:31], v[46:47], v[120:121], v[30:31] op_sel_hi:[1,0,1]
	ds_read_b128 v[32:35], v7 offset:3712
	ds_read_b128 v[36:39], v7 offset:3728
	ds_read_b128 v[40:43], v7 offset:3744
	ds_read_b128 v[44:47], v7 offset:3760
	s_waitcnt vmcnt(6) lgkmcnt(4)
	v_pk_fma_f32 v[16:17], v[48:49], v[120:121], v[16:17] op_sel:[0,1,0] op_sel_hi:[1,1,1]
	v_pk_fma_f32 v[18:19], v[50:51], v[120:121], v[18:19] op_sel:[0,1,0] op_sel_hi:[1,1,1]
	v_pk_fma_f32 v[20:21], v[52:53], v[120:121], v[20:21] op_sel:[0,1,0] op_sel_hi:[1,1,1]
	v_pk_fma_f32 v[22:23], v[54:55], v[120:121], v[22:23] op_sel:[0,1,0] op_sel_hi:[1,1,1]
	v_pk_fma_f32 v[24:25], v[56:57], v[120:121], v[24:25] op_sel:[0,1,0] op_sel_hi:[1,1,1]
	v_pk_fma_f32 v[26:27], v[58:59], v[120:121], v[26:27] op_sel:[0,1,0] op_sel_hi:[1,1,1]
	v_pk_fma_f32 v[28:29], v[60:61], v[120:121], v[28:29] op_sel:[0,1,0] op_sel_hi:[1,1,1]
	v_pk_fma_f32 v[30:31], v[62:63], v[120:121], v[30:31] op_sel:[0,1,0] op_sel_hi:[1,1,1]
	ds_read_b128 v[48:51], v7 offset:3776
	ds_read_b128 v[52:55], v7 offset:3792
	ds_read_b128 v[56:59], v7 offset:3808
	ds_read_b128 v[60:63], v7 offset:3824
	s_waitcnt vmcnt(5) lgkmcnt(4)
; #define LAS __attribute__((address_space(3)))
; __device__ __forceinline__ void ph_mod(const float* cp, const float* cs, const float* w_ada, const float* b_ada, float* MOD, float* MISC,
;                                        const float* lq1, const float* lk1, const float* lq2, const float* lk2, LAS unsigned char* lds, int G, int tid) {
;     ...
; #pragma unroll 16
;         for (int kk = 0; kk < 128; ++kk) { const int k = k0 + kk; const float wv = w_ada[(size_t)k * 9216 + col];
;             const f32x4 s0 = *(const LAS f32x4*)(scT + k * 16), s1 = *(const LAS f32x4*)(scT + k * 16 + 4), s2 = *(const LAS f32x4*)(scT + k * 16 + 8), s3 = *(const LAS f32x4*)(scT + k * 16 + 12);
;             acc[0] += s0[0] * wv; acc[1] += s0[1] * wv; acc[2] += s0[2] * wv; acc[3] += s0[3] * wv; acc[4] += s1[0] * wv; acc[5] += s1[1] * wv; acc[6] += s1[2] * wv; acc[7] += s1[3] * wv;
;             acc[8] += s2[0] * wv; acc[9] += s2[1] * wv; acc[10] += s2[2] * wv; acc[11] += s2[3] * wv; acc[12] += s3[0] * wv; acc[13] += s3[1] * wv; acc[14] += s3[2] * wv; acc[15] += s3[3] * wv; }
	v_pk_fma_f32 v[16:17], v[32:33], v[122:123], v[16:17] op_sel_hi:[1,0,1]
	v_pk_fma_f32 v[18:19], v[34:35], v[122:123], v[18:19] op_sel_hi:[1,0,1]
	v_pk_fma_f32 v[20:21], v[36:37], v[122:123], v[20:21] op_sel_hi:[1,0,1]
	v_pk_fma_f32 v[22:23], v[38:39], v[122:123], v[22:23] op_sel_hi:[1,0,1]
	v_pk_fma_f32 v[24:25], v[40:41], v[122:123], v[24:25] op_sel_hi:[1,0,1]
	v_pk_fma_f32 v[26:27], v[42:43], v[122:123], v[26:27] op_sel_hi:[1,0,1]
	v_pk_fma_f32 v[28:29], v[44:45], v[122:123], v[28:29] op_sel_hi:[1,0,1]
	v_pk_fma_f32 v[30:31], v[46:47], v[122:123], v[30:31] op_sel_hi:[1,0,1]
	ds_read_b128 v[32:35], v7 offset:3840
	ds_read_b128 v[36:39], v7 offset:3856
	ds_read_b128 v[40:43], v7 offset:3872
	ds_read_b128 v[44:47], v7 offset:3888
	s_waitcnt vmcnt(4) lgkmcnt(4)
	v_pk_fma_f32 v[16:17], v[48:49], v[122:123], v[16:17] op_sel:[0,1,0] op_sel_hi:[1,1,1]
	v_pk_fma_f32 v[18:19], v[50:51], v[122:123], v[18:19] op_sel:[0,1,0] op_sel_hi:[1,1,1]
	v_pk_fma_f32 v[20:21], v[52:53], v[122:123], v[20:21] op_sel:[0,1,0] op_sel_hi:[1,1,1]
	v_pk_fma_f32 v[22:23], v[54:55], v[122:123], v[22:23] op_sel:[0,1,0] op_sel_hi:[1,1,1]
	v_pk_fma_f32 v[24:25], v[56:57], v[122:123], v[24:25] op_sel:[0,1,0] op_sel_hi:[1,1,1]
	v_pk_fma_f32 v[26:27], v[58:59], v[122:123], v[26:27] op_sel:[0,1,0] op_sel_hi:[1,1,1]
	v_pk_fma_f32 v[28:29], v[60:61], v[122:123], v[28:29] op_sel:[0,1,0] op_sel_hi:[1,1,1]
	v_pk_fma_f32 v[30:31], v[62:63], v[122:123], v[30:31] op_sel:[0,1,0] op_sel_hi:[1,1,1]
	ds_read_b128 v[48:51], v7 offset:3904
	ds_read_b128 v[52:55], v7 offset:3920
	ds_read_b128 v[56:59], v7 offset:3936
	ds_read_b128 v[60:63], v7 offset:3952
	s_waitcnt vmcnt(3) lgkmcnt(4)
	v_pk_fma_f32 v[16:17], v[32:33], v[124:125], v[16:17] op_sel_hi:[1,0,1]
	v_pk_fma_f32 v[18:19], v[34:35], v[124:125], v[18:19] op_sel_hi:[1,0,1]
	v_pk_fma_f32 v[20:21], v[36:37], v[124:125], v[20:21] op_sel_hi:[1,0,1]
	v_pk_fma_f32 v[22:23], v[38:39], v[124:125], v[22:23] op_sel_hi:[1,0,1]
	v_pk_fma_f32 v[24:25], v[40:41], v[124:125], v[24:25] op_sel_hi:[1,0,1]
	v_pk_fma_f32 v[26:27], v[42:43], v[124:125], v[26:27] op_sel_hi:[1,0,1]
	v_pk_fma_f32 v[28:29], v[44:45], v[124:125], v[28:29] op_sel_hi:[1,0,1]
	v_pk_fma_f32 v[30:31], v[46:47], v[124:125], v[30:31] op_sel_hi:[1,0,1]
	ds_read_b128 v[32:35], v7 offset:3968
	ds_read_b128 v[36:39], v7 offset:3984
	ds_read_b128 v[40:43], v7 offset:4000
	ds_read_b128 v[44:47], v7 offset:4016
	s_waitcnt vmcnt(2) lgkmcnt(4)
	v_pk_fma_f32 v[16:17], v[48:49], v[124:125], v[16:17] op_sel:[0,1,0] op_sel_hi:[1,1,1]
	v_pk_fma_f32 v[18:19], v[50:51], v[124:125], v[18:19] op_sel:[0,1,0] op_sel_hi:[1,1,1]
	v_pk_fma_f32 v[20:21], v[52:53], v[124:125], v[20:21] op_sel:[0,1,0] op_sel_hi:[1,1,1]
	v_pk_fma_f32 v[22:23], v[54:55], v[124:125], v[22:23] op_sel:[0,1,0] op_sel_hi:[1,1,1]
	v_pk_fma_f32 v[24:25], v[56:57], v[124:125], v[24:25] op_sel:[0,1,0] op_sel_hi:[1,1,1]
	v_pk_fma_f32 v[26:27], v[58:59], v[124:125], v[26:27] op_sel:[0,1,0] op_sel_hi:[1,1,1]
	v_pk_fma_f32 v[28:29], v[60:61], v[124:125], v[28:29] op_sel:[0,1,0] op_sel_hi:[1,1,1]
	v_pk_fma_f32 v[30:31], v[62:63], v[124:125], v[30:31] op_sel:[0,1,0] op_sel_hi:[1,1,1]
	ds_read_b128 v[48:51], v7 offset:4032
	ds_read_b128 v[52:55], v7 offset:4048
	ds_read_b128 v[56:59], v7 offset:4064
	ds_read_b128 v[60:63], v7 offset:4080
	s_waitcnt vmcnt(1) lgkmcnt(4)
	v_pk_fma_f32 v[16:17], v[32:33], v[126:127], v[16:17] op_sel_hi:[1,0,1]
	v_pk_fma_f32 v[18:19], v[34:35], v[126:127], v[18:19] op_sel_hi:[1,0,1]
	v_pk_fma_f32 v[20:21], v[36:37], v[126:127], v[20:21] op_sel_hi:[1,0,1]
	v_pk_fma_f32 v[22:23], v[38:39], v[126:127], v[22:23] op_sel_hi:[1,0,1]
	v_pk_fma_f32 v[24:25], v[40:41], v[126:127], v[24:25] op_sel_hi:[1,0,1]
	v_pk_fma_f32 v[26:27], v[42:43], v[126:127], v[26:27] op_sel_hi:[1,0,1]
	v_pk_fma_f32 v[28:29], v[44:45], v[126:127], v[28:29] op_sel_hi:[1,0,1]
	v_pk_fma_f32 v[30:31], v[46:47], v[126:127], v[30:31] op_sel_hi:[1,0,1]
	ds_read_b128 v[32:35], v7 offset:4096
	ds_read_b128 v[36:39], v7 offset:4112
	ds_read_b128 v[40:43], v7 offset:4128
	ds_read_b128 v[44:47], v7 offset:4144
	s_waitcnt vmcnt(0) lgkmcnt(4)
	v_pk_fma_f32 v[16:17], v[48:49], v[126:127], v[16:17] op_sel:[0,1,0] op_sel_hi:[1,1,1]
	v_pk_fma_f32 v[18:19], v[50:51], v[126:127], v[18:19] op_sel:[0,1,0] op_sel_hi:[1,1,1]
	v_pk_fma_f32 v[20:21], v[52:53], v[126:127], v[20:21] op_sel:[0,1,0] op_sel_hi:[1,1,1]
	v_pk_fma_f32 v[22:23], v[54:55], v[126:127], v[22:23] op_sel:[0,1,0] op_sel_hi:[1,1,1]
	v_pk_fma_f32 v[24:25], v[56:57], v[126:127], v[24:25] op_sel:[0,1,0] op_sel_hi:[1,1,1]
	v_pk_fma_f32 v[26:27], v[58:59], v[126:127], v[26:27] op_sel:[0,1,0] op_sel_hi:[1,1,1]
	v_pk_fma_f32 v[28:29], v[60:61], v[126:127], v[28:29] op_sel:[0,1,0] op_sel_hi:[1,1,1]
	v_pk_fma_f32 v[30:31], v[62:63], v[126:127], v[30:31] op_sel:[0,1,0] op_sel_hi:[1,1,1]
	global_load_dword v64, v4, s[20:21]
	s_add_u32 s20, s20, 0x9000
	s_addc_u32 s21, s21, 0
	global_load_dword v65, v4, s[20:21]
	s_add_u32 s20, s20, 0x9000
	s_addc_u32 s21, s21, 0
	global_load_dword v66, v4, s[20:21]
	s_add_u32 s20, s20, 0x9000
	s_addc_u32 s21, s21, 0
	global_load_dword v67, v4, s[20:21]
	s_add_u32 s20, s20, 0x9000
	s_addc_u32 s21, s21, 0
	global_load_dword v68, v4, s[20:21]
	s_add_u32 s20, s20, 0x9000
	s_addc_u32 s21, s21, 0
	global_load_dword v69, v4, s[20:21]
	s_add_u32 s20, s20, 0x9000
	s_addc_u32 s21, s21, 0
	global_load_dword v70, v4, s[20:21]
	s_add_u32 s20, s20, 0x9000
	s_addc_u32 s21, s21, 0
	global_load_dword v71, v4, s[20:21]
	s_add_u32 s20, s20, 0x9000
	s_addc_u32 s21, s21, 0
	global_load_dword v72, v4, s[20:21]
	s_add_u32 s20, s20, 0x9000
	s_addc_u32 s21, s21, 0
	global_load_dword v73, v4, s[20:21]
; #define LAS __attribute__((address_space(3)))
; __device__ __forceinline__ void ph_mod(const float* cp, const float* cs, const float* w_ada, const float* b_ada, float* MOD, float* MISC,
;                                        const float* lq1, const float* lk1, const float* lq2, const float* lk2, LAS unsigned char* lds, int G, int tid) {
;     ...
; #pragma unroll 16
;         for (int kk = 0; kk < 128; ++kk) { const int k = k0 + kk; const float wv = w_ada[(size_t)k * 9216 + col];
;             const f32x4 s0 = *(const LAS f32x4*)(scT + k * 16), s1 = *(const LAS f32x4*)(scT + k * 16 + 4), s2 = *(const LAS f32x4*)(scT + k * 16 + 8), s3 = *(const LAS f32x4*)(scT + k * 16 + 12);
;             acc[0] += s0[0] * wv; acc[1] += s0[1] * wv; acc[2] += s0[2] * wv; acc[3] += s0[3] * wv; acc[4] += s1[0] * wv; acc[5] += s1[1] * wv; acc[6] += s1[2] * wv; acc[7] += s1[3] * wv;
;             acc[8] += s2[0] * wv; acc[9] += s2[1] * wv; acc[10] += s2[2] * wv; acc[11] += s2[3] * wv; acc[12] += s3[0] * wv; acc[13] += s3[1] * wv; acc[14] += s3[2] * wv; acc[15] += s3[3] * wv; }
	s_add_u32 s20, s20, 0x9000
	s_addc_u32 s21, s21, 0
	global_load_dword v74, v4, s[20:21]
	s_add_u32 s20, s20, 0x9000
	s_addc_u32 s21, s21, 0
	global_load_dword v75, v4, s[20:21]
	s_add_u32 s20, s20, 0x9000
	s_addc_u32 s21, s21, 0
	global_load_dword v76, v4, s[20:21]
	s_add_u32 s20, s20, 0x9000
	s_addc_u32 s21, s21, 0
	global_load_dword v77, v4, s[20:21]
	s_add_u32 s20, s20, 0x9000
	s_addc_u32 s21, s21, 0
	global_load_dword v78, v4, s[20:21]
	s_add_u32 s20, s20, 0x9000
	s_addc_u32 s21, s21, 0
	global_load_dword v79, v4, s[20:21]
	s_add_u32 s20, s20, 0x9000
	s_addc_u32 s21, s21, 0
	global_load_dword v80, v4, s[20:21]
	s_add_u32 s20, s20, 0x9000
	s_addc_u32 s21, s21, 0
	global_load_dword v81, v4, s[20:21]
	s_add_u32 s20, s20, 0x9000
	s_addc_u32 s21, s21, 0
	global_load_dword v82, v4, s[20:21]
	s_add_u32 s20, s20, 0x9000
	s_addc_u32 s21, s21, 0
	global_load_dword v83, v4, s[20:21]
	s_add_u32 s20, s20, 0x9000
	s_addc_u32 s21, s21, 0
	global_load_dword v84, v4, s[20:21]
	s_add_u32 s20, s20, 0x9000
	s_addc_u32 s21, s21, 0
	global_load_dword v85, v4, s[20:21]
	s_add_u32 s20, s20, 0x9000
	s_addc_u32 s21, s21, 0
	global_load_dword v86, v4, s[20:21]
	s_add_u32 s20, s20, 0x9000
	s_addc_u32 s21, s21, 0
	global_load_dword v87, v4, s[20:21]
	s_add_u32 s20, s20, 0x9000
	s_addc_u32 s21, s21, 0
	global_load_dword v88, v4, s[20:21]
	s_add_u32 s20, s20, 0x9000
	s_addc_u32 s21, s21, 0
	global_load_dword v89, v4, s[20:21]
	s_add_u32 s20, s20, 0x9000
	s_addc_u32 s21, s21, 0
	global_load_dword v90, v4, s[20:21]
	s_add_u32 s20, s20, 0x9000
	s_addc_u32 s21, s21, 0
	global_load_dword v91, v4, s[20:21]
	s_add_u32 s20, s20, 0x9000
	s_addc_u32 s21, s21, 0
	global_load_dword v92, v4, s[20:21]
	s_add_u32 s20, s20, 0x9000
	s_addc_u32 s21, s21, 0
	global_load_dword v93, v4, s[20:21]
	s_add_u32 s20, s20, 0x9000
	s_addc_u32 s21, s21, 0
	global_load_dword v94, v4, s[20:21]
	s_add_u32 s20, s20, 0x9000
	s_addc_u32 s21, s21, 0
	global_load_dword v95, v4, s[20:21]
	s_add_u32 s20, s20, 0x9000
	s_addc_u32 s21, s21, 0
	global_load_dword v96, v4, s[20:21]
	s_add_u32 s20, s20, 0x9000
	s_addc_u32 s21, s21, 0
	global_load_dword v97, v4, s[20:21]
	s_add_u32 s20, s20, 0x9000
	s_addc_u32 s21, s21, 0
	global_load_dword v98, v4, s[20:21]
	s_add_u32 s20, s20, 0x9000
	s_addc_u32 s21, s21, 0
	global_load_dword v99, v4, s[20:21]
	s_add_u32 s20, s20, 0x9000
	s_addc_u32 s21, s21, 0
	global_load_dword v100, v4, s[20:21]
	s_add_u32 s20, s20, 0x9000
	s_addc_u32 s21, s21, 0
	global_load_dword v101, v4, s[20:21]
	s_add_u32 s20, s20, 0x9000
	s_addc_u32 s21, s21, 0
	global_load_dword v102, v4, s[20:21]
	s_add_u32 s20, s20, 0x9000
	s_addc_u32 s21, s21, 0
	global_load_dword v103, v4, s[20:21]
	s_add_u32 s20, s20, 0x9000
	s_addc_u32 s21, s21, 0
	global_load_dword v104, v4, s[20:21]
	s_add_u32 s20, s20, 0x9000
	s_addc_u32 s21, s21, 0
	global_load_dword v105, v4, s[20:21]
	s_add_u32 s20, s20, 0x9000
	s_addc_u32 s21, s21, 0
	global_load_dword v106, v4, s[20:21]
	s_add_u32 s20, s20, 0x9000
	s_addc_u32 s21, s21, 0
	global_load_dword v107, v4, s[20:21]
	s_add_u32 s20, s20, 0x9000
	s_addc_u32 s21, s21, 0
	global_load_dword v108, v4, s[20:21]
	s_add_u32 s20, s20, 0x9000
	s_addc_u32 s21, s21, 0
	global_load_dword v109, v4, s[20:21]
	s_add_u32 s20, s20, 0x9000
	s_addc_u32 s21, s21, 0
	global_load_dword v110, v4, s[20:21]
	s_add_u32 s20, s20, 0x9000
	s_addc_u32 s21, s21, 0
	global_load_dword v111, v4, s[20:21]
	s_add_u32 s20, s20, 0x9000
	s_addc_u32 s21, s21, 0
	global_load_dword v112, v4, s[20:21]
	s_add_u32 s20, s20, 0x9000
	s_addc_u32 s21, s21, 0
	global_load_dword v113, v4, s[20:21]
	s_add_u32 s20, s20, 0x9000
	s_addc_u32 s21, s21, 0
	global_load_dword v114, v4, s[20:21]
	s_add_u32 s20, s20, 0x9000
	s_addc_u32 s21, s21, 0
	global_load_dword v115, v4, s[20:21]
	s_add_u32 s20, s20, 0x9000
	s_addc_u32 s21, s21, 0
	global_load_dword v116, v4, s[20:21]
	s_add_u32 s20, s20, 0x9000
	s_addc_u32 s21, s21, 0
	global_load_dword v117, v4, s[20:21]
	s_add_u32 s20, s20, 0x9000
	s_addc_u32 s21, s21, 0
	global_load_dword v118, v4, s[20:21]
	s_add_u32 s20, s20, 0x9000
	s_addc_u32 s21, s21, 0
	global_load_dword v119, v4, s[20:21]
	s_add_u32 s20, s20, 0x9000
	s_addc_u32 s21, s21, 0
	global_load_dword v120, v4, s[20:21]
	s_add_u32 s20, s20, 0x9000
	s_addc_u32 s21, s21, 0
	global_load_dword v121, v4, s[20:21]
	s_add_u32 s20, s20, 0x9000
	s_addc_u32 s21, s21, 0
	global_load_dword v122, v4, s[20:21]
	s_add_u32 s20, s20, 0x9000
	s_addc_u32 s21, s21, 0
	global_load_dword v123, v4, s[20:21]
	s_add_u32 s20, s20, 0x9000
	s_addc_u32 s21, s21, 0
	global_load_dword v124, v4, s[20:21]
	s_add_u32 s20, s20, 0x9000
	s_addc_u32 s21, s21, 0
	global_load_dword v125, v4, s[20:21]
	s_add_u32 s20, s20, 0x9000
	s_addc_u32 s21, s21, 0
	global_load_dword v126, v4, s[20:21]
	s_add_u32 s20, s20, 0x9000
	s_addc_u32 s21, s21, 0
	global_load_dword v127, v4, s[20:21]
	s_add_u32 s20, s20, 0x9000
	s_addc_u32 s21, s21, 0
	ds_read_b128 v[48:51], v7 offset:4160
	ds_read_b128 v[52:55], v7 offset:4176
	ds_read_b128 v[56:59], v7 offset:4192
	ds_read_b128 v[60:63], v7 offset:4208
	s_waitcnt vmcnt(63) lgkmcnt(4)
	v_pk_fma_f32 v[16:17], v[32:33], v[64:65], v[16:17] op_sel_hi:[1,0,1]
	v_pk_fma_f32 v[18:19], v[34:35], v[64:65], v[18:19] op_sel_hi:[1,0,1]
	v_pk_fma_f32 v[20:21], v[36:37], v[64:65], v[20:21] op_sel_hi:[1,0,1]
	v_pk_fma_f32 v[22:23], v[38:39], v[64:65], v[22:23] op_sel_hi:[1,0,1]
	v_pk_fma_f32 v[24:25], v[40:41], v[64:65], v[24:25] op_sel_hi:[1,0,1]
	v_pk_fma_f32 v[26:27], v[42:43], v[64:65], v[26:27] op_sel_hi:[1,0,1]
	v_pk_fma_f32 v[28:29], v[44:45], v[64:65], v[28:29] op_sel_hi:[1,0,1]
	v_pk_fma_f32 v[30:31], v[46:47], v[64:65], v[30:31] op_sel_hi:[1,0,1]
	ds_read_b128 v[32:35], v7 offset:4224
	ds_read_b128 v[36:39], v7 offset:4240
	ds_read_b128 v[40:43], v7 offset:4256
	ds_read_b128 v[44:47], v7 offset:4272
	s_waitcnt vmcnt(62) lgkmcnt(4)
; #define LAS __attribute__((address_space(3)))
; __device__ __forceinline__ void ph_mod(const float* cp, const float* cs, const float* w_ada, const float* b_ada, float* MOD, float* MISC,
;                                        const float* lq1, const float* lk1, const float* lq2, const float* lk2, LAS unsigned char* lds, int G, int tid) {
;     ...
; #pragma unroll 16
;         for (int kk = 0; kk < 128; ++kk) { const int k = k0 + kk; const float wv = w_ada[(size_t)k * 9216 + col];
;             const f32x4 s0 = *(const LAS f32x4*)(scT + k * 16), s1 = *(const LAS f32x4*)(scT + k * 16 + 4), s2 = *(const LAS f32x4*)(scT + k * 16 + 8), s3 = *(const LAS f32x4*)(scT + k * 16 + 12);
;             acc[0] += s0[0] * wv; acc[1] += s0[1] * wv; acc[2] += s0[2] * wv; acc[3] += s0[3] * wv; acc[4] += s1[0] * wv; acc[5] += s1[1] * wv; acc[6] += s1[2] * wv; acc[7] += s1[3] * wv;
;             acc[8] += s2[0] * wv; acc[9] += s2[1] * wv; acc[10] += s2[2] * wv; acc[11] += s2[3] * wv; acc[12] += s3[0] * wv; acc[13] += s3[1] * wv; acc[14] += s3[2] * wv; acc[15] += s3[3] * wv; }
	v_pk_fma_f32 v[16:17], v[48:49], v[64:65], v[16:17] op_sel:[0,1,0] op_sel_hi:[1,1,1]
	v_pk_fma_f32 v[18:19], v[50:51], v[64:65], v[18:19] op_sel:[0,1,0] op_sel_hi:[1,1,1]
	v_pk_fma_f32 v[20:21], v[52:53], v[64:65], v[20:21] op_sel:[0,1,0] op_sel_hi:[1,1,1]
	v_pk_fma_f32 v[22:23], v[54:55], v[64:65], v[22:23] op_sel:[0,1,0] op_sel_hi:[1,1,1]
	v_pk_fma_f32 v[24:25], v[56:57], v[64:65], v[24:25] op_sel:[0,1,0] op_sel_hi:[1,1,1]
	v_pk_fma_f32 v[26:27], v[58:59], v[64:65], v[26:27] op_sel:[0,1,0] op_sel_hi:[1,1,1]
	v_pk_fma_f32 v[28:29], v[60:61], v[64:65], v[28:29] op_sel:[0,1,0] op_sel_hi:[1,1,1]
	v_pk_fma_f32 v[30:31], v[62:63], v[64:65], v[30:31] op_sel:[0,1,0] op_sel_hi:[1,1,1]
	ds_read_b128 v[48:51], v7 offset:4288
	ds_read_b128 v[52:55], v7 offset:4304
	ds_read_b128 v[56:59], v7 offset:4320
	ds_read_b128 v[60:63], v7 offset:4336
	s_waitcnt vmcnt(61) lgkmcnt(4)
	v_pk_fma_f32 v[16:17], v[32:33], v[66:67], v[16:17] op_sel_hi:[1,0,1]
	v_pk_fma_f32 v[18:19], v[34:35], v[66:67], v[18:19] op_sel_hi:[1,0,1]
	v_pk_fma_f32 v[20:21], v[36:37], v[66:67], v[20:21] op_sel_hi:[1,0,1]
	v_pk_fma_f32 v[22:23], v[38:39], v[66:67], v[22:23] op_sel_hi:[1,0,1]
	v_pk_fma_f32 v[24:25], v[40:41], v[66:67], v[24:25] op_sel_hi:[1,0,1]
	v_pk_fma_f32 v[26:27], v[42:43], v[66:67], v[26:27] op_sel_hi:[1,0,1]
	v_pk_fma_f32 v[28:29], v[44:45], v[66:67], v[28:29] op_sel_hi:[1,0,1]
	v_pk_fma_f32 v[30:31], v[46:47], v[66:67], v[30:31] op_sel_hi:[1,0,1]
	ds_read_b128 v[32:35], v7 offset:4352
	ds_read_b128 v[36:39], v7 offset:4368
	ds_read_b128 v[40:43], v7 offset:4384
	ds_read_b128 v[44:47], v7 offset:4400
	s_waitcnt vmcnt(60) lgkmcnt(4)
	v_pk_fma_f32 v[16:17], v[48:49], v[66:67], v[16:17] op_sel:[0,1,0] op_sel_hi:[1,1,1]
	v_pk_fma_f32 v[18:19], v[50:51], v[66:67], v[18:19] op_sel:[0,1,0] op_sel_hi:[1,1,1]
	v_pk_fma_f32 v[20:21], v[52:53], v[66:67], v[20:21] op_sel:[0,1,0] op_sel_hi:[1,1,1]
	v_pk_fma_f32 v[22:23], v[54:55], v[66:67], v[22:23] op_sel:[0,1,0] op_sel_hi:[1,1,1]
	v_pk_fma_f32 v[24:25], v[56:57], v[66:67], v[24:25] op_sel:[0,1,0] op_sel_hi:[1,1,1]
	v_pk_fma_f32 v[26:27], v[58:59], v[66:67], v[26:27] op_sel:[0,1,0] op_sel_hi:[1,1,1]
	v_pk_fma_f32 v[28:29], v[60:61], v[66:67], v[28:29] op_sel:[0,1,0] op_sel_hi:[1,1,1]
	v_pk_fma_f32 v[30:31], v[62:63], v[66:67], v[30:31] op_sel:[0,1,0] op_sel_hi:[1,1,1]
	ds_read_b128 v[48:51], v7 offset:4416
	ds_read_b128 v[52:55], v7 offset:4432
	ds_read_b128 v[56:59], v7 offset:4448
	ds_read_b128 v[60:63], v7 offset:4464
	s_waitcnt vmcnt(59) lgkmcnt(4)
	v_pk_fma_f32 v[16:17], v[32:33], v[68:69], v[16:17] op_sel_hi:[1,0,1]
	v_pk_fma_f32 v[18:19], v[34:35], v[68:69], v[18:19] op_sel_hi:[1,0,1]
	v_pk_fma_f32 v[20:21], v[36:37], v[68:69], v[20:21] op_sel_hi:[1,0,1]
	v_pk_fma_f32 v[22:23], v[38:39], v[68:69], v[22:23] op_sel_hi:[1,0,1]
	v_pk_fma_f32 v[24:25], v[40:41], v[68:69], v[24:25] op_sel_hi:[1,0,1]
	v_pk_fma_f32 v[26:27], v[42:43], v[68:69], v[26:27] op_sel_hi:[1,0,1]
	v_pk_fma_f32 v[28:29], v[44:45], v[68:69], v[28:29] op_sel_hi:[1,0,1]
	v_pk_fma_f32 v[30:31], v[46:47], v[68:69], v[30:31] op_sel_hi:[1,0,1]
	ds_read_b128 v[32:35], v7 offset:4480
	ds_read_b128 v[36:39], v7 offset:4496
	ds_read_b128 v[40:43], v7 offset:4512
	ds_read_b128 v[44:47], v7 offset:4528
	s_waitcnt vmcnt(58) lgkmcnt(4)
	v_pk_fma_f32 v[16:17], v[48:49], v[68:69], v[16:17] op_sel:[0,1,0] op_sel_hi:[1,1,1]
	v_pk_fma_f32 v[18:19], v[50:51], v[68:69], v[18:19] op_sel:[0,1,0] op_sel_hi:[1,1,1]
	v_pk_fma_f32 v[20:21], v[52:53], v[68:69], v[20:21] op_sel:[0,1,0] op_sel_hi:[1,1,1]
	v_pk_fma_f32 v[22:23], v[54:55], v[68:69], v[22:23] op_sel:[0,1,0] op_sel_hi:[1,1,1]
	v_pk_fma_f32 v[24:25], v[56:57], v[68:69], v[24:25] op_sel:[0,1,0] op_sel_hi:[1,1,1]
	v_pk_fma_f32 v[26:27], v[58:59], v[68:69], v[26:27] op_sel:[0,1,0] op_sel_hi:[1,1,1]
	v_pk_fma_f32 v[28:29], v[60:61], v[68:69], v[28:29] op_sel:[0,1,0] op_sel_hi:[1,1,1]
	v_pk_fma_f32 v[30:31], v[62:63], v[68:69], v[30:31] op_sel:[0,1,0] op_sel_hi:[1,1,1]
	ds_read_b128 v[48:51], v7 offset:4544
	ds_read_b128 v[52:55], v7 offset:4560
	ds_read_b128 v[56:59], v7 offset:4576
	ds_read_b128 v[60:63], v7 offset:4592
	s_waitcnt vmcnt(57) lgkmcnt(4)
	v_pk_fma_f32 v[16:17], v[32:33], v[70:71], v[16:17] op_sel_hi:[1,0,1]
	v_pk_fma_f32 v[18:19], v[34:35], v[70:71], v[18:19] op_sel_hi:[1,0,1]
	v_pk_fma_f32 v[20:21], v[36:37], v[70:71], v[20:21] op_sel_hi:[1,0,1]
	v_pk_fma_f32 v[22:23], v[38:39], v[70:71], v[22:23] op_sel_hi:[1,0,1]
	v_pk_fma_f32 v[24:25], v[40:41], v[70:71], v[24:25] op_sel_hi:[1,0,1]
	v_pk_fma_f32 v[26:27], v[42:43], v[70:71], v[26:27] op_sel_hi:[1,0,1]
	v_pk_fma_f32 v[28:29], v[44:45], v[70:71], v[28:29] op_sel_hi:[1,0,1]
	v_pk_fma_f32 v[30:31], v[46:47], v[70:71], v[30:31] op_sel_hi:[1,0,1]
	ds_read_b128 v[32:35], v7 offset:4608
	ds_read_b128 v[36:39], v7 offset:4624
	ds_read_b128 v[40:43], v7 offset:4640
	ds_read_b128 v[44:47], v7 offset:4656
	s_waitcnt vmcnt(56) lgkmcnt(4)
	v_pk_fma_f32 v[16:17], v[48:49], v[70:71], v[16:17] op_sel:[0,1,0] op_sel_hi:[1,1,1]
	v_pk_fma_f32 v[18:19], v[50:51], v[70:71], v[18:19] op_sel:[0,1,0] op_sel_hi:[1,1,1]
	v_pk_fma_f32 v[20:21], v[52:53], v[70:71], v[20:21] op_sel:[0,1,0] op_sel_hi:[1,1,1]
	v_pk_fma_f32 v[22:23], v[54:55], v[70:71], v[22:23] op_sel:[0,1,0] op_sel_hi:[1,1,1]
	v_pk_fma_f32 v[24:25], v[56:57], v[70:71], v[24:25] op_sel:[0,1,0] op_sel_hi:[1,1,1]
	v_pk_fma_f32 v[26:27], v[58:59], v[70:71], v[26:27] op_sel:[0,1,0] op_sel_hi:[1,1,1]
	v_pk_fma_f32 v[28:29], v[60:61], v[70:71], v[28:29] op_sel:[0,1,0] op_sel_hi:[1,1,1]
	v_pk_fma_f32 v[30:31], v[62:63], v[70:71], v[30:31] op_sel:[0,1,0] op_sel_hi:[1,1,1]
	ds_read_b128 v[48:51], v7 offset:4672
	ds_read_b128 v[52:55], v7 offset:4688
	ds_read_b128 v[56:59], v7 offset:4704
	ds_read_b128 v[60:63], v7 offset:4720
	s_waitcnt vmcnt(55) lgkmcnt(4)
; #define LAS __attribute__((address_space(3)))
; __device__ __forceinline__ void ph_mod(const float* cp, const float* cs, const float* w_ada, const float* b_ada, float* MOD, float* MISC,
;                                        const float* lq1, const float* lk1, const float* lq2, const float* lk2, LAS unsigned char* lds, int G, int tid) {
;     ...
; #pragma unroll 16
;         for (int kk = 0; kk < 128; ++kk) { const int k = k0 + kk; const float wv = w_ada[(size_t)k * 9216 + col];
;             const f32x4 s0 = *(const LAS f32x4*)(scT + k * 16), s1 = *(const LAS f32x4*)(scT + k * 16 + 4), s2 = *(const LAS f32x4*)(scT + k * 16 + 8), s3 = *(const LAS f32x4*)(scT + k * 16 + 12);
;             acc[0] += s0[0] * wv; acc[1] += s0[1] * wv; acc[2] += s0[2] * wv; acc[3] += s0[3] * wv; acc[4] += s1[0] * wv; acc[5] += s1[1] * wv; acc[6] += s1[2] * wv; acc[7] += s1[3] * wv;
;             acc[8] += s2[0] * wv; acc[9] += s2[1] * wv; acc[10] += s2[2] * wv; acc[11] += s2[3] * wv; acc[12] += s3[0] * wv; acc[13] += s3[1] * wv; acc[14] += s3[2] * wv; acc[15] += s3[3] * wv; }
	v_pk_fma_f32 v[16:17], v[32:33], v[72:73], v[16:17] op_sel_hi:[1,0,1]
	v_pk_fma_f32 v[18:19], v[34:35], v[72:73], v[18:19] op_sel_hi:[1,0,1]
	v_pk_fma_f32 v[20:21], v[36:37], v[72:73], v[20:21] op_sel_hi:[1,0,1]
	v_pk_fma_f32 v[22:23], v[38:39], v[72:73], v[22:23] op_sel_hi:[1,0,1]
	v_pk_fma_f32 v[24:25], v[40:41], v[72:73], v[24:25] op_sel_hi:[1,0,1]
	v_pk_fma_f32 v[26:27], v[42:43], v[72:73], v[26:27] op_sel_hi:[1,0,1]
	v_pk_fma_f32 v[28:29], v[44:45], v[72:73], v[28:29] op_sel_hi:[1,0,1]
	v_pk_fma_f32 v[30:31], v[46:47], v[72:73], v[30:31] op_sel_hi:[1,0,1]
	ds_read_b128 v[32:35], v7 offset:4736
	ds_read_b128 v[36:39], v7 offset:4752
	ds_read_b128 v[40:43], v7 offset:4768
	ds_read_b128 v[44:47], v7 offset:4784
	s_waitcnt vmcnt(54) lgkmcnt(4)
	v_pk_fma_f32 v[16:17], v[48:49], v[72:73], v[16:17] op_sel:[0,1,0] op_sel_hi:[1,1,1]
	v_pk_fma_f32 v[18:19], v[50:51], v[72:73], v[18:19] op_sel:[0,1,0] op_sel_hi:[1,1,1]
	v_pk_fma_f32 v[20:21], v[52:53], v[72:73], v[20:21] op_sel:[0,1,0] op_sel_hi:[1,1,1]
	v_pk_fma_f32 v[22:23], v[54:55], v[72:73], v[22:23] op_sel:[0,1,0] op_sel_hi:[1,1,1]
	v_pk_fma_f32 v[24:25], v[56:57], v[72:73], v[24:25] op_sel:[0,1,0] op_sel_hi:[1,1,1]
	v_pk_fma_f32 v[26:27], v[58:59], v[72:73], v[26:27] op_sel:[0,1,0] op_sel_hi:[1,1,1]
	v_pk_fma_f32 v[28:29], v[60:61], v[72:73], v[28:29] op_sel:[0,1,0] op_sel_hi:[1,1,1]
	v_pk_fma_f32 v[30:31], v[62:63], v[72:73], v[30:31] op_sel:[0,1,0] op_sel_hi:[1,1,1]
	ds_read_b128 v[48:51], v7 offset:4800
	ds_read_b128 v[52:55], v7 offset:4816
	ds_read_b128 v[56:59], v7 offset:4832
	ds_read_b128 v[60:63], v7 offset:4848
	s_waitcnt vmcnt(53) lgkmcnt(4)
	v_pk_fma_f32 v[16:17], v[32:33], v[74:75], v[16:17] op_sel_hi:[1,0,1]
	v_pk_fma_f32 v[18:19], v[34:35], v[74:75], v[18:19] op_sel_hi:[1,0,1]
	v_pk_fma_f32 v[20:21], v[36:37], v[74:75], v[20:21] op_sel_hi:[1,0,1]
	v_pk_fma_f32 v[22:23], v[38:39], v[74:75], v[22:23] op_sel_hi:[1,0,1]
	v_pk_fma_f32 v[24:25], v[40:41], v[74:75], v[24:25] op_sel_hi:[1,0,1]
	v_pk_fma_f32 v[26:27], v[42:43], v[74:75], v[26:27] op_sel_hi:[1,0,1]
	v_pk_fma_f32 v[28:29], v[44:45], v[74:75], v[28:29] op_sel_hi:[1,0,1]
	v_pk_fma_f32 v[30:31], v[46:47], v[74:75], v[30:31] op_sel_hi:[1,0,1]
	ds_read_b128 v[32:35], v7 offset:4864
	ds_read_b128 v[36:39], v7 offset:4880
	ds_read_b128 v[40:43], v7 offset:4896
	ds_read_b128 v[44:47], v7 offset:4912
	s_waitcnt vmcnt(52) lgkmcnt(4)
	v_pk_fma_f32 v[16:17], v[48:49], v[74:75], v[16:17] op_sel:[0,1,0] op_sel_hi:[1,1,1]
	v_pk_fma_f32 v[18:19], v[50:51], v[74:75], v[18:19] op_sel:[0,1,0] op_sel_hi:[1,1,1]
	v_pk_fma_f32 v[20:21], v[52:53], v[74:75], v[20:21] op_sel:[0,1,0] op_sel_hi:[1,1,1]
	v_pk_fma_f32 v[22:23], v[54:55], v[74:75], v[22:23] op_sel:[0,1,0] op_sel_hi:[1,1,1]
	v_pk_fma_f32 v[24:25], v[56:57], v[74:75], v[24:25] op_sel:[0,1,0] op_sel_hi:[1,1,1]
	v_pk_fma_f32 v[26:27], v[58:59], v[74:75], v[26:27] op_sel:[0,1,0] op_sel_hi:[1,1,1]
	v_pk_fma_f32 v[28:29], v[60:61], v[74:75], v[28:29] op_sel:[0,1,0] op_sel_hi:[1,1,1]
	v_pk_fma_f32 v[30:31], v[62:63], v[74:75], v[30:31] op_sel:[0,1,0] op_sel_hi:[1,1,1]
	ds_read_b128 v[48:51], v7 offset:4928
	ds_read_b128 v[52:55], v7 offset:4944
	ds_read_b128 v[56:59], v7 offset:4960
	ds_read_b128 v[60:63], v7 offset:4976
	s_waitcnt vmcnt(51) lgkmcnt(4)
	v_pk_fma_f32 v[16:17], v[32:33], v[76:77], v[16:17] op_sel_hi:[1,0,1]
	v_pk_fma_f32 v[18:19], v[34:35], v[76:77], v[18:19] op_sel_hi:[1,0,1]
	v_pk_fma_f32 v[20:21], v[36:37], v[76:77], v[20:21] op_sel_hi:[1,0,1]
	v_pk_fma_f32 v[22:23], v[38:39], v[76:77], v[22:23] op_sel_hi:[1,0,1]
	v_pk_fma_f32 v[24:25], v[40:41], v[76:77], v[24:25] op_sel_hi:[1,0,1]
	v_pk_fma_f32 v[26:27], v[42:43], v[76:77], v[26:27] op_sel_hi:[1,0,1]
	v_pk_fma_f32 v[28:29], v[44:45], v[76:77], v[28:29] op_sel_hi:[1,0,1]
	v_pk_fma_f32 v[30:31], v[46:47], v[76:77], v[30:31] op_sel_hi:[1,0,1]
	ds_read_b128 v[32:35], v7 offset:4992
	ds_read_b128 v[36:39], v7 offset:5008
	ds_read_b128 v[40:43], v7 offset:5024
	ds_read_b128 v[44:47], v7 offset:5040
	s_waitcnt vmcnt(50) lgkmcnt(4)
	v_pk_fma_f32 v[16:17], v[48:49], v[76:77], v[16:17] op_sel:[0,1,0] op_sel_hi:[1,1,1]
	v_pk_fma_f32 v[18:19], v[50:51], v[76:77], v[18:19] op_sel:[0,1,0] op_sel_hi:[1,1,1]
	v_pk_fma_f32 v[20:21], v[52:53], v[76:77], v[20:21] op_sel:[0,1,0] op_sel_hi:[1,1,1]
	v_pk_fma_f32 v[22:23], v[54:55], v[76:77], v[22:23] op_sel:[0,1,0] op_sel_hi:[1,1,1]
	v_pk_fma_f32 v[24:25], v[56:57], v[76:77], v[24:25] op_sel:[0,1,0] op_sel_hi:[1,1,1]
	v_pk_fma_f32 v[26:27], v[58:59], v[76:77], v[26:27] op_sel:[0,1,0] op_sel_hi:[1,1,1]
	v_pk_fma_f32 v[28:29], v[60:61], v[76:77], v[28:29] op_sel:[0,1,0] op_sel_hi:[1,1,1]
	v_pk_fma_f32 v[30:31], v[62:63], v[76:77], v[30:31] op_sel:[0,1,0] op_sel_hi:[1,1,1]
	ds_read_b128 v[48:51], v7 offset:5056
	ds_read_b128 v[52:55], v7 offset:5072
	ds_read_b128 v[56:59], v7 offset:5088
	ds_read_b128 v[60:63], v7 offset:5104
	s_waitcnt vmcnt(49) lgkmcnt(4)
	v_pk_fma_f32 v[16:17], v[32:33], v[78:79], v[16:17] op_sel_hi:[1,0,1]
	v_pk_fma_f32 v[18:19], v[34:35], v[78:79], v[18:19] op_sel_hi:[1,0,1]
	v_pk_fma_f32 v[20:21], v[36:37], v[78:79], v[20:21] op_sel_hi:[1,0,1]
	v_pk_fma_f32 v[22:23], v[38:39], v[78:79], v[22:23] op_sel_hi:[1,0,1]
	v_pk_fma_f32 v[24:25], v[40:41], v[78:79], v[24:25] op_sel_hi:[1,0,1]
	v_pk_fma_f32 v[26:27], v[42:43], v[78:79], v[26:27] op_sel_hi:[1,0,1]
	v_pk_fma_f32 v[28:29], v[44:45], v[78:79], v[28:29] op_sel_hi:[1,0,1]
	v_pk_fma_f32 v[30:31], v[46:47], v[78:79], v[30:31] op_sel_hi:[1,0,1]
	ds_read_b128 v[32:35], v7 offset:5120
	ds_read_b128 v[36:39], v7 offset:5136
	ds_read_b128 v[40:43], v7 offset:5152
	ds_read_b128 v[44:47], v7 offset:5168
	s_waitcnt vmcnt(48) lgkmcnt(4)
; #define LAS __attribute__((address_space(3)))
; __device__ __forceinline__ void ph_mod(const float* cp, const float* cs, const float* w_ada, const float* b_ada, float* MOD, float* MISC,
;                                        const float* lq1, const float* lk1, const float* lq2, const float* lk2, LAS unsigned char* lds, int G, int tid) {
;     ...
; #pragma unroll 16
;         for (int kk = 0; kk < 128; ++kk) { const int k = k0 + kk; const float wv = w_ada[(size_t)k * 9216 + col];
;             const f32x4 s0 = *(const LAS f32x4*)(scT + k * 16), s1 = *(const LAS f32x4*)(scT + k * 16 + 4), s2 = *(const LAS f32x4*)(scT + k * 16 + 8), s3 = *(const LAS f32x4*)(scT + k * 16 + 12);
;             acc[0] += s0[0] * wv; acc[1] += s0[1] * wv; acc[2] += s0[2] * wv; acc[3] += s0[3] * wv; acc[4] += s1[0] * wv; acc[5] += s1[1] * wv; acc[6] += s1[2] * wv; acc[7] += s1[3] * wv;
;             acc[8] += s2[0] * wv; acc[9] += s2[1] * wv; acc[10] += s2[2] * wv; acc[11] += s2[3] * wv; acc[12] += s3[0] * wv; acc[13] += s3[1] * wv; acc[14] += s3[2] * wv; acc[15] += s3[3] * wv; }
	v_pk_fma_f32 v[16:17], v[48:49], v[78:79], v[16:17] op_sel:[0,1,0] op_sel_hi:[1,1,1]
	v_pk_fma_f32 v[18:19], v[50:51], v[78:79], v[18:19] op_sel:[0,1,0] op_sel_hi:[1,1,1]
	v_pk_fma_f32 v[20:21], v[52:53], v[78:79], v[20:21] op_sel:[0,1,0] op_sel_hi:[1,1,1]
	v_pk_fma_f32 v[22:23], v[54:55], v[78:79], v[22:23] op_sel:[0,1,0] op_sel_hi:[1,1,1]
	v_pk_fma_f32 v[24:25], v[56:57], v[78:79], v[24:25] op_sel:[0,1,0] op_sel_hi:[1,1,1]
	v_pk_fma_f32 v[26:27], v[58:59], v[78:79], v[26:27] op_sel:[0,1,0] op_sel_hi:[1,1,1]
	v_pk_fma_f32 v[28:29], v[60:61], v[78:79], v[28:29] op_sel:[0,1,0] op_sel_hi:[1,1,1]
	v_pk_fma_f32 v[30:31], v[62:63], v[78:79], v[30:31] op_sel:[0,1,0] op_sel_hi:[1,1,1]
	ds_read_b128 v[48:51], v7 offset:5184
	ds_read_b128 v[52:55], v7 offset:5200
	ds_read_b128 v[56:59], v7 offset:5216
	ds_read_b128 v[60:63], v7 offset:5232
	s_waitcnt vmcnt(47) lgkmcnt(4)
	v_pk_fma_f32 v[16:17], v[32:33], v[80:81], v[16:17] op_sel_hi:[1,0,1]
	v_pk_fma_f32 v[18:19], v[34:35], v[80:81], v[18:19] op_sel_hi:[1,0,1]
	v_pk_fma_f32 v[20:21], v[36:37], v[80:81], v[20:21] op_sel_hi:[1,0,1]
	v_pk_fma_f32 v[22:23], v[38:39], v[80:81], v[22:23] op_sel_hi:[1,0,1]
	v_pk_fma_f32 v[24:25], v[40:41], v[80:81], v[24:25] op_sel_hi:[1,0,1]
	v_pk_fma_f32 v[26:27], v[42:43], v[80:81], v[26:27] op_sel_hi:[1,0,1]
	v_pk_fma_f32 v[28:29], v[44:45], v[80:81], v[28:29] op_sel_hi:[1,0,1]
	v_pk_fma_f32 v[30:31], v[46:47], v[80:81], v[30:31] op_sel_hi:[1,0,1]
	ds_read_b128 v[32:35], v7 offset:5248
	ds_read_b128 v[36:39], v7 offset:5264
	ds_read_b128 v[40:43], v7 offset:5280
	ds_read_b128 v[44:47], v7 offset:5296
	s_waitcnt vmcnt(46) lgkmcnt(4)
	v_pk_fma_f32 v[16:17], v[48:49], v[80:81], v[16:17] op_sel:[0,1,0] op_sel_hi:[1,1,1]
	v_pk_fma_f32 v[18:19], v[50:51], v[80:81], v[18:19] op_sel:[0,1,0] op_sel_hi:[1,1,1]
	v_pk_fma_f32 v[20:21], v[52:53], v[80:81], v[20:21] op_sel:[0,1,0] op_sel_hi:[1,1,1]
	v_pk_fma_f32 v[22:23], v[54:55], v[80:81], v[22:23] op_sel:[0,1,0] op_sel_hi:[1,1,1]
	v_pk_fma_f32 v[24:25], v[56:57], v[80:81], v[24:25] op_sel:[0,1,0] op_sel_hi:[1,1,1]
	v_pk_fma_f32 v[26:27], v[58:59], v[80:81], v[26:27] op_sel:[0,1,0] op_sel_hi:[1,1,1]
	v_pk_fma_f32 v[28:29], v[60:61], v[80:81], v[28:29] op_sel:[0,1,0] op_sel_hi:[1,1,1]
	v_pk_fma_f32 v[30:31], v[62:63], v[80:81], v[30:31] op_sel:[0,1,0] op_sel_hi:[1,1,1]
	ds_read_b128 v[48:51], v7 offset:5312
	ds_read_b128 v[52:55], v7 offset:5328
	ds_read_b128 v[56:59], v7 offset:5344
	ds_read_b128 v[60:63], v7 offset:5360
	s_waitcnt vmcnt(45) lgkmcnt(4)
	v_pk_fma_f32 v[16:17], v[32:33], v[82:83], v[16:17] op_sel_hi:[1,0,1]
	v_pk_fma_f32 v[18:19], v[34:35], v[82:83], v[18:19] op_sel_hi:[1,0,1]
	v_pk_fma_f32 v[20:21], v[36:37], v[82:83], v[20:21] op_sel_hi:[1,0,1]
	v_pk_fma_f32 v[22:23], v[38:39], v[82:83], v[22:23] op_sel_hi:[1,0,1]
	v_pk_fma_f32 v[24:25], v[40:41], v[82:83], v[24:25] op_sel_hi:[1,0,1]
	v_pk_fma_f32 v[26:27], v[42:43], v[82:83], v[26:27] op_sel_hi:[1,0,1]
	v_pk_fma_f32 v[28:29], v[44:45], v[82:83], v[28:29] op_sel_hi:[1,0,1]
	v_pk_fma_f32 v[30:31], v[46:47], v[82:83], v[30:31] op_sel_hi:[1,0,1]
	ds_read_b128 v[32:35], v7 offset:5376
	ds_read_b128 v[36:39], v7 offset:5392
	ds_read_b128 v[40:43], v7 offset:5408
	ds_read_b128 v[44:47], v7 offset:5424
	s_waitcnt vmcnt(44) lgkmcnt(4)
	v_pk_fma_f32 v[16:17], v[48:49], v[82:83], v[16:17] op_sel:[0,1,0] op_sel_hi:[1,1,1]
	v_pk_fma_f32 v[18:19], v[50:51], v[82:83], v[18:19] op_sel:[0,1,0] op_sel_hi:[1,1,1]
	v_pk_fma_f32 v[20:21], v[52:53], v[82:83], v[20:21] op_sel:[0,1,0] op_sel_hi:[1,1,1]
	v_pk_fma_f32 v[22:23], v[54:55], v[82:83], v[22:23] op_sel:[0,1,0] op_sel_hi:[1,1,1]
	v_pk_fma_f32 v[24:25], v[56:57], v[82:83], v[24:25] op_sel:[0,1,0] op_sel_hi:[1,1,1]
	v_pk_fma_f32 v[26:27], v[58:59], v[82:83], v[26:27] op_sel:[0,1,0] op_sel_hi:[1,1,1]
	v_pk_fma_f32 v[28:29], v[60:61], v[82:83], v[28:29] op_sel:[0,1,0] op_sel_hi:[1,1,1]
	v_pk_fma_f32 v[30:31], v[62:63], v[82:83], v[30:31] op_sel:[0,1,0] op_sel_hi:[1,1,1]
	ds_read_b128 v[48:51], v7 offset:5440
	ds_read_b128 v[52:55], v7 offset:5456
	ds_read_b128 v[56:59], v7 offset:5472
	ds_read_b128 v[60:63], v7 offset:5488
	s_waitcnt vmcnt(43) lgkmcnt(4)
	v_pk_fma_f32 v[16:17], v[32:33], v[84:85], v[16:17] op_sel_hi:[1,0,1]
	v_pk_fma_f32 v[18:19], v[34:35], v[84:85], v[18:19] op_sel_hi:[1,0,1]
	v_pk_fma_f32 v[20:21], v[36:37], v[84:85], v[20:21] op_sel_hi:[1,0,1]
	v_pk_fma_f32 v[22:23], v[38:39], v[84:85], v[22:23] op_sel_hi:[1,0,1]
	v_pk_fma_f32 v[24:25], v[40:41], v[84:85], v[24:25] op_sel_hi:[1,0,1]
	v_pk_fma_f32 v[26:27], v[42:43], v[84:85], v[26:27] op_sel_hi:[1,0,1]
	v_pk_fma_f32 v[28:29], v[44:45], v[84:85], v[28:29] op_sel_hi:[1,0,1]
	v_pk_fma_f32 v[30:31], v[46:47], v[84:85], v[30:31] op_sel_hi:[1,0,1]
	ds_read_b128 v[32:35], v7 offset:5504
	ds_read_b128 v[36:39], v7 offset:5520
	ds_read_b128 v[40:43], v7 offset:5536
	ds_read_b128 v[44:47], v7 offset:5552
	s_waitcnt vmcnt(42) lgkmcnt(4)
	v_pk_fma_f32 v[16:17], v[48:49], v[84:85], v[16:17] op_sel:[0,1,0] op_sel_hi:[1,1,1]
	v_pk_fma_f32 v[18:19], v[50:51], v[84:85], v[18:19] op_sel:[0,1,0] op_sel_hi:[1,1,1]
	v_pk_fma_f32 v[20:21], v[52:53], v[84:85], v[20:21] op_sel:[0,1,0] op_sel_hi:[1,1,1]
	v_pk_fma_f32 v[22:23], v[54:55], v[84:85], v[22:23] op_sel:[0,1,0] op_sel_hi:[1,1,1]
	v_pk_fma_f32 v[24:25], v[56:57], v[84:85], v[24:25] op_sel:[0,1,0] op_sel_hi:[1,1,1]
	v_pk_fma_f32 v[26:27], v[58:59], v[84:85], v[26:27] op_sel:[0,1,0] op_sel_hi:[1,1,1]
	v_pk_fma_f32 v[28:29], v[60:61], v[84:85], v[28:29] op_sel:[0,1,0] op_sel_hi:[1,1,1]
	v_pk_fma_f32 v[30:31], v[62:63], v[84:85], v[30:31] op_sel:[0,1,0] op_sel_hi:[1,1,1]
	ds_read_b128 v[48:51], v7 offset:5568
	ds_read_b128 v[52:55], v7 offset:5584
	ds_read_b128 v[56:59], v7 offset:5600
	ds_read_b128 v[60:63], v7 offset:5616
	s_waitcnt vmcnt(41) lgkmcnt(4)
; #define LAS __attribute__((address_space(3)))
; __device__ __forceinline__ void ph_mod(const float* cp, const float* cs, const float* w_ada, const float* b_ada, float* MOD, float* MISC,
;                                        const float* lq1, const float* lk1, const float* lq2, const float* lk2, LAS unsigned char* lds, int G, int tid) {
;     ...
; #pragma unroll 16
;         for (int kk = 0; kk < 128; ++kk) { const int k = k0 + kk; const float wv = w_ada[(size_t)k * 9216 + col];
;             const f32x4 s0 = *(const LAS f32x4*)(scT + k * 16), s1 = *(const LAS f32x4*)(scT + k * 16 + 4), s2 = *(const LAS f32x4*)(scT + k * 16 + 8), s3 = *(const LAS f32x4*)(scT + k * 16 + 12);
;             acc[0] += s0[0] * wv; acc[1] += s0[1] * wv; acc[2] += s0[2] * wv; acc[3] += s0[3] * wv; acc[4] += s1[0] * wv; acc[5] += s1[1] * wv; acc[6] += s1[2] * wv; acc[7] += s1[3] * wv;
;             acc[8] += s2[0] * wv; acc[9] += s2[1] * wv; acc[10] += s2[2] * wv; acc[11] += s2[3] * wv; acc[12] += s3[0] * wv; acc[13] += s3[1] * wv; acc[14] += s3[2] * wv; acc[15] += s3[3] * wv; }
	v_pk_fma_f32 v[16:17], v[32:33], v[86:87], v[16:17] op_sel_hi:[1,0,1]
	v_pk_fma_f32 v[18:19], v[34:35], v[86:87], v[18:19] op_sel_hi:[1,0,1]
	v_pk_fma_f32 v[20:21], v[36:37], v[86:87], v[20:21] op_sel_hi:[1,0,1]
	v_pk_fma_f32 v[22:23], v[38:39], v[86:87], v[22:23] op_sel_hi:[1,0,1]
	v_pk_fma_f32 v[24:25], v[40:41], v[86:87], v[24:25] op_sel_hi:[1,0,1]
	v_pk_fma_f32 v[26:27], v[42:43], v[86:87], v[26:27] op_sel_hi:[1,0,1]
	v_pk_fma_f32 v[28:29], v[44:45], v[86:87], v[28:29] op_sel_hi:[1,0,1]
	v_pk_fma_f32 v[30:31], v[46:47], v[86:87], v[30:31] op_sel_hi:[1,0,1]
	ds_read_b128 v[32:35], v7 offset:5632
	ds_read_b128 v[36:39], v7 offset:5648
	ds_read_b128 v[40:43], v7 offset:5664
	ds_read_b128 v[44:47], v7 offset:5680
	s_waitcnt vmcnt(40) lgkmcnt(4)
	v_pk_fma_f32 v[16:17], v[48:49], v[86:87], v[16:17] op_sel:[0,1,0] op_sel_hi:[1,1,1]
	v_pk_fma_f32 v[18:19], v[50:51], v[86:87], v[18:19] op_sel:[0,1,0] op_sel_hi:[1,1,1]
	v_pk_fma_f32 v[20:21], v[52:53], v[86:87], v[20:21] op_sel:[0,1,0] op_sel_hi:[1,1,1]
	v_pk_fma_f32 v[22:23], v[54:55], v[86:87], v[22:23] op_sel:[0,1,0] op_sel_hi:[1,1,1]
	v_pk_fma_f32 v[24:25], v[56:57], v[86:87], v[24:25] op_sel:[0,1,0] op_sel_hi:[1,1,1]
	v_pk_fma_f32 v[26:27], v[58:59], v[86:87], v[26:27] op_sel:[0,1,0] op_sel_hi:[1,1,1]
	v_pk_fma_f32 v[28:29], v[60:61], v[86:87], v[28:29] op_sel:[0,1,0] op_sel_hi:[1,1,1]
	v_pk_fma_f32 v[30:31], v[62:63], v[86:87], v[30:31] op_sel:[0,1,0] op_sel_hi:[1,1,1]
	ds_read_b128 v[48:51], v7 offset:5696
	ds_read_b128 v[52:55], v7 offset:5712
	ds_read_b128 v[56:59], v7 offset:5728
	ds_read_b128 v[60:63], v7 offset:5744
	s_waitcnt vmcnt(39) lgkmcnt(4)
	v_pk_fma_f32 v[16:17], v[32:33], v[88:89], v[16:17] op_sel_hi:[1,0,1]
	v_pk_fma_f32 v[18:19], v[34:35], v[88:89], v[18:19] op_sel_hi:[1,0,1]
	v_pk_fma_f32 v[20:21], v[36:37], v[88:89], v[20:21] op_sel_hi:[1,0,1]
	v_pk_fma_f32 v[22:23], v[38:39], v[88:89], v[22:23] op_sel_hi:[1,0,1]
	v_pk_fma_f32 v[24:25], v[40:41], v[88:89], v[24:25] op_sel_hi:[1,0,1]
	v_pk_fma_f32 v[26:27], v[42:43], v[88:89], v[26:27] op_sel_hi:[1,0,1]
	v_pk_fma_f32 v[28:29], v[44:45], v[88:89], v[28:29] op_sel_hi:[1,0,1]
	v_pk_fma_f32 v[30:31], v[46:47], v[88:89], v[30:31] op_sel_hi:[1,0,1]
	ds_read_b128 v[32:35], v7 offset:5760
	ds_read_b128 v[36:39], v7 offset:5776
	ds_read_b128 v[40:43], v7 offset:5792
	ds_read_b128 v[44:47], v7 offset:5808
	s_waitcnt vmcnt(38) lgkmcnt(4)
	v_pk_fma_f32 v[16:17], v[48:49], v[88:89], v[16:17] op_sel:[0,1,0] op_sel_hi:[1,1,1]
	v_pk_fma_f32 v[18:19], v[50:51], v[88:89], v[18:19] op_sel:[0,1,0] op_sel_hi:[1,1,1]
	v_pk_fma_f32 v[20:21], v[52:53], v[88:89], v[20:21] op_sel:[0,1,0] op_sel_hi:[1,1,1]
	v_pk_fma_f32 v[22:23], v[54:55], v[88:89], v[22:23] op_sel:[0,1,0] op_sel_hi:[1,1,1]
	v_pk_fma_f32 v[24:25], v[56:57], v[88:89], v[24:25] op_sel:[0,1,0] op_sel_hi:[1,1,1]
	v_pk_fma_f32 v[26:27], v[58:59], v[88:89], v[26:27] op_sel:[0,1,0] op_sel_hi:[1,1,1]
	v_pk_fma_f32 v[28:29], v[60:61], v[88:89], v[28:29] op_sel:[0,1,0] op_sel_hi:[1,1,1]
	v_pk_fma_f32 v[30:31], v[62:63], v[88:89], v[30:31] op_sel:[0,1,0] op_sel_hi:[1,1,1]
	ds_read_b128 v[48:51], v7 offset:5824
	ds_read_b128 v[52:55], v7 offset:5840
	ds_read_b128 v[56:59], v7 offset:5856
	ds_read_b128 v[60:63], v7 offset:5872
	s_waitcnt vmcnt(37) lgkmcnt(4)
	v_pk_fma_f32 v[16:17], v[32:33], v[90:91], v[16:17] op_sel_hi:[1,0,1]
	v_pk_fma_f32 v[18:19], v[34:35], v[90:91], v[18:19] op_sel_hi:[1,0,1]
	v_pk_fma_f32 v[20:21], v[36:37], v[90:91], v[20:21] op_sel_hi:[1,0,1]
	v_pk_fma_f32 v[22:23], v[38:39], v[90:91], v[22:23] op_sel_hi:[1,0,1]
	v_pk_fma_f32 v[24:25], v[40:41], v[90:91], v[24:25] op_sel_hi:[1,0,1]
	v_pk_fma_f32 v[26:27], v[42:43], v[90:91], v[26:27] op_sel_hi:[1,0,1]
	v_pk_fma_f32 v[28:29], v[44:45], v[90:91], v[28:29] op_sel_hi:[1,0,1]
	v_pk_fma_f32 v[30:31], v[46:47], v[90:91], v[30:31] op_sel_hi:[1,0,1]
	ds_read_b128 v[32:35], v7 offset:5888
	ds_read_b128 v[36:39], v7 offset:5904
	ds_read_b128 v[40:43], v7 offset:5920
	ds_read_b128 v[44:47], v7 offset:5936
	s_waitcnt vmcnt(36) lgkmcnt(4)
	v_pk_fma_f32 v[16:17], v[48:49], v[90:91], v[16:17] op_sel:[0,1,0] op_sel_hi:[1,1,1]
	v_pk_fma_f32 v[18:19], v[50:51], v[90:91], v[18:19] op_sel:[0,1,0] op_sel_hi:[1,1,1]
	v_pk_fma_f32 v[20:21], v[52:53], v[90:91], v[20:21] op_sel:[0,1,0] op_sel_hi:[1,1,1]
	v_pk_fma_f32 v[22:23], v[54:55], v[90:91], v[22:23] op_sel:[0,1,0] op_sel_hi:[1,1,1]
	v_pk_fma_f32 v[24:25], v[56:57], v[90:91], v[24:25] op_sel:[0,1,0] op_sel_hi:[1,1,1]
	v_pk_fma_f32 v[26:27], v[58:59], v[90:91], v[26:27] op_sel:[0,1,0] op_sel_hi:[1,1,1]
	v_pk_fma_f32 v[28:29], v[60:61], v[90:91], v[28:29] op_sel:[0,1,0] op_sel_hi:[1,1,1]
	v_pk_fma_f32 v[30:31], v[62:63], v[90:91], v[30:31] op_sel:[0,1,0] op_sel_hi:[1,1,1]
	ds_read_b128 v[48:51], v7 offset:5952
	ds_read_b128 v[52:55], v7 offset:5968
	ds_read_b128 v[56:59], v7 offset:5984
	ds_read_b128 v[60:63], v7 offset:6000
	s_waitcnt vmcnt(35) lgkmcnt(4)
	v_pk_fma_f32 v[16:17], v[32:33], v[92:93], v[16:17] op_sel_hi:[1,0,1]
	v_pk_fma_f32 v[18:19], v[34:35], v[92:93], v[18:19] op_sel_hi:[1,0,1]
	v_pk_fma_f32 v[20:21], v[36:37], v[92:93], v[20:21] op_sel_hi:[1,0,1]
	v_pk_fma_f32 v[22:23], v[38:39], v[92:93], v[22:23] op_sel_hi:[1,0,1]
	v_pk_fma_f32 v[24:25], v[40:41], v[92:93], v[24:25] op_sel_hi:[1,0,1]
	v_pk_fma_f32 v[26:27], v[42:43], v[92:93], v[26:27] op_sel_hi:[1,0,1]
	v_pk_fma_f32 v[28:29], v[44:45], v[92:93], v[28:29] op_sel_hi:[1,0,1]
	v_pk_fma_f32 v[30:31], v[46:47], v[92:93], v[30:31] op_sel_hi:[1,0,1]
	ds_read_b128 v[32:35], v7 offset:6016
	ds_read_b128 v[36:39], v7 offset:6032
	ds_read_b128 v[40:43], v7 offset:6048
	ds_read_b128 v[44:47], v7 offset:6064
	s_waitcnt vmcnt(34) lgkmcnt(4)
; #define LAS __attribute__((address_space(3)))
; __device__ __forceinline__ void ph_mod(const float* cp, const float* cs, const float* w_ada, const float* b_ada, float* MOD, float* MISC,
;                                        const float* lq1, const float* lk1, const float* lq2, const float* lk2, LAS unsigned char* lds, int G, int tid) {
;     ...
; #pragma unroll 16
;         for (int kk = 0; kk < 128; ++kk) { const int k = k0 + kk; const float wv = w_ada[(size_t)k * 9216 + col];
;             const f32x4 s0 = *(const LAS f32x4*)(scT + k * 16), s1 = *(const LAS f32x4*)(scT + k * 16 + 4), s2 = *(const LAS f32x4*)(scT + k * 16 + 8), s3 = *(const LAS f32x4*)(scT + k * 16 + 12);
;             acc[0] += s0[0] * wv; acc[1] += s0[1] * wv; acc[2] += s0[2] * wv; acc[3] += s0[3] * wv; acc[4] += s1[0] * wv; acc[5] += s1[1] * wv; acc[6] += s1[2] * wv; acc[7] += s1[3] * wv;
;             acc[8] += s2[0] * wv; acc[9] += s2[1] * wv; acc[10] += s2[2] * wv; acc[11] += s2[3] * wv; acc[12] += s3[0] * wv; acc[13] += s3[1] * wv; acc[14] += s3[2] * wv; acc[15] += s3[3] * wv; }
	v_pk_fma_f32 v[16:17], v[48:49], v[92:93], v[16:17] op_sel:[0,1,0] op_sel_hi:[1,1,1]
	v_pk_fma_f32 v[18:19], v[50:51], v[92:93], v[18:19] op_sel:[0,1,0] op_sel_hi:[1,1,1]
	v_pk_fma_f32 v[20:21], v[52:53], v[92:93], v[20:21] op_sel:[0,1,0] op_sel_hi:[1,1,1]
	v_pk_fma_f32 v[22:23], v[54:55], v[92:93], v[22:23] op_sel:[0,1,0] op_sel_hi:[1,1,1]
	v_pk_fma_f32 v[24:25], v[56:57], v[92:93], v[24:25] op_sel:[0,1,0] op_sel_hi:[1,1,1]
	v_pk_fma_f32 v[26:27], v[58:59], v[92:93], v[26:27] op_sel:[0,1,0] op_sel_hi:[1,1,1]
	v_pk_fma_f32 v[28:29], v[60:61], v[92:93], v[28:29] op_sel:[0,1,0] op_sel_hi:[1,1,1]
	v_pk_fma_f32 v[30:31], v[62:63], v[92:93], v[30:31] op_sel:[0,1,0] op_sel_hi:[1,1,1]
	ds_read_b128 v[48:51], v7 offset:6080
	ds_read_b128 v[52:55], v7 offset:6096
	ds_read_b128 v[56:59], v7 offset:6112
	ds_read_b128 v[60:63], v7 offset:6128
	s_waitcnt vmcnt(33) lgkmcnt(4)
	v_pk_fma_f32 v[16:17], v[32:33], v[94:95], v[16:17] op_sel_hi:[1,0,1]
	v_pk_fma_f32 v[18:19], v[34:35], v[94:95], v[18:19] op_sel_hi:[1,0,1]
	v_pk_fma_f32 v[20:21], v[36:37], v[94:95], v[20:21] op_sel_hi:[1,0,1]
	v_pk_fma_f32 v[22:23], v[38:39], v[94:95], v[22:23] op_sel_hi:[1,0,1]
	v_pk_fma_f32 v[24:25], v[40:41], v[94:95], v[24:25] op_sel_hi:[1,0,1]
	v_pk_fma_f32 v[26:27], v[42:43], v[94:95], v[26:27] op_sel_hi:[1,0,1]
	v_pk_fma_f32 v[28:29], v[44:45], v[94:95], v[28:29] op_sel_hi:[1,0,1]
	v_pk_fma_f32 v[30:31], v[46:47], v[94:95], v[30:31] op_sel_hi:[1,0,1]
	ds_read_b128 v[32:35], v7 offset:6144
	ds_read_b128 v[36:39], v7 offset:6160
	ds_read_b128 v[40:43], v7 offset:6176
	ds_read_b128 v[44:47], v7 offset:6192
	s_waitcnt vmcnt(32) lgkmcnt(4)
	v_pk_fma_f32 v[16:17], v[48:49], v[94:95], v[16:17] op_sel:[0,1,0] op_sel_hi:[1,1,1]
	v_pk_fma_f32 v[18:19], v[50:51], v[94:95], v[18:19] op_sel:[0,1,0] op_sel_hi:[1,1,1]
	v_pk_fma_f32 v[20:21], v[52:53], v[94:95], v[20:21] op_sel:[0,1,0] op_sel_hi:[1,1,1]
	v_pk_fma_f32 v[22:23], v[54:55], v[94:95], v[22:23] op_sel:[0,1,0] op_sel_hi:[1,1,1]
	v_pk_fma_f32 v[24:25], v[56:57], v[94:95], v[24:25] op_sel:[0,1,0] op_sel_hi:[1,1,1]
	v_pk_fma_f32 v[26:27], v[58:59], v[94:95], v[26:27] op_sel:[0,1,0] op_sel_hi:[1,1,1]
	v_pk_fma_f32 v[28:29], v[60:61], v[94:95], v[28:29] op_sel:[0,1,0] op_sel_hi:[1,1,1]
	v_pk_fma_f32 v[30:31], v[62:63], v[94:95], v[30:31] op_sel:[0,1,0] op_sel_hi:[1,1,1]
	ds_read_b128 v[48:51], v7 offset:6208
	ds_read_b128 v[52:55], v7 offset:6224
	ds_read_b128 v[56:59], v7 offset:6240
	ds_read_b128 v[60:63], v7 offset:6256
	s_waitcnt vmcnt(31) lgkmcnt(4)
	v_pk_fma_f32 v[16:17], v[32:33], v[96:97], v[16:17] op_sel_hi:[1,0,1]
	v_pk_fma_f32 v[18:19], v[34:35], v[96:97], v[18:19] op_sel_hi:[1,0,1]
	v_pk_fma_f32 v[20:21], v[36:37], v[96:97], v[20:21] op_sel_hi:[1,0,1]
	v_pk_fma_f32 v[22:23], v[38:39], v[96:97], v[22:23] op_sel_hi:[1,0,1]
	v_pk_fma_f32 v[24:25], v[40:41], v[96:97], v[24:25] op_sel_hi:[1,0,1]
	v_pk_fma_f32 v[26:27], v[42:43], v[96:97], v[26:27] op_sel_hi:[1,0,1]
	v_pk_fma_f32 v[28:29], v[44:45], v[96:97], v[28:29] op_sel_hi:[1,0,1]
	v_pk_fma_f32 v[30:31], v[46:47], v[96:97], v[30:31] op_sel_hi:[1,0,1]
	ds_read_b128 v[32:35], v7 offset:6272
	ds_read_b128 v[36:39], v7 offset:6288
	ds_read_b128 v[40:43], v7 offset:6304
	ds_read_b128 v[44:47], v7 offset:6320
	s_waitcnt vmcnt(30) lgkmcnt(4)
	v_pk_fma_f32 v[16:17], v[48:49], v[96:97], v[16:17] op_sel:[0,1,0] op_sel_hi:[1,1,1]
	v_pk_fma_f32 v[18:19], v[50:51], v[96:97], v[18:19] op_sel:[0,1,0] op_sel_hi:[1,1,1]
	v_pk_fma_f32 v[20:21], v[52:53], v[96:97], v[20:21] op_sel:[0,1,0] op_sel_hi:[1,1,1]
	v_pk_fma_f32 v[22:23], v[54:55], v[96:97], v[22:23] op_sel:[0,1,0] op_sel_hi:[1,1,1]
	v_pk_fma_f32 v[24:25], v[56:57], v[96:97], v[24:25] op_sel:[0,1,0] op_sel_hi:[1,1,1]
	v_pk_fma_f32 v[26:27], v[58:59], v[96:97], v[26:27] op_sel:[0,1,0] op_sel_hi:[1,1,1]
	v_pk_fma_f32 v[28:29], v[60:61], v[96:97], v[28:29] op_sel:[0,1,0] op_sel_hi:[1,1,1]
	v_pk_fma_f32 v[30:31], v[62:63], v[96:97], v[30:31] op_sel:[0,1,0] op_sel_hi:[1,1,1]
	ds_read_b128 v[48:51], v7 offset:6336
	ds_read_b128 v[52:55], v7 offset:6352
	ds_read_b128 v[56:59], v7 offset:6368
	ds_read_b128 v[60:63], v7 offset:6384
	s_waitcnt vmcnt(29) lgkmcnt(4)
	v_pk_fma_f32 v[16:17], v[32:33], v[98:99], v[16:17] op_sel_hi:[1,0,1]
	v_pk_fma_f32 v[18:19], v[34:35], v[98:99], v[18:19] op_sel_hi:[1,0,1]
	v_pk_fma_f32 v[20:21], v[36:37], v[98:99], v[20:21] op_sel_hi:[1,0,1]
	v_pk_fma_f32 v[22:23], v[38:39], v[98:99], v[22:23] op_sel_hi:[1,0,1]
	v_pk_fma_f32 v[24:25], v[40:41], v[98:99], v[24:25] op_sel_hi:[1,0,1]
	v_pk_fma_f32 v[26:27], v[42:43], v[98:99], v[26:27] op_sel_hi:[1,0,1]
	v_pk_fma_f32 v[28:29], v[44:45], v[98:99], v[28:29] op_sel_hi:[1,0,1]
	v_pk_fma_f32 v[30:31], v[46:47], v[98:99], v[30:31] op_sel_hi:[1,0,1]
	ds_read_b128 v[32:35], v7 offset:6400
	ds_read_b128 v[36:39], v7 offset:6416
	ds_read_b128 v[40:43], v7 offset:6432
	ds_read_b128 v[44:47], v7 offset:6448
	s_waitcnt vmcnt(28) lgkmcnt(4)
	v_pk_fma_f32 v[16:17], v[48:49], v[98:99], v[16:17] op_sel:[0,1,0] op_sel_hi:[1,1,1]
	v_pk_fma_f32 v[18:19], v[50:51], v[98:99], v[18:19] op_sel:[0,1,0] op_sel_hi:[1,1,1]
	v_pk_fma_f32 v[20:21], v[52:53], v[98:99], v[20:21] op_sel:[0,1,0] op_sel_hi:[1,1,1]
	v_pk_fma_f32 v[22:23], v[54:55], v[98:99], v[22:23] op_sel:[0,1,0] op_sel_hi:[1,1,1]
	v_pk_fma_f32 v[24:25], v[56:57], v[98:99], v[24:25] op_sel:[0,1,0] op_sel_hi:[1,1,1]
	v_pk_fma_f32 v[26:27], v[58:59], v[98:99], v[26:27] op_sel:[0,1,0] op_sel_hi:[1,1,1]
	v_pk_fma_f32 v[28:29], v[60:61], v[98:99], v[28:29] op_sel:[0,1,0] op_sel_hi:[1,1,1]
	v_pk_fma_f32 v[30:31], v[62:63], v[98:99], v[30:31] op_sel:[0,1,0] op_sel_hi:[1,1,1]
	ds_read_b128 v[48:51], v7 offset:6464
	ds_read_b128 v[52:55], v7 offset:6480
	ds_read_b128 v[56:59], v7 offset:6496
	ds_read_b128 v[60:63], v7 offset:6512
	s_waitcnt vmcnt(27) lgkmcnt(4)
; #define LAS __attribute__((address_space(3)))
; __device__ __forceinline__ void ph_mod(const float* cp, const float* cs, const float* w_ada, const float* b_ada, float* MOD, float* MISC,
;                                        const float* lq1, const float* lk1, const float* lq2, const float* lk2, LAS unsigned char* lds, int G, int tid) {
;     ...
; #pragma unroll 16
;         for (int kk = 0; kk < 128; ++kk) { const int k = k0 + kk; const float wv = w_ada[(size_t)k * 9216 + col];
;             const f32x4 s0 = *(const LAS f32x4*)(scT + k * 16), s1 = *(const LAS f32x4*)(scT + k * 16 + 4), s2 = *(const LAS f32x4*)(scT + k * 16 + 8), s3 = *(const LAS f32x4*)(scT + k * 16 + 12);
;             acc[0] += s0[0] * wv; acc[1] += s0[1] * wv; acc[2] += s0[2] * wv; acc[3] += s0[3] * wv; acc[4] += s1[0] * wv; acc[5] += s1[1] * wv; acc[6] += s1[2] * wv; acc[7] += s1[3] * wv;
;             acc[8] += s2[0] * wv; acc[9] += s2[1] * wv; acc[10] += s2[2] * wv; acc[11] += s2[3] * wv; acc[12] += s3[0] * wv; acc[13] += s3[1] * wv; acc[14] += s3[2] * wv; acc[15] += s3[3] * wv; }
	v_pk_fma_f32 v[16:17], v[32:33], v[100:101], v[16:17] op_sel_hi:[1,0,1]
	v_pk_fma_f32 v[18:19], v[34:35], v[100:101], v[18:19] op_sel_hi:[1,0,1]
	v_pk_fma_f32 v[20:21], v[36:37], v[100:101], v[20:21] op_sel_hi:[1,0,1]
	v_pk_fma_f32 v[22:23], v[38:39], v[100:101], v[22:23] op_sel_hi:[1,0,1]
	v_pk_fma_f32 v[24:25], v[40:41], v[100:101], v[24:25] op_sel_hi:[1,0,1]
	v_pk_fma_f32 v[26:27], v[42:43], v[100:101], v[26:27] op_sel_hi:[1,0,1]
	v_pk_fma_f32 v[28:29], v[44:45], v[100:101], v[28:29] op_sel_hi:[1,0,1]
	v_pk_fma_f32 v[30:31], v[46:47], v[100:101], v[30:31] op_sel_hi:[1,0,1]
	ds_read_b128 v[32:35], v7 offset:6528
	ds_read_b128 v[36:39], v7 offset:6544
	ds_read_b128 v[40:43], v7 offset:6560
	ds_read_b128 v[44:47], v7 offset:6576
	s_waitcnt vmcnt(26) lgkmcnt(4)
	v_pk_fma_f32 v[16:17], v[48:49], v[100:101], v[16:17] op_sel:[0,1,0] op_sel_hi:[1,1,1]
	v_pk_fma_f32 v[18:19], v[50:51], v[100:101], v[18:19] op_sel:[0,1,0] op_sel_hi:[1,1,1]
	v_pk_fma_f32 v[20:21], v[52:53], v[100:101], v[20:21] op_sel:[0,1,0] op_sel_hi:[1,1,1]
	v_pk_fma_f32 v[22:23], v[54:55], v[100:101], v[22:23] op_sel:[0,1,0] op_sel_hi:[1,1,1]
	v_pk_fma_f32 v[24:25], v[56:57], v[100:101], v[24:25] op_sel:[0,1,0] op_sel_hi:[1,1,1]
	v_pk_fma_f32 v[26:27], v[58:59], v[100:101], v[26:27] op_sel:[0,1,0] op_sel_hi:[1,1,1]
	v_pk_fma_f32 v[28:29], v[60:61], v[100:101], v[28:29] op_sel:[0,1,0] op_sel_hi:[1,1,1]
	v_pk_fma_f32 v[30:31], v[62:63], v[100:101], v[30:31] op_sel:[0,1,0] op_sel_hi:[1,1,1]
	ds_read_b128 v[48:51], v7 offset:6592
	ds_read_b128 v[52:55], v7 offset:6608
	ds_read_b128 v[56:59], v7 offset:6624
	ds_read_b128 v[60:63], v7 offset:6640
	s_waitcnt vmcnt(25) lgkmcnt(4)
	v_pk_fma_f32 v[16:17], v[32:33], v[102:103], v[16:17] op_sel_hi:[1,0,1]
	v_pk_fma_f32 v[18:19], v[34:35], v[102:103], v[18:19] op_sel_hi:[1,0,1]
	v_pk_fma_f32 v[20:21], v[36:37], v[102:103], v[20:21] op_sel_hi:[1,0,1]
	v_pk_fma_f32 v[22:23], v[38:39], v[102:103], v[22:23] op_sel_hi:[1,0,1]
	v_pk_fma_f32 v[24:25], v[40:41], v[102:103], v[24:25] op_sel_hi:[1,0,1]
	v_pk_fma_f32 v[26:27], v[42:43], v[102:103], v[26:27] op_sel_hi:[1,0,1]
	v_pk_fma_f32 v[28:29], v[44:45], v[102:103], v[28:29] op_sel_hi:[1,0,1]
	v_pk_fma_f32 v[30:31], v[46:47], v[102:103], v[30:31] op_sel_hi:[1,0,1]
	ds_read_b128 v[32:35], v7 offset:6656
	ds_read_b128 v[36:39], v7 offset:6672
	ds_read_b128 v[40:43], v7 offset:6688
	ds_read_b128 v[44:47], v7 offset:6704
	s_waitcnt vmcnt(24) lgkmcnt(4)
	v_pk_fma_f32 v[16:17], v[48:49], v[102:103], v[16:17] op_sel:[0,1,0] op_sel_hi:[1,1,1]
	v_pk_fma_f32 v[18:19], v[50:51], v[102:103], v[18:19] op_sel:[0,1,0] op_sel_hi:[1,1,1]
	v_pk_fma_f32 v[20:21], v[52:53], v[102:103], v[20:21] op_sel:[0,1,0] op_sel_hi:[1,1,1]
	v_pk_fma_f32 v[22:23], v[54:55], v[102:103], v[22:23] op_sel:[0,1,0] op_sel_hi:[1,1,1]
	v_pk_fma_f32 v[24:25], v[56:57], v[102:103], v[24:25] op_sel:[0,1,0] op_sel_hi:[1,1,1]
	v_pk_fma_f32 v[26:27], v[58:59], v[102:103], v[26:27] op_sel:[0,1,0] op_sel_hi:[1,1,1]
	v_pk_fma_f32 v[28:29], v[60:61], v[102:103], v[28:29] op_sel:[0,1,0] op_sel_hi:[1,1,1]
	v_pk_fma_f32 v[30:31], v[62:63], v[102:103], v[30:31] op_sel:[0,1,0] op_sel_hi:[1,1,1]
	ds_read_b128 v[48:51], v7 offset:6720
	ds_read_b128 v[52:55], v7 offset:6736
	ds_read_b128 v[56:59], v7 offset:6752
	ds_read_b128 v[60:63], v7 offset:6768
	s_waitcnt vmcnt(23) lgkmcnt(4)
	v_pk_fma_f32 v[16:17], v[32:33], v[104:105], v[16:17] op_sel_hi:[1,0,1]
	v_pk_fma_f32 v[18:19], v[34:35], v[104:105], v[18:19] op_sel_hi:[1,0,1]
	v_pk_fma_f32 v[20:21], v[36:37], v[104:105], v[20:21] op_sel_hi:[1,0,1]
	v_pk_fma_f32 v[22:23], v[38:39], v[104:105], v[22:23] op_sel_hi:[1,0,1]
	v_pk_fma_f32 v[24:25], v[40:41], v[104:105], v[24:25] op_sel_hi:[1,0,1]
	v_pk_fma_f32 v[26:27], v[42:43], v[104:105], v[26:27] op_sel_hi:[1,0,1]
	v_pk_fma_f32 v[28:29], v[44:45], v[104:105], v[28:29] op_sel_hi:[1,0,1]
	v_pk_fma_f32 v[30:31], v[46:47], v[104:105], v[30:31] op_sel_hi:[1,0,1]
	ds_read_b128 v[32:35], v7 offset:6784
	ds_read_b128 v[36:39], v7 offset:6800
	ds_read_b128 v[40:43], v7 offset:6816
	ds_read_b128 v[44:47], v7 offset:6832
	s_waitcnt vmcnt(22) lgkmcnt(4)
	v_pk_fma_f32 v[16:17], v[48:49], v[104:105], v[16:17] op_sel:[0,1,0] op_sel_hi:[1,1,1]
	v_pk_fma_f32 v[18:19], v[50:51], v[104:105], v[18:19] op_sel:[0,1,0] op_sel_hi:[1,1,1]
	v_pk_fma_f32 v[20:21], v[52:53], v[104:105], v[20:21] op_sel:[0,1,0] op_sel_hi:[1,1,1]
	v_pk_fma_f32 v[22:23], v[54:55], v[104:105], v[22:23] op_sel:[0,1,0] op_sel_hi:[1,1,1]
	v_pk_fma_f32 v[24:25], v[56:57], v[104:105], v[24:25] op_sel:[0,1,0] op_sel_hi:[1,1,1]
	v_pk_fma_f32 v[26:27], v[58:59], v[104:105], v[26:27] op_sel:[0,1,0] op_sel_hi:[1,1,1]
	v_pk_fma_f32 v[28:29], v[60:61], v[104:105], v[28:29] op_sel:[0,1,0] op_sel_hi:[1,1,1]
	v_pk_fma_f32 v[30:31], v[62:63], v[104:105], v[30:31] op_sel:[0,1,0] op_sel_hi:[1,1,1]
	ds_read_b128 v[48:51], v7 offset:6848
	ds_read_b128 v[52:55], v7 offset:6864
	ds_read_b128 v[56:59], v7 offset:6880
	ds_read_b128 v[60:63], v7 offset:6896
	s_waitcnt vmcnt(21) lgkmcnt(4)
	v_pk_fma_f32 v[16:17], v[32:33], v[106:107], v[16:17] op_sel_hi:[1,0,1]
	v_pk_fma_f32 v[18:19], v[34:35], v[106:107], v[18:19] op_sel_hi:[1,0,1]
	v_pk_fma_f32 v[20:21], v[36:37], v[106:107], v[20:21] op_sel_hi:[1,0,1]
	v_pk_fma_f32 v[22:23], v[38:39], v[106:107], v[22:23] op_sel_hi:[1,0,1]
	v_pk_fma_f32 v[24:25], v[40:41], v[106:107], v[24:25] op_sel_hi:[1,0,1]
	v_pk_fma_f32 v[26:27], v[42:43], v[106:107], v[26:27] op_sel_hi:[1,0,1]
	v_pk_fma_f32 v[28:29], v[44:45], v[106:107], v[28:29] op_sel_hi:[1,0,1]
	v_pk_fma_f32 v[30:31], v[46:47], v[106:107], v[30:31] op_sel_hi:[1,0,1]
	ds_read_b128 v[32:35], v7 offset:6912
	ds_read_b128 v[36:39], v7 offset:6928
	ds_read_b128 v[40:43], v7 offset:6944
	ds_read_b128 v[44:47], v7 offset:6960
	s_waitcnt vmcnt(20) lgkmcnt(4)
; #define LAS __attribute__((address_space(3)))
; __device__ __forceinline__ void ph_mod(const float* cp, const float* cs, const float* w_ada, const float* b_ada, float* MOD, float* MISC,
;                                        const float* lq1, const float* lk1, const float* lq2, const float* lk2, LAS unsigned char* lds, int G, int tid) {
;     ...
;         for (int kk = 0; kk < 128; ++kk) { const int k = k0 + kk; const float wv = w_ada[(size_t)k * 9216 + col];
;             const f32x4 s0 = *(const LAS f32x4*)(scT + k * 16), s1 = *(const LAS f32x4*)(scT + k * 16 + 4), s2 = *(const LAS f32x4*)(scT + k * 16 + 8), s3 = *(const LAS f32x4*)(scT + k * 16 + 12);
;             acc[0] += s0[0] * wv; acc[1] += s0[1] * wv; acc[2] += s0[2] * wv; acc[3] += s0[3] * wv; acc[4] += s1[0] * wv; acc[5] += s1[1] * wv; acc[6] += s1[2] * wv; acc[7] += s1[3] * wv;
;             acc[8] += s2[0] * wv; acc[9] += s2[1] * wv; acc[10] += s2[2] * wv; acc[11] += s2[3] * wv; acc[12] += s3[0] * wv; acc[13] += s3[1] * wv; acc[14] += s3[2] * wv; acc[15] += s3[3] * wv; }
	v_pk_fma_f32 v[16:17], v[48:49], v[106:107], v[16:17] op_sel:[0,1,0] op_sel_hi:[1,1,1]
	v_pk_fma_f32 v[18:19], v[50:51], v[106:107], v[18:19] op_sel:[0,1,0] op_sel_hi:[1,1,1]
	v_pk_fma_f32 v[20:21], v[52:53], v[106:107], v[20:21] op_sel:[0,1,0] op_sel_hi:[1,1,1]
	v_pk_fma_f32 v[22:23], v[54:55], v[106:107], v[22:23] op_sel:[0,1,0] op_sel_hi:[1,1,1]
	v_pk_fma_f32 v[24:25], v[56:57], v[106:107], v[24:25] op_sel:[0,1,0] op_sel_hi:[1,1,1]
	v_pk_fma_f32 v[26:27], v[58:59], v[106:107], v[26:27] op_sel:[0,1,0] op_sel_hi:[1,1,1]
	v_pk_fma_f32 v[28:29], v[60:61], v[106:107], v[28:29] op_sel:[0,1,0] op_sel_hi:[1,1,1]
	v_pk_fma_f32 v[30:31], v[62:63], v[106:107], v[30:31] op_sel:[0,1,0] op_sel_hi:[1,1,1]
	ds_read_b128 v[48:51], v7 offset:6976
	ds_read_b128 v[52:55], v7 offset:6992
	ds_read_b128 v[56:59], v7 offset:7008
	ds_read_b128 v[60:63], v7 offset:7024
	s_waitcnt vmcnt(19) lgkmcnt(4)
	v_pk_fma_f32 v[16:17], v[32:33], v[108:109], v[16:17] op_sel_hi:[1,0,1]
	v_pk_fma_f32 v[18:19], v[34:35], v[108:109], v[18:19] op_sel_hi:[1,0,1]
	v_pk_fma_f32 v[20:21], v[36:37], v[108:109], v[20:21] op_sel_hi:[1,0,1]
	v_pk_fma_f32 v[22:23], v[38:39], v[108:109], v[22:23] op_sel_hi:[1,0,1]
	v_pk_fma_f32 v[24:25], v[40:41], v[108:109], v[24:25] op_sel_hi:[1,0,1]
	v_pk_fma_f32 v[26:27], v[42:43], v[108:109], v[26:27] op_sel_hi:[1,0,1]
	v_pk_fma_f32 v[28:29], v[44:45], v[108:109], v[28:29] op_sel_hi:[1,0,1]
	v_pk_fma_f32 v[30:31], v[46:47], v[108:109], v[30:31] op_sel_hi:[1,0,1]
	ds_read_b128 v[32:35], v7 offset:7040
	ds_read_b128 v[36:39], v7 offset:7056
	ds_read_b128 v[40:43], v7 offset:7072
	ds_read_b128 v[44:47], v7 offset:7088
	s_waitcnt vmcnt(18) lgkmcnt(4)
	v_pk_fma_f32 v[16:17], v[48:49], v[108:109], v[16:17] op_sel:[0,1,0] op_sel_hi:[1,1,1]
	v_pk_fma_f32 v[18:19], v[50:51], v[108:109], v[18:19] op_sel:[0,1,0] op_sel_hi:[1,1,1]
	v_pk_fma_f32 v[20:21], v[52:53], v[108:109], v[20:21] op_sel:[0,1,0] op_sel_hi:[1,1,1]
	v_pk_fma_f32 v[22:23], v[54:55], v[108:109], v[22:23] op_sel:[0,1,0] op_sel_hi:[1,1,1]
	v_pk_fma_f32 v[24:25], v[56:57], v[108:109], v[24:25] op_sel:[0,1,0] op_sel_hi:[1,1,1]
	v_pk_fma_f32 v[26:27], v[58:59], v[108:109], v[26:27] op_sel:[0,1,0] op_sel_hi:[1,1,1]
	v_pk_fma_f32 v[28:29], v[60:61], v[108:109], v[28:29] op_sel:[0,1,0] op_sel_hi:[1,1,1]
	v_pk_fma_f32 v[30:31], v[62:63], v[108:109], v[30:31] op_sel:[0,1,0] op_sel_hi:[1,1,1]
	ds_read_b128 v[48:51], v7 offset:7104
	ds_read_b128 v[52:55], v7 offset:7120
	ds_read_b128 v[56:59], v7 offset:7136
	ds_read_b128 v[60:63], v7 offset:7152
	s_waitcnt vmcnt(17) lgkmcnt(4)
	v_pk_fma_f32 v[16:17], v[32:33], v[110:111], v[16:17] op_sel_hi:[1,0,1]
	v_pk_fma_f32 v[18:19], v[34:35], v[110:111], v[18:19] op_sel_hi:[1,0,1]
	v_pk_fma_f32 v[20:21], v[36:37], v[110:111], v[20:21] op_sel_hi:[1,0,1]
	v_pk_fma_f32 v[22:23], v[38:39], v[110:111], v[22:23] op_sel_hi:[1,0,1]
	v_pk_fma_f32 v[24:25], v[40:41], v[110:111], v[24:25] op_sel_hi:[1,0,1]
	v_pk_fma_f32 v[26:27], v[42:43], v[110:111], v[26:27] op_sel_hi:[1,0,1]
	v_pk_fma_f32 v[28:29], v[44:45], v[110:111], v[28:29] op_sel_hi:[1,0,1]
	v_pk_fma_f32 v[30:31], v[46:47], v[110:111], v[30:31] op_sel_hi:[1,0,1]
	ds_read_b128 v[32:35], v7 offset:7168
	ds_read_b128 v[36:39], v7 offset:7184
	ds_read_b128 v[40:43], v7 offset:7200
	ds_read_b128 v[44:47], v7 offset:7216
	s_waitcnt vmcnt(16) lgkmcnt(4)
	v_pk_fma_f32 v[16:17], v[48:49], v[110:111], v[16:17] op_sel:[0,1,0] op_sel_hi:[1,1,1]
	v_pk_fma_f32 v[18:19], v[50:51], v[110:111], v[18:19] op_sel:[0,1,0] op_sel_hi:[1,1,1]
	v_pk_fma_f32 v[20:21], v[52:53], v[110:111], v[20:21] op_sel:[0,1,0] op_sel_hi:[1,1,1]
	v_pk_fma_f32 v[22:23], v[54:55], v[110:111], v[22:23] op_sel:[0,1,0] op_sel_hi:[1,1,1]
	v_pk_fma_f32 v[24:25], v[56:57], v[110:111], v[24:25] op_sel:[0,1,0] op_sel_hi:[1,1,1]
	v_pk_fma_f32 v[26:27], v[58:59], v[110:111], v[26:27] op_sel:[0,1,0] op_sel_hi:[1,1,1]
	v_pk_fma_f32 v[28:29], v[60:61], v[110:111], v[28:29] op_sel:[0,1,0] op_sel_hi:[1,1,1]
	v_pk_fma_f32 v[30:31], v[62:63], v[110:111], v[30:31] op_sel:[0,1,0] op_sel_hi:[1,1,1]
	ds_read_b128 v[48:51], v7 offset:7232
	ds_read_b128 v[52:55], v7 offset:7248
	ds_read_b128 v[56:59], v7 offset:7264
	ds_read_b128 v[60:63], v7 offset:7280
	s_waitcnt vmcnt(15) lgkmcnt(4)
	v_pk_fma_f32 v[16:17], v[32:33], v[112:113], v[16:17] op_sel_hi:[1,0,1]
	v_pk_fma_f32 v[18:19], v[34:35], v[112:113], v[18:19] op_sel_hi:[1,0,1]
	v_pk_fma_f32 v[20:21], v[36:37], v[112:113], v[20:21] op_sel_hi:[1,0,1]
	v_pk_fma_f32 v[22:23], v[38:39], v[112:113], v[22:23] op_sel_hi:[1,0,1]
	v_pk_fma_f32 v[24:25], v[40:41], v[112:113], v[24:25] op_sel_hi:[1,0,1]
	v_pk_fma_f32 v[26:27], v[42:43], v[112:113], v[26:27] op_sel_hi:[1,0,1]
	v_pk_fma_f32 v[28:29], v[44:45], v[112:113], v[28:29] op_sel_hi:[1,0,1]
	v_pk_fma_f32 v[30:31], v[46:47], v[112:113], v[30:31] op_sel_hi:[1,0,1]
	ds_read_b128 v[32:35], v7 offset:7296
	ds_read_b128 v[36:39], v7 offset:7312
	ds_read_b128 v[40:43], v7 offset:7328
	ds_read_b128 v[44:47], v7 offset:7344
	s_waitcnt vmcnt(14) lgkmcnt(4)
	v_pk_fma_f32 v[16:17], v[48:49], v[112:113], v[16:17] op_sel:[0,1,0] op_sel_hi:[1,1,1]
	v_pk_fma_f32 v[18:19], v[50:51], v[112:113], v[18:19] op_sel:[0,1,0] op_sel_hi:[1,1,1]
	v_pk_fma_f32 v[20:21], v[52:53], v[112:113], v[20:21] op_sel:[0,1,0] op_sel_hi:[1,1,1]
	v_pk_fma_f32 v[22:23], v[54:55], v[112:113], v[22:23] op_sel:[0,1,0] op_sel_hi:[1,1,1]
	v_pk_fma_f32 v[24:25], v[56:57], v[112:113], v[24:25] op_sel:[0,1,0] op_sel_hi:[1,1,1]
	v_pk_fma_f32 v[26:27], v[58:59], v[112:113], v[26:27] op_sel:[0,1,0] op_sel_hi:[1,1,1]
	v_pk_fma_f32 v[28:29], v[60:61], v[112:113], v[28:29] op_sel:[0,1,0] op_sel_hi:[1,1,1]
	v_pk_fma_f32 v[30:31], v[62:63], v[112:113], v[30:31] op_sel:[0,1,0] op_sel_hi:[1,1,1]
	ds_read_b128 v[48:51], v7 offset:7360
	ds_read_b128 v[52:55], v7 offset:7376
	ds_read_b128 v[56:59], v7 offset:7392
	ds_read_b128 v[60:63], v7 offset:7408
	s_waitcnt vmcnt(13) lgkmcnt(4)
; #define LAS __attribute__((address_space(3)))
; __device__ __forceinline__ void ph_mod(const float* cp, const float* cs, const float* w_ada, const float* b_ada, float* MOD, float* MISC,
;                                        const float* lq1, const float* lk1, const float* lq2, const float* lk2, LAS unsigned char* lds, int G, int tid) {
;     ...
;         for (int kk = 0; kk < 128; ++kk) { const int k = k0 + kk; const float wv = w_ada[(size_t)k * 9216 + col];
;             const f32x4 s0 = *(const LAS f32x4*)(scT + k * 16), s1 = *(const LAS f32x4*)(scT + k * 16 + 4), s2 = *(const LAS f32x4*)(scT + k * 16 + 8), s3 = *(const LAS f32x4*)(scT + k * 16 + 12);
;             acc[0] += s0[0] * wv; acc[1] += s0[1] * wv; acc[2] += s0[2] * wv; acc[3] += s0[3] * wv; acc[4] += s1[0] * wv; acc[5] += s1[1] * wv; acc[6] += s1[2] * wv; acc[7] += s1[3] * wv;
;             acc[8] += s2[0] * wv; acc[9] += s2[1] * wv; acc[10] += s2[2] * wv; acc[11] += s2[3] * wv; acc[12] += s3[0] * wv; acc[13] += s3[1] * wv; acc[14] += s3[2] * wv; acc[15] += s3[3] * wv; }
	v_pk_fma_f32 v[16:17], v[32:33], v[114:115], v[16:17] op_sel_hi:[1,0,1]
	v_pk_fma_f32 v[18:19], v[34:35], v[114:115], v[18:19] op_sel_hi:[1,0,1]
	v_pk_fma_f32 v[20:21], v[36:37], v[114:115], v[20:21] op_sel_hi:[1,0,1]
	v_pk_fma_f32 v[22:23], v[38:39], v[114:115], v[22:23] op_sel_hi:[1,0,1]
	v_pk_fma_f32 v[24:25], v[40:41], v[114:115], v[24:25] op_sel_hi:[1,0,1]
	v_pk_fma_f32 v[26:27], v[42:43], v[114:115], v[26:27] op_sel_hi:[1,0,1]
	v_pk_fma_f32 v[28:29], v[44:45], v[114:115], v[28:29] op_sel_hi:[1,0,1]
	v_pk_fma_f32 v[30:31], v[46:47], v[114:115], v[30:31] op_sel_hi:[1,0,1]
	ds_read_b128 v[32:35], v7 offset:7424
	ds_read_b128 v[36:39], v7 offset:7440
	ds_read_b128 v[40:43], v7 offset:7456
	ds_read_b128 v[44:47], v7 offset:7472
	s_waitcnt vmcnt(12) lgkmcnt(4)
	v_pk_fma_f32 v[16:17], v[48:49], v[114:115], v[16:17] op_sel:[0,1,0] op_sel_hi:[1,1,1]
	v_pk_fma_f32 v[18:19], v[50:51], v[114:115], v[18:19] op_sel:[0,1,0] op_sel_hi:[1,1,1]
	v_pk_fma_f32 v[20:21], v[52:53], v[114:115], v[20:21] op_sel:[0,1,0] op_sel_hi:[1,1,1]
	v_pk_fma_f32 v[22:23], v[54:55], v[114:115], v[22:23] op_sel:[0,1,0] op_sel_hi:[1,1,1]
	v_pk_fma_f32 v[24:25], v[56:57], v[114:115], v[24:25] op_sel:[0,1,0] op_sel_hi:[1,1,1]
	v_pk_fma_f32 v[26:27], v[58:59], v[114:115], v[26:27] op_sel:[0,1,0] op_sel_hi:[1,1,1]
	v_pk_fma_f32 v[28:29], v[60:61], v[114:115], v[28:29] op_sel:[0,1,0] op_sel_hi:[1,1,1]
	v_pk_fma_f32 v[30:31], v[62:63], v[114:115], v[30:31] op_sel:[0,1,0] op_sel_hi:[1,1,1]
	ds_read_b128 v[48:51], v7 offset:7488
	ds_read_b128 v[52:55], v7 offset:7504
	ds_read_b128 v[56:59], v7 offset:7520
	ds_read_b128 v[60:63], v7 offset:7536
	s_waitcnt vmcnt(11) lgkmcnt(4)
	v_pk_fma_f32 v[16:17], v[32:33], v[116:117], v[16:17] op_sel_hi:[1,0,1]
	v_pk_fma_f32 v[18:19], v[34:35], v[116:117], v[18:19] op_sel_hi:[1,0,1]
	v_pk_fma_f32 v[20:21], v[36:37], v[116:117], v[20:21] op_sel_hi:[1,0,1]
	v_pk_fma_f32 v[22:23], v[38:39], v[116:117], v[22:23] op_sel_hi:[1,0,1]
	v_pk_fma_f32 v[24:25], v[40:41], v[116:117], v[24:25] op_sel_hi:[1,0,1]
	v_pk_fma_f32 v[26:27], v[42:43], v[116:117], v[26:27] op_sel_hi:[1,0,1]
	v_pk_fma_f32 v[28:29], v[44:45], v[116:117], v[28:29] op_sel_hi:[1,0,1]
	v_pk_fma_f32 v[30:31], v[46:47], v[116:117], v[30:31] op_sel_hi:[1,0,1]
	ds_read_b128 v[32:35], v7 offset:7552
	ds_read_b128 v[36:39], v7 offset:7568
	ds_read_b128 v[40:43], v7 offset:7584
	ds_read_b128 v[44:47], v7 offset:7600
	s_waitcnt vmcnt(10) lgkmcnt(4)
	v_pk_fma_f32 v[16:17], v[48:49], v[116:117], v[16:17] op_sel:[0,1,0] op_sel_hi:[1,1,1]
	v_pk_fma_f32 v[18:19], v[50:51], v[116:117], v[18:19] op_sel:[0,1,0] op_sel_hi:[1,1,1]
	v_pk_fma_f32 v[20:21], v[52:53], v[116:117], v[20:21] op_sel:[0,1,0] op_sel_hi:[1,1,1]
	v_pk_fma_f32 v[22:23], v[54:55], v[116:117], v[22:23] op_sel:[0,1,0] op_sel_hi:[1,1,1]
	v_pk_fma_f32 v[24:25], v[56:57], v[116:117], v[24:25] op_sel:[0,1,0] op_sel_hi:[1,1,1]
	v_pk_fma_f32 v[26:27], v[58:59], v[116:117], v[26:27] op_sel:[0,1,0] op_sel_hi:[1,1,1]
	v_pk_fma_f32 v[28:29], v[60:61], v[116:117], v[28:29] op_sel:[0,1,0] op_sel_hi:[1,1,1]
	v_pk_fma_f32 v[30:31], v[62:63], v[116:117], v[30:31] op_sel:[0,1,0] op_sel_hi:[1,1,1]
	ds_read_b128 v[48:51], v7 offset:7616
	ds_read_b128 v[52:55], v7 offset:7632
	ds_read_b128 v[56:59], v7 offset:7648
	ds_read_b128 v[60:63], v7 offset:7664
	s_waitcnt vmcnt(9) lgkmcnt(4)
	v_pk_fma_f32 v[16:17], v[32:33], v[118:119], v[16:17] op_sel_hi:[1,0,1]
	v_pk_fma_f32 v[18:19], v[34:35], v[118:119], v[18:19] op_sel_hi:[1,0,1]
	v_pk_fma_f32 v[20:21], v[36:37], v[118:119], v[20:21] op_sel_hi:[1,0,1]
	v_pk_fma_f32 v[22:23], v[38:39], v[118:119], v[22:23] op_sel_hi:[1,0,1]
	v_pk_fma_f32 v[24:25], v[40:41], v[118:119], v[24:25] op_sel_hi:[1,0,1]
	v_pk_fma_f32 v[26:27], v[42:43], v[118:119], v[26:27] op_sel_hi:[1,0,1]
	v_pk_fma_f32 v[28:29], v[44:45], v[118:119], v[28:29] op_sel_hi:[1,0,1]
	v_pk_fma_f32 v[30:31], v[46:47], v[118:119], v[30:31] op_sel_hi:[1,0,1]
	ds_read_b128 v[32:35], v7 offset:7680
	ds_read_b128 v[36:39], v7 offset:7696
	ds_read_b128 v[40:43], v7 offset:7712
	ds_read_b128 v[44:47], v7 offset:7728
	s_waitcnt vmcnt(8) lgkmcnt(4)
	v_pk_fma_f32 v[16:17], v[48:49], v[118:119], v[16:17] op_sel:[0,1,0] op_sel_hi:[1,1,1]
	v_pk_fma_f32 v[18:19], v[50:51], v[118:119], v[18:19] op_sel:[0,1,0] op_sel_hi:[1,1,1]
	v_pk_fma_f32 v[20:21], v[52:53], v[118:119], v[20:21] op_sel:[0,1,0] op_sel_hi:[1,1,1]
	v_pk_fma_f32 v[22:23], v[54:55], v[118:119], v[22:23] op_sel:[0,1,0] op_sel_hi:[1,1,1]
	v_pk_fma_f32 v[24:25], v[56:57], v[118:119], v[24:25] op_sel:[0,1,0] op_sel_hi:[1,1,1]
	v_pk_fma_f32 v[26:27], v[58:59], v[118:119], v[26:27] op_sel:[0,1,0] op_sel_hi:[1,1,1]
	v_pk_fma_f32 v[28:29], v[60:61], v[118:119], v[28:29] op_sel:[0,1,0] op_sel_hi:[1,1,1]
	v_pk_fma_f32 v[30:31], v[62:63], v[118:119], v[30:31] op_sel:[0,1,0] op_sel_hi:[1,1,1]
	ds_read_b128 v[48:51], v7 offset:7744
	ds_read_b128 v[52:55], v7 offset:7760
	ds_read_b128 v[56:59], v7 offset:7776
	ds_read_b128 v[60:63], v7 offset:7792
	s_waitcnt vmcnt(7) lgkmcnt(4)
	v_pk_fma_f32 v[16:17], v[32:33], v[120:121], v[16:17] op_sel_hi:[1,0,1]
	v_pk_fma_f32 v[18:19], v[34:35], v[120:121], v[18:19] op_sel_hi:[1,0,1]
	v_pk_fma_f32 v[20:21], v[36:37], v[120:121], v[20:21] op_sel_hi:[1,0,1]
	v_pk_fma_f32 v[22:23], v[38:39], v[120:121], v[22:23] op_sel_hi:[1,0,1]
	v_pk_fma_f32 v[24:25], v[40:41], v[120:121], v[24:25] op_sel_hi:[1,0,1]
	v_pk_fma_f32 v[26:27], v[42:43], v[120:121], v[26:27] op_sel_hi:[1,0,1]
	v_pk_fma_f32 v[28:29], v[44:45], v[120:121], v[28:29] op_sel_hi:[1,0,1]
	v_pk_fma_f32 v[30:31], v[46:47], v[120:121], v[30:31] op_sel_hi:[1,0,1]
	ds_read_b128 v[32:35], v7 offset:7808
	ds_read_b128 v[36:39], v7 offset:7824
	ds_read_b128 v[40:43], v7 offset:7840
	ds_read_b128 v[44:47], v7 offset:7856
	s_waitcnt vmcnt(6) lgkmcnt(4)
; #define LAS __attribute__((address_space(3)))
; __device__ __forceinline__ void ph_mod(const float* cp, const float* cs, const float* w_ada, const float* b_ada, float* MOD, float* MISC,
;                                        const float* lq1, const float* lk1, const float* lq2, const float* lk2, LAS unsigned char* lds, int G, int tid) {
;     ...
;         for (int kk = 0; kk < 128; ++kk) { const int k = k0 + kk; const float wv = w_ada[(size_t)k * 9216 + col];
;             const f32x4 s0 = *(const LAS f32x4*)(scT + k * 16), s1 = *(const LAS f32x4*)(scT + k * 16 + 4), s2 = *(const LAS f32x4*)(scT + k * 16 + 8), s3 = *(const LAS f32x4*)(scT + k * 16 + 12);
;             acc[0] += s0[0] * wv; acc[1] += s0[1] * wv; acc[2] += s0[2] * wv; acc[3] += s0[3] * wv; acc[4] += s1[0] * wv; acc[5] += s1[1] * wv; acc[6] += s1[2] * wv; acc[7] += s1[3] * wv;
;             acc[8] += s2[0] * wv; acc[9] += s2[1] * wv; acc[10] += s2[2] * wv; acc[11] += s2[3] * wv; acc[12] += s3[0] * wv; acc[13] += s3[1] * wv; acc[14] += s3[2] * wv; acc[15] += s3[3] * wv; }
; #pragma unroll
;         for (int b = 0; b < 16; ++b) red[(wave * 16 + b) * 64 + lane] = acc[b];
;         __syncthreads();
	v_pk_fma_f32 v[16:17], v[48:49], v[120:121], v[16:17] op_sel:[0,1,0] op_sel_hi:[1,1,1]
	v_pk_fma_f32 v[18:19], v[50:51], v[120:121], v[18:19] op_sel:[0,1,0] op_sel_hi:[1,1,1]
	v_pk_fma_f32 v[20:21], v[52:53], v[120:121], v[20:21] op_sel:[0,1,0] op_sel_hi:[1,1,1]
	v_pk_fma_f32 v[22:23], v[54:55], v[120:121], v[22:23] op_sel:[0,1,0] op_sel_hi:[1,1,1]
	v_pk_fma_f32 v[24:25], v[56:57], v[120:121], v[24:25] op_sel:[0,1,0] op_sel_hi:[1,1,1]
	v_pk_fma_f32 v[26:27], v[58:59], v[120:121], v[26:27] op_sel:[0,1,0] op_sel_hi:[1,1,1]
	v_pk_fma_f32 v[28:29], v[60:61], v[120:121], v[28:29] op_sel:[0,1,0] op_sel_hi:[1,1,1]
	v_pk_fma_f32 v[30:31], v[62:63], v[120:121], v[30:31] op_sel:[0,1,0] op_sel_hi:[1,1,1]
	ds_read_b128 v[48:51], v7 offset:7872
	ds_read_b128 v[52:55], v7 offset:7888
	ds_read_b128 v[56:59], v7 offset:7904
	ds_read_b128 v[60:63], v7 offset:7920
	s_waitcnt vmcnt(5) lgkmcnt(4)
	v_pk_fma_f32 v[16:17], v[32:33], v[122:123], v[16:17] op_sel_hi:[1,0,1]
	v_pk_fma_f32 v[18:19], v[34:35], v[122:123], v[18:19] op_sel_hi:[1,0,1]
	v_pk_fma_f32 v[20:21], v[36:37], v[122:123], v[20:21] op_sel_hi:[1,0,1]
	v_pk_fma_f32 v[22:23], v[38:39], v[122:123], v[22:23] op_sel_hi:[1,0,1]
	v_pk_fma_f32 v[24:25], v[40:41], v[122:123], v[24:25] op_sel_hi:[1,0,1]
	v_pk_fma_f32 v[26:27], v[42:43], v[122:123], v[26:27] op_sel_hi:[1,0,1]
	v_pk_fma_f32 v[28:29], v[44:45], v[122:123], v[28:29] op_sel_hi:[1,0,1]
	v_pk_fma_f32 v[30:31], v[46:47], v[122:123], v[30:31] op_sel_hi:[1,0,1]
	ds_read_b128 v[32:35], v7 offset:7936
	ds_read_b128 v[36:39], v7 offset:7952
	ds_read_b128 v[40:43], v7 offset:7968
	ds_read_b128 v[44:47], v7 offset:7984
	s_waitcnt vmcnt(4) lgkmcnt(4)
	v_pk_fma_f32 v[16:17], v[48:49], v[122:123], v[16:17] op_sel:[0,1,0] op_sel_hi:[1,1,1]
	v_pk_fma_f32 v[18:19], v[50:51], v[122:123], v[18:19] op_sel:[0,1,0] op_sel_hi:[1,1,1]
	v_pk_fma_f32 v[20:21], v[52:53], v[122:123], v[20:21] op_sel:[0,1,0] op_sel_hi:[1,1,1]
	v_pk_fma_f32 v[22:23], v[54:55], v[122:123], v[22:23] op_sel:[0,1,0] op_sel_hi:[1,1,1]
	v_pk_fma_f32 v[24:25], v[56:57], v[122:123], v[24:25] op_sel:[0,1,0] op_sel_hi:[1,1,1]
	v_pk_fma_f32 v[26:27], v[58:59], v[122:123], v[26:27] op_sel:[0,1,0] op_sel_hi:[1,1,1]
	v_pk_fma_f32 v[28:29], v[60:61], v[122:123], v[28:29] op_sel:[0,1,0] op_sel_hi:[1,1,1]
	v_pk_fma_f32 v[30:31], v[62:63], v[122:123], v[30:31] op_sel:[0,1,0] op_sel_hi:[1,1,1]
	ds_read_b128 v[48:51], v7 offset:8000
	ds_read_b128 v[52:55], v7 offset:8016
	ds_read_b128 v[56:59], v7 offset:8032
	ds_read_b128 v[60:63], v7 offset:8048
	s_waitcnt vmcnt(3) lgkmcnt(4)
	v_pk_fma_f32 v[16:17], v[32:33], v[124:125], v[16:17] op_sel_hi:[1,0,1]
	v_pk_fma_f32 v[18:19], v[34:35], v[124:125], v[18:19] op_sel_hi:[1,0,1]
	v_pk_fma_f32 v[20:21], v[36:37], v[124:125], v[20:21] op_sel_hi:[1,0,1]
	v_pk_fma_f32 v[22:23], v[38:39], v[124:125], v[22:23] op_sel_hi:[1,0,1]
	v_pk_fma_f32 v[24:25], v[40:41], v[124:125], v[24:25] op_sel_hi:[1,0,1]
	v_pk_fma_f32 v[26:27], v[42:43], v[124:125], v[26:27] op_sel_hi:[1,0,1]
	v_pk_fma_f32 v[28:29], v[44:45], v[124:125], v[28:29] op_sel_hi:[1,0,1]
	v_pk_fma_f32 v[30:31], v[46:47], v[124:125], v[30:31] op_sel_hi:[1,0,1]
	ds_read_b128 v[32:35], v7 offset:8064
	ds_read_b128 v[36:39], v7 offset:8080
	ds_read_b128 v[40:43], v7 offset:8096
	ds_read_b128 v[44:47], v7 offset:8112
	s_waitcnt vmcnt(2) lgkmcnt(4)
	v_pk_fma_f32 v[16:17], v[48:49], v[124:125], v[16:17] op_sel:[0,1,0] op_sel_hi:[1,1,1]
	v_pk_fma_f32 v[18:19], v[50:51], v[124:125], v[18:19] op_sel:[0,1,0] op_sel_hi:[1,1,1]
	v_pk_fma_f32 v[20:21], v[52:53], v[124:125], v[20:21] op_sel:[0,1,0] op_sel_hi:[1,1,1]
	v_pk_fma_f32 v[22:23], v[54:55], v[124:125], v[22:23] op_sel:[0,1,0] op_sel_hi:[1,1,1]
	v_pk_fma_f32 v[24:25], v[56:57], v[124:125], v[24:25] op_sel:[0,1,0] op_sel_hi:[1,1,1]
	v_pk_fma_f32 v[26:27], v[58:59], v[124:125], v[26:27] op_sel:[0,1,0] op_sel_hi:[1,1,1]
	v_pk_fma_f32 v[28:29], v[60:61], v[124:125], v[28:29] op_sel:[0,1,0] op_sel_hi:[1,1,1]
	v_pk_fma_f32 v[30:31], v[62:63], v[124:125], v[30:31] op_sel:[0,1,0] op_sel_hi:[1,1,1]
	ds_read_b128 v[48:51], v7 offset:8128
	ds_read_b128 v[52:55], v7 offset:8144
	ds_read_b128 v[56:59], v7 offset:8160
	ds_read_b128 v[60:63], v7 offset:8176
	s_waitcnt vmcnt(1) lgkmcnt(4)
	v_pk_fma_f32 v[16:17], v[32:33], v[126:127], v[16:17] op_sel_hi:[1,0,1]
	v_pk_fma_f32 v[18:19], v[34:35], v[126:127], v[18:19] op_sel_hi:[1,0,1]
	v_pk_fma_f32 v[20:21], v[36:37], v[126:127], v[20:21] op_sel_hi:[1,0,1]
	v_pk_fma_f32 v[22:23], v[38:39], v[126:127], v[22:23] op_sel_hi:[1,0,1]
	v_pk_fma_f32 v[24:25], v[40:41], v[126:127], v[24:25] op_sel_hi:[1,0,1]
	v_pk_fma_f32 v[26:27], v[42:43], v[126:127], v[26:27] op_sel_hi:[1,0,1]
	v_pk_fma_f32 v[28:29], v[44:45], v[126:127], v[28:29] op_sel_hi:[1,0,1]
	v_pk_fma_f32 v[30:31], v[46:47], v[126:127], v[30:31] op_sel_hi:[1,0,1]
	s_waitcnt vmcnt(0) lgkmcnt(0)
	v_pk_fma_f32 v[16:17], v[48:49], v[126:127], v[16:17] op_sel:[0,1,0] op_sel_hi:[1,1,1]
	v_pk_fma_f32 v[18:19], v[50:51], v[126:127], v[18:19] op_sel:[0,1,0] op_sel_hi:[1,1,1]
	v_pk_fma_f32 v[20:21], v[52:53], v[126:127], v[20:21] op_sel:[0,1,0] op_sel_hi:[1,1,1]
	v_pk_fma_f32 v[22:23], v[54:55], v[126:127], v[22:23] op_sel:[0,1,0] op_sel_hi:[1,1,1]
	v_pk_fma_f32 v[24:25], v[56:57], v[126:127], v[24:25] op_sel:[0,1,0] op_sel_hi:[1,1,1]
	v_pk_fma_f32 v[26:27], v[58:59], v[126:127], v[26:27] op_sel:[0,1,0] op_sel_hi:[1,1,1]
	v_pk_fma_f32 v[28:29], v[60:61], v[126:127], v[28:29] op_sel:[0,1,0] op_sel_hi:[1,1,1]
	v_pk_fma_f32 v[30:31], v[62:63], v[126:127], v[30:31] op_sel:[0,1,0] op_sel_hi:[1,1,1]
	ds_write_b32 v9, v16 offset:0
	ds_write_b32 v9, v17 offset:256
	ds_write_b32 v9, v18 offset:512
	ds_write_b32 v9, v19 offset:768
	ds_write_b32 v9, v20 offset:1024
	ds_write_b32 v9, v21 offset:1280
	ds_write_b32 v9, v22 offset:1536
	ds_write_b32 v9, v23 offset:1792
	ds_write_b32 v9, v24 offset:2048
	ds_write_b32 v9, v25 offset:2304
	ds_write_b32 v9, v26 offset:2560
	ds_write_b32 v9, v27 offset:2816
	ds_write_b32 v9, v28 offset:3072
	ds_write_b32 v9, v29 offset:3328
	ds_write_b32 v9, v30 offset:3584
	ds_write_b32 v9, v31 offset:3840
	s_waitcnt lgkmcnt(0)
	s_barrier
; __device__ __forceinline__ void ph_mod(const float* cp, const float* cs, const float* w_ada, const float* b_ada, float* MOD, float* MISC,
;                                        const float* lq1, const float* lk1, const float* lq2, const float* lk2, LAS unsigned char* lds, int G, int tid) {
;     ...
;         for (int o = tid; o < 1024; o += 512) { const int b = o >> 6, l = o & 63; float s = 0.f;
; #pragma unroll
;             for (int w = 0; w < 8; ++w) s += red[(w * 16 + b) * 64 + l];
;             MOD[(size_t)b * 9216 + unit * 64 + l] = s + b_ada[unit * 64 + l]; }
;         __syncthreads();
;     }
;     if (blockIdx.x == (unsigned)(G - 1) && wave == 0) { float a = lq1[lane] * lk1[lane], b = lq2[lane] * lk2[lane]; a = wave_sum(a); b = wave_sum(b); if (lane == 0) MISC[0] = __expf(a) - __expf(b) + 0.2f; }
	s_lshl_b32 s28, s34, 8
	s_add_u32 s22, s10, s28
	s_addc_u32 s23, s11, 0
	global_load_dword v15, v4, s[22:23]
	s_mul_i32 s27, s24, 0x9000
	s_add_u32 s22, s66, s27
	s_addc_u32 s23, s67, 0
	s_add_u32 s22, s22, s28
	s_addc_u32 s23, s23, 0
	s_add_u32 s22, s22, 0x100000
	s_addc_u32 s23, s23, 0
	ds_read_b32 v32, v14 offset:0
	ds_read_b32 v33, v14 offset:4096
	ds_read_b32 v34, v14 offset:8192
	ds_read_b32 v35, v14 offset:12288
	ds_read_b32 v36, v14 offset:16384
	ds_read_b32 v37, v14 offset:20480
	ds_read_b32 v38, v14 offset:24576
	ds_read_b32 v39, v14 offset:28672
	ds_read_b32 v40, v14 offset:2048
	ds_read_b32 v41, v14 offset:6144
	ds_read_b32 v42, v14 offset:10240
	ds_read_b32 v43, v14 offset:14336
	ds_read_b32 v44, v14 offset:18432
	ds_read_b32 v45, v14 offset:22528
	ds_read_b32 v46, v14 offset:26624
	ds_read_b32 v47, v14 offset:30720
	s_waitcnt lgkmcnt(8)
	v_add_f32_e32 v48, 0, v32
	v_add_f32_e32 v48, v48, v33
	v_add_f32_e32 v48, v48, v34
	v_add_f32_e32 v48, v48, v35
	v_add_f32_e32 v48, v48, v36
	v_add_f32_e32 v48, v48, v37
	v_add_f32_e32 v48, v48, v38
	v_add_f32_e32 v48, v48, v39
	s_waitcnt lgkmcnt(0)
	v_add_f32_e32 v49, 0, v40
	v_add_f32_e32 v49, v49, v41
	v_add_f32_e32 v49, v49, v42
	v_add_f32_e32 v49, v49, v43
	v_add_f32_e32 v49, v49, v44
	v_add_f32_e32 v49, v49, v45
	v_add_f32_e32 v49, v49, v46
	v_add_f32_e32 v49, v49, v47
	s_waitcnt vmcnt(0)
	v_add_f32_e32 v48, v48, v15
	v_add_f32_e32 v49, v49, v15
	global_store_dword v4, v48, s[22:23]
	s_add_u32 s22, s22, 0x48000
	s_addc_u32 s23, s23, 0
	global_store_dword v4, v49, s[22:23]
	s_add_i32 s34, s34, s69
	s_cmpk_gt_i32 s34, 0x8f
	s_barrier
	s_cbranch_scc0 .Lp0_unit
.Lp0_done:
.LBB0_24:
	s_add_i32 s0, s69, -1
	v_readlane_b32 s1, v254, 6
	s_cmp_eq_u32 s1, s0
	s_cselect_b64 s[0:1], -1, 0
	v_cmp_gt_u32_e32 vcc, 64, v2
	s_and_b64 s[10:11], s[0:1], vcc
	s_and_saveexec_b64 s[0:1], s[10:11]
	s_cbranch_execz .LBB0_27
	v_mov_b32_e32 v5, 0
	v_lshl_add_u64 v[2:3], s[8:9], 0, v[4:5]
	flat_load_dword v6, v[2:3]
	v_lshl_add_u64 v[2:3], s[6:7], 0, v[4:5]
	flat_load_dword v7, v[2:3]
	v_lshl_add_u64 v[2:3], s[4:5], 0, v[4:5]
	flat_load_dword v8, v[2:3]
	v_lshl_add_u64 v[2:3], s[2:3], 0, v[4:5]
	flat_load_dword v2, v[2:3]
	v_mbcnt_lo_u32_b32 v3, -1, 0
	v_mbcnt_hi_u32_b32 v3, -1, v3
	v_and_b32_e32 v4, 64, v3
	v_xor_b32_e32 v5, 1, v3
	v_add_u32_e32 v4, 64, v4
	v_cmp_lt_i32_e32 vcc, v5, v4
	v_xor_b32_e32 v9, 2, v3
	v_xor_b32_e32 v10, 4, v3
	v_cndmask_b32_e32 v5, v3, v5, vcc
	v_lshlrev_b32_e32 v5, 2, v5
	v_cmp_lt_i32_e32 vcc, v9, v4
	v_xor_b32_e32 v11, 8, v3
	v_xor_b32_e32 v12, 16, v3
	v_cndmask_b32_e32 v9, v3, v9, vcc
	v_lshlrev_b32_e32 v9, 2, v9
	v_cmp_lt_i32_e32 vcc, v10, v4
	v_xor_b32_e32 v13, 32, v3
	s_waitcnt vmcnt(0) lgkmcnt(0)
	v_mul_f32_e32 v14, v6, v7
	ds_bpermute_b32 v14, v5, v14
	v_mul_f32_e32 v15, v8, v2
	ds_bpermute_b32 v5, v5, v15
	s_waitcnt lgkmcnt(1)
	v_fmac_f32_e32 v14, v6, v7
	v_cndmask_b32_e32 v7, v3, v10, vcc
	v_lshlrev_b32_e32 v7, 2, v7
	v_cmp_lt_i32_e32 vcc, v11, v4
	s_waitcnt lgkmcnt(0)
	v_fmac_f32_e32 v5, v8, v2
	ds_bpermute_b32 v2, v9, v14
	ds_bpermute_b32 v6, v9, v5
	v_cndmask_b32_e32 v8, v3, v11, vcc
	v_lshlrev_b32_e32 v8, 2, v8
	v_cmp_lt_i32_e32 vcc, v12, v4
	s_waitcnt lgkmcnt(1)
	v_add_f32_e32 v2, v14, v2
	s_waitcnt lgkmcnt(0)
	v_add_f32_e32 v5, v5, v6
	ds_bpermute_b32 v6, v7, v2
	ds_bpermute_b32 v7, v7, v5
	s_waitcnt lgkmcnt(1)
	v_add_f32_e32 v2, v2, v6
	s_waitcnt lgkmcnt(0)
	v_add_f32_e32 v5, v5, v7
	ds_bpermute_b32 v6, v8, v2
	ds_bpermute_b32 v7, v8, v5
	v_cndmask_b32_e32 v8, v3, v12, vcc
	v_lshlrev_b32_e32 v8, 2, v8
	v_cmp_lt_i32_e32 vcc, v13, v4
	s_waitcnt lgkmcnt(1)
	v_add_f32_e32 v2, v2, v6
	s_waitcnt lgkmcnt(0)
	v_add_f32_e32 v5, v5, v7
	ds_bpermute_b32 v6, v8, v2
	ds_bpermute_b32 v7, v8, v5
	v_cndmask_b32_e32 v3, v3, v13, vcc
	v_lshlrev_b32_e32 v4, 2, v3
	v_cmp_eq_u32_e32 vcc, 0, v1
	s_waitcnt lgkmcnt(1)
	v_add_f32_e32 v3, v2, v6
	s_waitcnt lgkmcnt(0)
	v_add_f32_e32 v2, v5, v7
	ds_bpermute_b32 v5, v4, v3
	ds_bpermute_b32 v4, v4, v2
	s_and_b64 exec, exec, vcc
	s_cbranch_execz .LBB0_27
	s_waitcnt lgkmcnt(1)
	v_add_f32_e32 v1, v3, v5
	s_waitcnt lgkmcnt(0)
	v_add_f32_e32 v2, v2, v4
	v_mul_f32_e32 v1, 0x3fb8aa3b, v1
	v_mul_f32_e32 v2, 0x3fb8aa3b, v2
	v_exp_f32_e32 v1, v1
	v_exp_f32_e32 v2, v2
	s_nop 0
	v_sub_f32_e32 v1, v1, v2
	v_add_f32_e32 v1, 0x3e4ccccd, v1
	v_mov_b32_e32 v2, 0x1a0000
	global_store_dword v2, v1, s[66:67]

; #define LAS __attribute__((address_space(3)))
; template <bool WITH_DT, bool OUT8> __device__ __forceinline__ void norm_mod_rows(const void* xp, bool pb16, const void* xs, bool sb16, const float* w, const float* MOD, int ish, int isc, bf16* H, ...
;     asm volatile("" : "+v"(tid)); const int lane = tid & 63, gw = vcu * NWAVES + __builtin_amdgcn_readfirstlane(tid >> 6), NGW = G * NWAVES;
;     f32x4 wv[4];
; #pragma unroll
;     for (int j = 0; j < 4; ++j) wv[j] = ((const f32x4*)w)[lane + 64 * j];
;     f32x4 wdt[WITH_DT ? 8 : 1][4];
;     if (WITH_DT) {
; #pragma unroll
;         for (int c = 0; c < 8; ++c)
; #pragma unroll
;             for (int j = 0; j < 4; ++j) wdt[c][j] = *(const LAS f32x4*)(sW + c * 1024 + 4 * (lane + 64 * j)); }
;     f32x4 vn[4];
;     if (gw < MT) { if (gw < MP) load_row4(xp, pb16, (size_t)gw, lane, vn); else load_row4(xs, sb16, (size_t)(gw - MP), lane, vn); }
; __global__ void __launch_bounds__(NWAVES * 64, 2) mk_fwd(Args args) {
;     ...
;         LAS float* sW = (LAS float*)L;
;         for (int i = tid; i < 8192; i += 512) { const int c = i & 7, k = i >> 3; sW[c * 1024 + k] = karg_in<14>()[(size_t)k * INC + 1536 + c]; }
;         __syncthreads();
;         norm_mod_rows<true, false>(XB, true, karg_in<1>(), false, karg_in<13>(), MOD, 3, 4, H, vcu, G, tid, sW, karg_in<17>(), DT, (const bf16*)(ws + WS_HST), 11, MOD + 2 * 1024, 0.5f * INV_D, XB);
.LBB0_381:
	v_readlane_b32 s4, v254, 0
	s_cmp_lt_i32 s4, 5
	s_cselect_b64 s[2:3], -1, 0
	s_and_b64 s[8:9], s[2:3], s[0:1]
	s_andn2_b64 vcc, exec, s[8:9]
	v_readlane_b32 s5, v254, 1
	v_readlane_b32 s6, v254, 2
	v_readlane_b32 s7, v254, 3
	s_cbranch_vccnz .LBB0_401
	v_lshrrev_b32_e32 v1, 3, v252
	v_and_b32_e32 v0, 7, v252
	v_lshlrev_b32_e32 v3, 2, v1
	v_mul_u32_u24_e32 v1, 0xc08, v1
	v_lshl_or_b32 v3, v0, 12, v3
	v_or_b32_e32 v0, v1, v0
	v_mov_b32_e32 v1, 0x1800
	v_add_u32_e32 v2, 0xfffffe00, v252
	v_add_u32_e32 v3, 0, v3
	v_lshl_add_u32 v0, v0, 2, v1
	v_mov_b32_e32 v1, 0
	s_load_dwordx2 s[6:7], s[58:59], 0x70
	s_waitcnt lgkmcnt(0)
	s_mov_b64 s[2:3], 0xc0800
	v_lshl_add_u64 v[4:5], s[6:7], 0, v[0:1]
	global_load_dword v8, v[4:5], off
	v_lshl_add_u64 v[4:5], v[4:5], 0, s[2:3]
	global_load_dword v9, v[4:5], off
	v_lshl_add_u64 v[4:5], v[4:5], 0, s[2:3]
	global_load_dword v10, v[4:5], off
	v_lshl_add_u64 v[4:5], v[4:5], 0, s[2:3]
	global_load_dword v11, v[4:5], off
	v_lshl_add_u64 v[4:5], v[4:5], 0, s[2:3]
	global_load_dword v12, v[4:5], off
	v_lshl_add_u64 v[4:5], v[4:5], 0, s[2:3]
	global_load_dword v13, v[4:5], off
	v_lshl_add_u64 v[4:5], v[4:5], 0, s[2:3]
	global_load_dword v14, v[4:5], off
	v_lshl_add_u64 v[4:5], v[4:5], 0, s[2:3]
	global_load_dword v15, v[4:5], off
	v_lshl_add_u64 v[4:5], v[4:5], 0, s[2:3]
	global_load_dword v16, v[4:5], off
	v_lshl_add_u64 v[4:5], v[4:5], 0, s[2:3]
	global_load_dword v17, v[4:5], off
	v_lshl_add_u64 v[4:5], v[4:5], 0, s[2:3]
	global_load_dword v18, v[4:5], off
	v_lshl_add_u64 v[4:5], v[4:5], 0, s[2:3]
	global_load_dword v19, v[4:5], off
	v_lshl_add_u64 v[4:5], v[4:5], 0, s[2:3]
	global_load_dword v20, v[4:5], off
	v_lshl_add_u64 v[4:5], v[4:5], 0, s[2:3]
	global_load_dword v21, v[4:5], off
	v_lshl_add_u64 v[4:5], v[4:5], 0, s[2:3]
	global_load_dword v22, v[4:5], off
	v_lshl_add_u64 v[4:5], v[4:5], 0, s[2:3]
	global_load_dword v23, v[4:5], off
	s_waitcnt vmcnt(15)
	ds_write_b32 v3, v8 offset:0
	s_waitcnt vmcnt(14)
	ds_write_b32 v3, v9 offset:256
	s_waitcnt vmcnt(13)
	ds_write_b32 v3, v10 offset:512
	s_waitcnt vmcnt(12)
	ds_write_b32 v3, v11 offset:768
	s_waitcnt vmcnt(11)
	ds_write_b32 v3, v12 offset:1024
	s_waitcnt vmcnt(10)
	ds_write_b32 v3, v13 offset:1280
	s_waitcnt vmcnt(9)
	ds_write_b32 v3, v14 offset:1536
	s_waitcnt vmcnt(8)
	ds_write_b32 v3, v15 offset:1792
	s_waitcnt vmcnt(7)
	ds_write_b32 v3, v16 offset:2048
	s_waitcnt vmcnt(6)
	ds_write_b32 v3, v17 offset:2304
	s_waitcnt vmcnt(5)
	ds_write_b32 v3, v18 offset:2560
	s_waitcnt vmcnt(4)
	ds_write_b32 v3, v19 offset:2816
	s_waitcnt vmcnt(3)
	ds_write_b32 v3, v20 offset:3072
	s_waitcnt vmcnt(2)
	ds_write_b32 v3, v21 offset:3328
	s_waitcnt vmcnt(1)
	ds_write_b32 v3, v22 offset:3584
	s_waitcnt vmcnt(0)
	ds_write_b32 v3, v23 offset:3840
	s_waitcnt lgkmcnt(0)
	s_barrier
	s_load_dwordx2 s[0:1], s[58:59], 8
	s_waitcnt lgkmcnt(0)
	s_load_dwordx2 s[2:3], s[58:59], 0x68
	s_waitcnt lgkmcnt(0)
	v_mov_b32_e32 v144, v252
	s_load_dwordx2 s[14:15], s[58:59], 0x88
	s_waitcnt lgkmcnt(0)
	s_lshl_b32 s4, s92, 3
	v_readfirstlane_b32 s5, v144
	s_ashr_i32 s5, s5, 6
	s_add_i32 s24, s5, s4
	s_cmp_gt_i32 s24, 0x81ff
	s_cbranch_scc1 .LBB0_400
	v_and_b32_e32 v145, 63, v144
	v_mov_b32_e32 v181, 0
	v_lshlrev_b32_e32 v180, 4, v145
	v_lshl_add_u64 v[16:17], s[2:3], 0, v[180:181]
	flat_load_dwordx4 v[0:3], v[16:17]
	flat_load_dwordx4 v[4:7], v[16:17] offset:1024
	flat_load_dwordx4 v[8:11], v[16:17] offset:2048
	flat_load_dwordx4 v[12:15], v[16:17] offset:3072
	v_add_u32_e32 v140, 0, v180
	ds_read_b128 v[16:19], v140
	ds_read_b128 v[20:23], v140 offset:1024
	ds_read_b128 v[24:27], v140 offset:2048
	ds_read_b128 v[28:31], v140 offset:3072
	ds_read_b128 v[32:35], v140 offset:4096
	ds_read_b128 v[36:39], v140 offset:5120
	ds_read_b128 v[40:43], v140 offset:6144
	ds_read_b128 v[44:47], v140 offset:7168
	ds_read_b128 v[48:51], v140 offset:8192
	ds_read_b128 v[52:55], v140 offset:9216
	ds_read_b128 v[56:59], v140 offset:10240
	ds_read_b128 v[60:63], v140 offset:11264
	ds_read_b128 v[64:67], v140 offset:12288
	ds_read_b128 v[68:71], v140 offset:13312
	ds_read_b128 v[72:75], v140 offset:14336
	ds_read_b128 v[76:79], v140 offset:15360
	ds_read_b128 v[80:83], v140 offset:16384
	ds_read_b128 v[84:87], v140 offset:17408
	ds_read_b128 v[88:91], v140 offset:18432
	ds_read_b128 v[92:95], v140 offset:19456
	ds_read_b128 v[96:99], v140 offset:20480
	ds_read_b128 v[100:103], v140 offset:21504
	ds_read_b128 v[104:107], v140 offset:22528
	ds_read_b128 v[108:111], v140 offset:23552
	ds_read_b128 v[112:115], v140 offset:24576
	ds_read_b128 v[116:119], v140 offset:25600
	ds_read_b128 v[120:123], v140 offset:26624
	ds_read_b128 v[124:127], v140 offset:27648
	ds_read_b128 v[128:131], v140 offset:28672
	ds_read_b128 v[132:135], v140 offset:29696
	ds_read_b128 v[136:139], v140 offset:30720
	ds_read_b128 v[140:143], v140 offset:31744
	s_cmpk_gt_i32 s24, 0x7fff
	s_mov_b32 s3, 0
	s_cbranch_scc0 .LBB0_387
	s_add_i32 s2, s24, 0xffff8000
	s_lshl_b64 s[2:3], s[2:3], 12
	s_add_u32 s2, s0, s2
	s_addc_u32 s3, s1, s3
	v_lshl_add_u64 v[146:147], s[2:3], 0, v[180:181]
	flat_load_dwordx4 v[172:175], v[146:147]
	flat_load_dwordx4 v[168:171], v[146:147] offset:1024
	flat_load_dwordx4 v[164:167], v[146:147] offset:2048
	flat_load_dwordx4 v[160:163], v[146:147] offset:3072
	s_ashr_i32 s25, s24, 31
	s_lshl_b64 s[16:17], s[24:25], 11
	v_lshlrev_b32_e32 v182, 3, v145
	s_cbranch_execz .LBB0_388
	s_branch .LBB0_389

; __device__ __forceinline__ float bflo(unsigned x) { return __uint_as_float(x << 16); }
; __device__ __forceinline__ float bfhi(unsigned x) { return __uint_as_float(x & 0xffff0000u); }
; __device__ __forceinline__ unsigned pk2(float lo, float hi) { return pg8::cvt_pk_bf16(lo, hi); }
; template <bool WITH_DT, bool OUT8> __device__ __forceinline__ void norm_mod_rows(const void* xp, bool pb16, const void* xs, bool sb16, const float* w, const float* MOD, int ish, int isc, bf16* H, ...
;     ...
;         if (fslab && row >= MP) {
;             f32x4 a[4];
; #pragma unroll
;             for (int j = 0; j < 4; ++j) a[j] = (f32x4){0.f, 0.f, 0.f, 0.f};
;             for (int ks = 0; ks < fS; ++ks) { const v2u* sp = (const v2u*)(fslab + ((size_t)ks * MS + (row - MP)) * DM);
; #pragma unroll
;                 for (int j = 0; j < 4; ++j) { const v2u r = sp[lane + 64 * j]; a[j] += (f32x4){bflo(r.x), bfhi(r.x), bflo(r.y), bfhi(r.y)}; } }
; #pragma unroll
;             for (int j = 0; j < 4; ++j) { v[j] += ((const f32x4*)(fgate + (size_t)mb * 9216))[lane + 64 * j] * fsc * a[j];
;                 v2u o; o.x = pk2(v[j][0], v[j][1]); o.y = pk2(v[j][2], v[j][3]); *(v2u*)(fxout + (size_t)row * DM + 4 * (lane + 64 * j)) = o; }
.LBB0_396:
	s_add_i32 s12, s24, 0xffff8000
	s_lshr_b32 s21, s12, 6
	s_add_i32 s21, s21, 8
	s_cmp_lt_i32 s24, 0x8000
	s_cbranch_scc1 .LBB0_398
	s_lshl_b64 s[26:27], s[12:13], 11
	s_add_u32 s26, s29, s26
	s_addc_u32 s27, s30, s27
	s_mov_b64 s[38:39], s[26:27]
	global_load_dwordx2 v[220:221], v182, s[38:39]
	global_load_dwordx2 v[232:233], v182, s[38:39] offset:512
	global_load_dwordx2 v[234:235], v182, s[38:39] offset:1024
	global_load_dwordx2 v[236:237], v182, s[38:39] offset:1536
	s_add_u32 s38, s38, 0x100000
	s_addc_u32 s39, s39, 0
	global_load_dwordx2 v[238:239], v182, s[38:39]
	global_load_dwordx2 v[240:241], v182, s[38:39] offset:512
	global_load_dwordx2 v[242:243], v182, s[38:39] offset:1024
	global_load_dwordx2 v[244:245], v182, s[38:39] offset:1536
	s_add_u32 s38, s38, 0x100000
	s_addc_u32 s39, s39, 0
	global_load_dwordx2 v[246:247], v182, s[38:39]
	global_load_dwordx2 v[248:249], v182, s[38:39] offset:512
	global_load_dwordx2 v[250:251], v182, s[38:39] offset:1024
	global_load_dwordx2 v[176:177], v182, s[38:39] offset:1536
	s_waitcnt vmcnt(11)
	v_lshlrev_b32_e32 v212, 16, v220
	v_and_b32_e32 v213, 0xffff0000, v220
	v_lshlrev_b32_e32 v214, 16, v221
	v_and_b32_e32 v215, 0xffff0000, v221
	s_add_u32 s38, s38, 0x100000
	s_addc_u32 s39, s39, 0
	global_load_dwordx2 v[220:221], v182, s[38:39]
	s_waitcnt vmcnt(11)
	v_lshlrev_b32_e32 v208, 16, v232
	v_and_b32_e32 v209, 0xffff0000, v232
	v_lshlrev_b32_e32 v210, 16, v233
	v_and_b32_e32 v211, 0xffff0000, v233
	global_load_dwordx2 v[232:233], v182, s[38:39] offset:512
	s_waitcnt vmcnt(11)
	v_lshlrev_b32_e32 v204, 16, v234
	v_and_b32_e32 v205, 0xffff0000, v234
	v_lshlrev_b32_e32 v206, 16, v235
	v_and_b32_e32 v207, 0xffff0000, v235
	global_load_dwordx2 v[234:235], v182, s[38:39] offset:1024
	s_waitcnt vmcnt(11)
	v_lshlrev_b32_e32 v216, 16, v236
	v_and_b32_e32 v217, 0xffff0000, v236
	v_lshlrev_b32_e32 v218, 16, v237
	v_and_b32_e32 v219, 0xffff0000, v237
	global_load_dwordx2 v[236:237], v182, s[38:39] offset:1536
	s_waitcnt vmcnt(11)
	v_lshlrev_b32_e32 v178, 16, v238
	v_and_b32_e32 v179, 0xffff0000, v238
	v_lshlrev_b32_e32 v203, 16, v239
	v_and_b32_e32 v231, 0xffff0000, v239
	s_add_u32 s38, s38, 0x100000
	s_addc_u32 s39, s39, 0
	global_load_dwordx2 v[238:239], v182, s[38:39]
	v_pk_add_f32 v[212:213], v[212:213], v[178:179]
	v_add_f32_e32 v214, v214, v203
	v_add_f32_e32 v215, v215, v231
	s_waitcnt vmcnt(11)
	v_lshlrev_b32_e32 v178, 16, v240
	v_and_b32_e32 v179, 0xffff0000, v240
	v_lshlrev_b32_e32 v203, 16, v241
	v_and_b32_e32 v231, 0xffff0000, v241
	global_load_dwordx2 v[240:241], v182, s[38:39] offset:512
	v_pk_add_f32 v[208:209], v[208:209], v[178:179]
	v_add_f32_e32 v210, v210, v203
	v_add_f32_e32 v211, v211, v231
	s_waitcnt vmcnt(11)
	v_lshlrev_b32_e32 v178, 16, v242
	v_and_b32_e32 v179, 0xffff0000, v242
	v_lshlrev_b32_e32 v203, 16, v243
	v_and_b32_e32 v231, 0xffff0000, v243
	global_load_dwordx2 v[242:243], v182, s[38:39] offset:1024
	v_pk_add_f32 v[204:205], v[204:205], v[178:179]
	v_add_f32_e32 v206, v206, v203
	v_add_f32_e32 v207, v207, v231
	s_waitcnt vmcnt(11)
	v_lshlrev_b32_e32 v178, 16, v244
	v_and_b32_e32 v179, 0xffff0000, v244
	v_lshlrev_b32_e32 v203, 16, v245
	v_and_b32_e32 v231, 0xffff0000, v245
	global_load_dwordx2 v[244:245], v182, s[38:39] offset:1536
	v_pk_add_f32 v[216:217], v[216:217], v[178:179]
	v_add_f32_e32 v218, v218, v203
	v_add_f32_e32 v219, v219, v231
	s_waitcnt vmcnt(11)
	v_lshlrev_b32_e32 v178, 16, v246
	v_and_b32_e32 v179, 0xffff0000, v246
	v_lshlrev_b32_e32 v203, 16, v247
	v_and_b32_e32 v231, 0xffff0000, v247
	s_add_u32 s38, s38, 0x100000
	s_addc_u32 s39, s39, 0
	global_load_dwordx2 v[246:247], v182, s[38:39]
	v_pk_add_f32 v[212:213], v[212:213], v[178:179]
	v_add_f32_e32 v214, v214, v203
	v_add_f32_e32 v215, v215, v231
	s_waitcnt vmcnt(11)
	v_lshlrev_b32_e32 v178, 16, v248
	v_and_b32_e32 v179, 0xffff0000, v248
	v_lshlrev_b32_e32 v203, 16, v249
	v_and_b32_e32 v231, 0xffff0000, v249
	global_load_dwordx2 v[248:249], v182, s[38:39] offset:512
	v_pk_add_f32 v[208:209], v[208:209], v[178:179]
	v_add_f32_e32 v210, v210, v203
	v_add_f32_e32 v211, v211, v231
	s_waitcnt vmcnt(11)
	v_lshlrev_b32_e32 v178, 16, v250
	v_and_b32_e32 v179, 0xffff0000, v250
	v_lshlrev_b32_e32 v203, 16, v251
	v_and_b32_e32 v231, 0xffff0000, v251
	global_load_dwordx2 v[250:251], v182, s[38:39] offset:1024
	v_pk_add_f32 v[204:205], v[204:205], v[178:179]
	v_add_f32_e32 v206, v206, v203
	v_add_f32_e32 v207, v207, v231
	s_waitcnt vmcnt(11)
	v_lshlrev_b32_e32 v178, 16, v176
	v_and_b32_e32 v179, 0xffff0000, v176
	v_lshlrev_b32_e32 v203, 16, v177
	v_and_b32_e32 v231, 0xffff0000, v177
	global_load_dwordx2 v[176:177], v182, s[38:39] offset:1536
	v_pk_add_f32 v[216:217], v[216:217], v[178:179]
	v_add_f32_e32 v218, v218, v203
	v_add_f32_e32 v219, v219, v231
	s_waitcnt vmcnt(11)
	v_lshlrev_b32_e32 v178, 16, v220
	v_and_b32_e32 v179, 0xffff0000, v220
	v_lshlrev_b32_e32 v203, 16, v221
	v_and_b32_e32 v231, 0xffff0000, v221
	s_add_u32 s38, s38, 0x100000
	s_addc_u32 s39, s39, 0
	global_load_dwordx2 v[220:221], v182, s[38:39]
	v_pk_add_f32 v[212:213], v[212:213], v[178:179]
	v_add_f32_e32 v214, v214, v203
	v_add_f32_e32 v215, v215, v231
	s_waitcnt vmcnt(11)
	v_lshlrev_b32_e32 v178, 16, v232
	v_and_b32_e32 v179, 0xffff0000, v232
	v_lshlrev_b32_e32 v203, 16, v233
	v_and_b32_e32 v231, 0xffff0000, v233
	global_load_dwordx2 v[232:233], v182, s[38:39] offset:512
	v_pk_add_f32 v[208:209], v[208:209], v[178:179]
	v_add_f32_e32 v210, v210, v203
	v_add_f32_e32 v211, v211, v231
	s_waitcnt vmcnt(11)
; __device__ __forceinline__ float bflo(unsigned x) { return __uint_as_float(x << 16); }
; __device__ __forceinline__ float bfhi(unsigned x) { return __uint_as_float(x & 0xffff0000u); }
; template <bool WITH_DT, bool OUT8> __device__ __forceinline__ void norm_mod_rows(const void* xp, bool pb16, const void* xs, bool sb16, const float* w, const float* MOD, int ish, int isc, bf16* H, ...
;     ...
;             for (int ks = 0; ks < fS; ++ks) { const v2u* sp = (const v2u*)(fslab + ((size_t)ks * MS + (row - MP)) * DM);
; #pragma unroll
;                 for (int j = 0; j < 4; ++j) { const v2u r = sp[lane + 64 * j]; a[j] += (f32x4){bflo(r.x), bfhi(r.x), bflo(r.y), bfhi(r.y)}; } }
	v_lshlrev_b32_e32 v178, 16, v234
	v_and_b32_e32 v179, 0xffff0000, v234
	v_lshlrev_b32_e32 v203, 16, v235
	v_and_b32_e32 v231, 0xffff0000, v235
	global_load_dwordx2 v[234:235], v182, s[38:39] offset:1024
	v_pk_add_f32 v[204:205], v[204:205], v[178:179]
	v_add_f32_e32 v206, v206, v203
	v_add_f32_e32 v207, v207, v231
	s_waitcnt vmcnt(11)
	v_lshlrev_b32_e32 v178, 16, v236
	v_and_b32_e32 v179, 0xffff0000, v236
	v_lshlrev_b32_e32 v203, 16, v237
	v_and_b32_e32 v231, 0xffff0000, v237
	global_load_dwordx2 v[236:237], v182, s[38:39] offset:1536
	v_pk_add_f32 v[216:217], v[216:217], v[178:179]
	v_add_f32_e32 v218, v218, v203
	v_add_f32_e32 v219, v219, v231
	s_waitcnt vmcnt(11)
	v_lshlrev_b32_e32 v178, 16, v238
	v_and_b32_e32 v179, 0xffff0000, v238
	v_lshlrev_b32_e32 v203, 16, v239
	v_and_b32_e32 v231, 0xffff0000, v239
	s_add_u32 s38, s38, 0x100000
	s_addc_u32 s39, s39, 0
	global_load_dwordx2 v[238:239], v182, s[38:39]
	v_pk_add_f32 v[212:213], v[212:213], v[178:179]
	v_add_f32_e32 v214, v214, v203
	v_add_f32_e32 v215, v215, v231
	s_waitcnt vmcnt(11)
	v_lshlrev_b32_e32 v178, 16, v240
	v_and_b32_e32 v179, 0xffff0000, v240
	v_lshlrev_b32_e32 v203, 16, v241
	v_and_b32_e32 v231, 0xffff0000, v241
	global_load_dwordx2 v[240:241], v182, s[38:39] offset:512
	v_pk_add_f32 v[208:209], v[208:209], v[178:179]
	v_add_f32_e32 v210, v210, v203
	v_add_f32_e32 v211, v211, v231
	s_waitcnt vmcnt(11)
	v_lshlrev_b32_e32 v178, 16, v242
	v_and_b32_e32 v179, 0xffff0000, v242
	v_lshlrev_b32_e32 v203, 16, v243
	v_and_b32_e32 v231, 0xffff0000, v243
	global_load_dwordx2 v[242:243], v182, s[38:39] offset:1024
	v_pk_add_f32 v[204:205], v[204:205], v[178:179]
	v_add_f32_e32 v206, v206, v203
	v_add_f32_e32 v207, v207, v231
	s_waitcnt vmcnt(11)
	v_lshlrev_b32_e32 v178, 16, v244
	v_and_b32_e32 v179, 0xffff0000, v244
	v_lshlrev_b32_e32 v203, 16, v245
	v_and_b32_e32 v231, 0xffff0000, v245
	global_load_dwordx2 v[244:245], v182, s[38:39] offset:1536
	v_pk_add_f32 v[216:217], v[216:217], v[178:179]
	v_add_f32_e32 v218, v218, v203
	v_add_f32_e32 v219, v219, v231
	s_waitcnt vmcnt(11)
	v_lshlrev_b32_e32 v178, 16, v246
	v_and_b32_e32 v179, 0xffff0000, v246
	v_lshlrev_b32_e32 v203, 16, v247
	v_and_b32_e32 v231, 0xffff0000, v247
	s_add_u32 s38, s38, 0x100000
	s_addc_u32 s39, s39, 0
	global_load_dwordx2 v[246:247], v182, s[38:39]
	v_pk_add_f32 v[212:213], v[212:213], v[178:179]
	v_add_f32_e32 v214, v214, v203
	v_add_f32_e32 v215, v215, v231
	s_waitcnt vmcnt(11)
	v_lshlrev_b32_e32 v178, 16, v248
	v_and_b32_e32 v179, 0xffff0000, v248
	v_lshlrev_b32_e32 v203, 16, v249
	v_and_b32_e32 v231, 0xffff0000, v249
	global_load_dwordx2 v[248:249], v182, s[38:39] offset:512
	v_pk_add_f32 v[208:209], v[208:209], v[178:179]
	v_add_f32_e32 v210, v210, v203
	v_add_f32_e32 v211, v211, v231
	s_waitcnt vmcnt(11)
	v_lshlrev_b32_e32 v178, 16, v250
	v_and_b32_e32 v179, 0xffff0000, v250
	v_lshlrev_b32_e32 v203, 16, v251
	v_and_b32_e32 v231, 0xffff0000, v251
	global_load_dwordx2 v[250:251], v182, s[38:39] offset:1024
	v_pk_add_f32 v[204:205], v[204:205], v[178:179]
	v_add_f32_e32 v206, v206, v203
	v_add_f32_e32 v207, v207, v231
	s_waitcnt vmcnt(11)
	v_lshlrev_b32_e32 v178, 16, v176
	v_and_b32_e32 v179, 0xffff0000, v176
	v_lshlrev_b32_e32 v203, 16, v177
	v_and_b32_e32 v231, 0xffff0000, v177
	global_load_dwordx2 v[176:177], v182, s[38:39] offset:1536
	v_pk_add_f32 v[216:217], v[216:217], v[178:179]
	v_add_f32_e32 v218, v218, v203
	v_add_f32_e32 v219, v219, v231
	s_waitcnt vmcnt(11)
	v_lshlrev_b32_e32 v178, 16, v220
	v_and_b32_e32 v179, 0xffff0000, v220
	v_lshlrev_b32_e32 v203, 16, v221
	v_and_b32_e32 v231, 0xffff0000, v221
	s_add_u32 s38, s38, 0x100000
	s_addc_u32 s39, s39, 0
	global_load_dwordx2 v[220:221], v182, s[38:39]
	v_pk_add_f32 v[212:213], v[212:213], v[178:179]
	v_add_f32_e32 v214, v214, v203
	v_add_f32_e32 v215, v215, v231
	s_waitcnt vmcnt(11)
	v_lshlrev_b32_e32 v178, 16, v232
	v_and_b32_e32 v179, 0xffff0000, v232
	v_lshlrev_b32_e32 v203, 16, v233
	v_and_b32_e32 v231, 0xffff0000, v233
	global_load_dwordx2 v[232:233], v182, s[38:39] offset:512
	v_pk_add_f32 v[208:209], v[208:209], v[178:179]
	v_add_f32_e32 v210, v210, v203
	v_add_f32_e32 v211, v211, v231
	s_waitcnt vmcnt(11)
	v_lshlrev_b32_e32 v178, 16, v234
	v_and_b32_e32 v179, 0xffff0000, v234
	v_lshlrev_b32_e32 v203, 16, v235
	v_and_b32_e32 v231, 0xffff0000, v235
	global_load_dwordx2 v[234:235], v182, s[38:39] offset:1024
	v_pk_add_f32 v[204:205], v[204:205], v[178:179]
	v_add_f32_e32 v206, v206, v203
	v_add_f32_e32 v207, v207, v231
	s_waitcnt vmcnt(11)
	v_lshlrev_b32_e32 v178, 16, v236
	v_and_b32_e32 v179, 0xffff0000, v236
	v_lshlrev_b32_e32 v203, 16, v237
	v_and_b32_e32 v231, 0xffff0000, v237
	global_load_dwordx2 v[236:237], v182, s[38:39] offset:1536
	v_pk_add_f32 v[216:217], v[216:217], v[178:179]
	v_add_f32_e32 v218, v218, v203
	v_add_f32_e32 v219, v219, v231
	s_waitcnt vmcnt(11)
	v_lshlrev_b32_e32 v178, 16, v238
	v_and_b32_e32 v179, 0xffff0000, v238
	v_lshlrev_b32_e32 v203, 16, v239
	v_and_b32_e32 v231, 0xffff0000, v239
	s_add_u32 s38, s38, 0x100000
	s_addc_u32 s39, s39, 0
	global_load_dwordx2 v[238:239], v182, s[38:39]
	v_pk_add_f32 v[212:213], v[212:213], v[178:179]
	v_add_f32_e32 v214, v214, v203
	v_add_f32_e32 v215, v215, v231
	s_waitcnt vmcnt(11)
	v_lshlrev_b32_e32 v178, 16, v240
	v_and_b32_e32 v179, 0xffff0000, v240
	v_lshlrev_b32_e32 v203, 16, v241
	v_and_b32_e32 v231, 0xffff0000, v241
	global_load_dwordx2 v[240:241], v182, s[38:39] offset:512
	v_pk_add_f32 v[208:209], v[208:209], v[178:179]
	v_add_f32_e32 v210, v210, v203
	v_add_f32_e32 v211, v211, v231
	s_waitcnt vmcnt(11)
; __device__ __forceinline__ float bflo(unsigned x) { return __uint_as_float(x << 16); }
; __device__ __forceinline__ float bfhi(unsigned x) { return __uint_as_float(x & 0xffff0000u); }
; __device__ __forceinline__ unsigned pk2(float lo, float hi) { return pg8::cvt_pk_bf16(lo, hi); }
; template <bool WITH_DT, bool OUT8> __device__ __forceinline__ void norm_mod_rows(const void* xp, bool pb16, const void* xs, bool sb16, const float* w, const float* MOD, int ish, int isc, bf16* H, ...
;     ...
;             for (int ks = 0; ks < fS; ++ks) { const v2u* sp = (const v2u*)(fslab + ((size_t)ks * MS + (row - MP)) * DM);
; #pragma unroll
;                 for (int j = 0; j < 4; ++j) { const v2u r = sp[lane + 64 * j]; a[j] += (f32x4){bflo(r.x), bfhi(r.x), bflo(r.y), bfhi(r.y)}; } }
; #pragma unroll
;             for (int j = 0; j < 4; ++j) { v[j] += ((const f32x4*)(fgate + (size_t)mb * 9216))[lane + 64 * j] * fsc * a[j];
;                 v2u o; o.x = pk2(v[j][0], v[j][1]); o.y = pk2(v[j][2], v[j][3]); *(v2u*)(fxout + (size_t)row * DM + 4 * (lane + 64 * j)) = o; }
	v_lshlrev_b32_e32 v178, 16, v242
	v_and_b32_e32 v179, 0xffff0000, v242
	v_lshlrev_b32_e32 v203, 16, v243
	v_and_b32_e32 v231, 0xffff0000, v243
	global_load_dwordx2 v[242:243], v182, s[38:39] offset:1024
	v_pk_add_f32 v[204:205], v[204:205], v[178:179]
	v_add_f32_e32 v206, v206, v203
	v_add_f32_e32 v207, v207, v231
	s_waitcnt vmcnt(11)
	v_lshlrev_b32_e32 v178, 16, v244
	v_and_b32_e32 v179, 0xffff0000, v244
	v_lshlrev_b32_e32 v203, 16, v245
	v_and_b32_e32 v231, 0xffff0000, v245
	global_load_dwordx2 v[244:245], v182, s[38:39] offset:1536
	v_pk_add_f32 v[216:217], v[216:217], v[178:179]
	v_add_f32_e32 v218, v218, v203
	v_add_f32_e32 v219, v219, v231
	s_waitcnt vmcnt(11)
	v_lshlrev_b32_e32 v178, 16, v246
	v_and_b32_e32 v179, 0xffff0000, v246
	v_lshlrev_b32_e32 v203, 16, v247
	v_and_b32_e32 v231, 0xffff0000, v247
	v_pk_add_f32 v[212:213], v[212:213], v[178:179]
	v_add_f32_e32 v214, v214, v203
	v_add_f32_e32 v215, v215, v231
	s_waitcnt vmcnt(10)
	v_lshlrev_b32_e32 v178, 16, v248
	v_and_b32_e32 v179, 0xffff0000, v248
	v_lshlrev_b32_e32 v203, 16, v249
	v_and_b32_e32 v231, 0xffff0000, v249
	v_pk_add_f32 v[208:209], v[208:209], v[178:179]
	v_add_f32_e32 v210, v210, v203
	v_add_f32_e32 v211, v211, v231
	s_waitcnt vmcnt(9)
	v_lshlrev_b32_e32 v178, 16, v250
	v_and_b32_e32 v179, 0xffff0000, v250
	v_lshlrev_b32_e32 v203, 16, v251
	v_and_b32_e32 v231, 0xffff0000, v251
	v_pk_add_f32 v[204:205], v[204:205], v[178:179]
	v_add_f32_e32 v206, v206, v203
	v_add_f32_e32 v207, v207, v231
	s_waitcnt vmcnt(8)
	v_lshlrev_b32_e32 v178, 16, v176
	v_and_b32_e32 v179, 0xffff0000, v176
	v_lshlrev_b32_e32 v203, 16, v177
	v_and_b32_e32 v231, 0xffff0000, v177
	v_pk_add_f32 v[216:217], v[216:217], v[178:179]
	v_add_f32_e32 v218, v218, v203
	v_add_f32_e32 v219, v219, v231
	s_waitcnt vmcnt(7)
	v_lshlrev_b32_e32 v178, 16, v220
	v_and_b32_e32 v179, 0xffff0000, v220
	v_lshlrev_b32_e32 v203, 16, v221
	v_and_b32_e32 v231, 0xffff0000, v221
	v_pk_add_f32 v[212:213], v[212:213], v[178:179]
	v_add_f32_e32 v214, v214, v203
	v_add_f32_e32 v215, v215, v231
	s_waitcnt vmcnt(6)
	v_lshlrev_b32_e32 v178, 16, v232
	v_and_b32_e32 v179, 0xffff0000, v232
	v_lshlrev_b32_e32 v203, 16, v233
	v_and_b32_e32 v231, 0xffff0000, v233
	v_pk_add_f32 v[208:209], v[208:209], v[178:179]
	v_add_f32_e32 v210, v210, v203
	v_add_f32_e32 v211, v211, v231
	s_waitcnt vmcnt(5)
	v_lshlrev_b32_e32 v178, 16, v234
	v_and_b32_e32 v179, 0xffff0000, v234
	v_lshlrev_b32_e32 v203, 16, v235
	v_and_b32_e32 v231, 0xffff0000, v235
	v_pk_add_f32 v[204:205], v[204:205], v[178:179]
	v_add_f32_e32 v206, v206, v203
	v_add_f32_e32 v207, v207, v231
	s_waitcnt vmcnt(4)
	v_lshlrev_b32_e32 v178, 16, v236
	v_and_b32_e32 v179, 0xffff0000, v236
	v_lshlrev_b32_e32 v203, 16, v237
	v_and_b32_e32 v231, 0xffff0000, v237
	v_pk_add_f32 v[216:217], v[216:217], v[178:179]
	v_add_f32_e32 v218, v218, v203
	v_add_f32_e32 v219, v219, v231
	s_waitcnt vmcnt(3)
	v_lshlrev_b32_e32 v178, 16, v238
	v_and_b32_e32 v179, 0xffff0000, v238
	v_lshlrev_b32_e32 v203, 16, v239
	v_and_b32_e32 v231, 0xffff0000, v239
	v_pk_add_f32 v[212:213], v[212:213], v[178:179]
	v_add_f32_e32 v214, v214, v203
	v_add_f32_e32 v215, v215, v231
	s_waitcnt vmcnt(2)
	v_lshlrev_b32_e32 v178, 16, v240
	v_and_b32_e32 v179, 0xffff0000, v240
	v_lshlrev_b32_e32 v203, 16, v241
	v_and_b32_e32 v231, 0xffff0000, v241
	v_pk_add_f32 v[208:209], v[208:209], v[178:179]
	v_add_f32_e32 v210, v210, v203
	v_add_f32_e32 v211, v211, v231
	s_waitcnt vmcnt(1)
	v_lshlrev_b32_e32 v178, 16, v242
	v_and_b32_e32 v179, 0xffff0000, v242
	v_lshlrev_b32_e32 v203, 16, v243
	v_and_b32_e32 v231, 0xffff0000, v243
	v_pk_add_f32 v[204:205], v[204:205], v[178:179]
	v_add_f32_e32 v206, v206, v203
	v_add_f32_e32 v207, v207, v231
	s_waitcnt vmcnt(0)
	v_lshlrev_b32_e32 v178, 16, v244
	v_and_b32_e32 v179, 0xffff0000, v244
	v_lshlrev_b32_e32 v203, 16, v245
	v_and_b32_e32 v231, 0xffff0000, v245
	v_pk_add_f32 v[216:217], v[216:217], v[178:179]
	v_add_f32_e32 v218, v218, v203
	v_add_f32_e32 v219, v219, v231
	v_mad_u64_u32 v[220:221], s[38:39], s21, v227, v[196:197]
	s_mov_b32 s25, s13
	s_lshl_b64 s[26:27], s[24:25], 11
	s_add_u32 s26, s64, s26
	s_addc_u32 s27, s65, s27
	global_load_dwordx4 v[232:235], v[220:221], off
	global_load_dwordx4 v[236:239], v[220:221], off offset:1024
	global_load_dwordx4 v[240:243], v[220:221], off offset:2048
	global_load_dwordx4 v[244:247], v[220:221], off offset:3072
	s_waitcnt vmcnt(3)
	v_pk_mul_f32 v[232:233], v[232:233], s[18:19] op_sel_hi:[1,0]
	v_pk_mul_f32 v[234:235], v[234:235], s[18:19] op_sel_hi:[1,0]
	v_pk_fma_f32 v[172:173], v[232:233], v[212:213], v[172:173]
	v_pk_fma_f32 v[174:175], v[234:235], v[214:215], v[174:175]
	s_waitcnt vmcnt(2)
	v_pk_mul_f32 v[236:237], v[236:237], s[18:19] op_sel_hi:[1,0]
	v_pk_mul_f32 v[238:239], v[238:239], s[18:19] op_sel_hi:[1,0]
	v_pk_fma_f32 v[168:169], v[236:237], v[208:209], v[168:169]
	v_pk_fma_f32 v[170:171], v[238:239], v[210:211], v[170:171]
	s_waitcnt vmcnt(1)
	v_pk_mul_f32 v[240:241], v[240:241], s[18:19] op_sel_hi:[1,0]
	v_pk_mul_f32 v[242:243], v[242:243], s[18:19] op_sel_hi:[1,0]
	v_pk_fma_f32 v[164:165], v[240:241], v[204:205], v[164:165]
	v_pk_fma_f32 v[166:167], v[242:243], v[206:207], v[166:167]
	s_waitcnt vmcnt(0)
	v_pk_mul_f32 v[244:245], v[244:245], s[18:19] op_sel_hi:[1,0]
	v_pk_mul_f32 v[246:247], v[246:247], s[18:19] op_sel_hi:[1,0]
	v_pk_fma_f32 v[160:161], v[244:245], v[216:217], v[160:161]
	v_pk_fma_f32 v[162:163], v[246:247], v[218:219], v[162:163]
	v_cvt_pk_bf16_f32 v248, v172, v173
	v_cvt_pk_bf16_f32 v249, v174, v175
	global_store_dwordx2 v181, v[248:249], s[26:27]
	s_nop 0
	v_cvt_pk_bf16_f32 v248, v168, v169
	v_cvt_pk_bf16_f32 v249, v170, v171
	global_store_dwordx2 v183, v[248:249], s[26:27]
	s_nop 0
	v_cvt_pk_bf16_f32 v248, v164, v165
	v_cvt_pk_bf16_f32 v249, v166, v167
	global_store_dwordx2 v185, v[248:249], s[26:27]
	s_nop 0
	v_cvt_pk_bf16_f32 v248, v160, v161
	v_cvt_pk_bf16_f32 v249, v162, v163
	global_store_dwordx2 v187, v[248:249], s[26:27]
